# residual epilogues: one dword load per lane touches the next batch's 64 cache lines while the current batch is in flight; counted waits allow the extra outstanding load
# baseline (speedup 1.0000x reference)
.Lres_pre_skip_c0:
	s_lshl_b32 s40, s54, 8
	s_add_i32 s44, s40, 0xffff8000
	s_ashr_i32 s41, s40, 31
	s_lshl_b64 s[50:51], s[44:45], 12
	s_add_u32 s52, s14, s50
	s_addc_u32 s53, s15, s51
	s_lshl_b64 s[50:51], s[40:41], 12
	s_add_u32 s55, s10, s50
	s_addc_u32 s64, s11, s51
	s_cmpk_lt_i32 s54, 0x80
	s_cselect_b32 s51, s41, 0
	s_cselect_b32 s50, s40, s44
	s_cselect_b32 s44, s21, s47
	s_cselect_b32 s65, s20, s46
	s_cselect_b32 s54, s40, s40
	s_cselect_b32 s41, s64, s53
	s_cselect_b32 s40, s55, s52
	s_lshl_b64 s[52:53], s[50:51], 12
	s_add_u32 s52, s65, s52
	v_add_u32_e32 v176, v230, v128
	s_addc_u32 s53, s44, s53
	v_lshlrev_b64 v[178:179], 2, v[176:177]
	v_lshl_add_u64 v[210:211], s[52:53], 0, v[178:179]
	s_mov_b32 s44, 0x10000
	s_mov_b64 s[52:53], 0x10000
	v_add_co_u32_e32 v130, vcc, s44, v210
	v_lshl_add_u64 v[128:129], v[210:211], 0, s[52:53]
	s_nop 0
	v_addc_co_u32_e32 v131, vcc, 0, v211, vcc
	s_mov_b64 s[52:53], 0x10200
	global_load_dwordx4 v[220:223], v[210:211], off offset:16 nt
	global_load_dwordx4 v[232:235], v[210:211], off nt
	global_load_dwordx4 v[148:151], v[210:211], off offset:528 nt
	global_load_dwordx4 v[152:155], v[210:211], off offset:512 nt
	global_load_dwordx4 v[140:143], v[130:131], off nt
	global_load_dwordx4 v[136:139], v[128:129], off offset:16 nt
	v_lshl_add_u64 v[128:129], v[210:211], 0, s[52:53]
	global_load_dwordx4 v[132:135], v[130:131], off offset:512 nt
	s_nop 0
	global_load_dwordx4 v[128:131], v[128:129], off offset:16 nt
	v_mbcnt_lo_u32_b32 v226, -1, 0
	v_mbcnt_hi_u32_b32 v226, -1, v226
	v_lshrrev_b32_e32 v226, 4, v226
	v_lshrrev_b32_e32 v227, 1, v226
	v_and_b32_e32 v236, 1, v226
	v_lshlrev_b32_e32 v227, 16, v227
	v_lshl_add_u32 v227, v236, 9, v227
	v_lshlrev_b32_e32 v226, 5, v226
	v_sub_u32_e32 v226, v227, v226
	v_add_u32_e32 v226, 0x20000, v226
	v_mov_b32_e32 v227, 0
	v_lshl_add_u64 v[226:227], v[210:211], 0, v[226:227]
	global_load_dword v236, v[226:227], off
	s_waitcnt vmcnt(1) lgkmcnt(0)
	s_andn2_b64 vcc, exec, s[28:29]
	s_cbranch_vccnz .Lres_zero_c0
	v_pk_add_f32 v[186:187], v[186:187], 1.0 op_sel_hi:[1,0]
	v_pk_add_f32 v[188:189], v[188:189], 1.0 op_sel_hi:[1,0]
	v_pk_add_f32 v[190:191], v[190:191], 1.0 op_sel_hi:[1,0]
	v_pk_add_f32 v[192:193], v[192:193], 1.0 op_sel_hi:[1,0]
	v_pk_add_f32 v[194:195], v[194:195], 1.0 op_sel_hi:[1,0]
	v_pk_add_f32 v[196:197], v[196:197], 1.0 op_sel_hi:[1,0]
	v_pk_add_f32 v[198:199], v[198:199], 1.0 op_sel_hi:[1,0]
	v_pk_add_f32 v[200:201], v[200:201], 1.0 op_sel_hi:[1,0]
	v_pk_mul_f32 v[238:239], v[238:239], v[186:187]
	v_pk_mul_f32 v[240:241], v[240:241], v[188:189]
	v_pk_mul_f32 v[242:243], v[242:243], v[190:191]
	v_pk_mul_f32 v[244:245], v[244:245], v[192:193]
	v_pk_mul_f32 v[246:247], v[246:247], v[194:195]
	v_pk_mul_f32 v[248:249], v[248:249], v[196:197]
	v_pk_mul_f32 v[250:251], v[250:251], v[198:199]
	v_pk_mul_f32 v[252:253], v[252:253], v[200:201]
	v_mov_b32_e32 v194, v238
	v_mov_b32_e32 v195, v239
	v_mov_b32_e32 v196, v240
	v_mov_b32_e32 v197, v241
	v_mov_b32_e32 v186, v242
	v_mov_b32_e32 v187, v243
	v_mov_b32_e32 v200, v244
	v_mov_b32_e32 v201, v245
	v_mov_b32_e32 v190, v246
	v_mov_b32_e32 v191, v247
	v_mov_b32_e32 v192, v248
	v_mov_b32_e32 v193, v249
	v_mov_b32_e32 v188, v250
	v_mov_b32_e32 v189, v251
	v_mov_b32_e32 v198, v252
	v_mov_b32_e32 v199, v253
	s_branch .Lres_done_c0

.Lres_done_c0:
	s_mov_b32 s55, s51
	s_lshl_b64 s[50:51], s[54:55], 11
	s_add_u32 s52, s60, s50
	s_addc_u32 s53, s61, s51
	s_lshl_b64 s[50:51], s[54:55], 6
	s_waitcnt vmcnt(1) lgkmcnt(0)
	v_pk_mul_f32 v[164:165], v[164:165], 0.5 op_sel_hi:[1,0]
	v_pk_mul_f32 v[160:161], v[160:161], 0.5 op_sel_hi:[1,0]
	v_pk_mul_f32 v[204:205], v[158:159], 0.5 op_sel_hi:[1,0]
	v_pk_mul_f32 v[202:203], v[156:157], 0.5 op_sel_hi:[1,0]
	v_pk_mul_f32 v[206:207], v[146:147], 0.5 op_sel_hi:[1,0]
	v_pk_mul_f32 v[208:209], v[144:145], 0.5 op_sel_hi:[1,0]
	s_add_u32 s50, s70, s50
	v_pk_mul_f32 v[166:167], v[166:167], 0.5 op_sel_hi:[1,0]
	v_pk_mul_f32 v[162:163], v[162:163], 0.5 op_sel_hi:[1,0]
	v_lshl_add_u64 v[212:213], s[40:41], 0, v[178:179]
	s_addc_u32 s51, s71, s51
	s_and_b64 vcc, exec, s[8:9]
	v_pk_fma_f32 v[146:147], v[122:123], v[204:205], v[222:223]
	v_pk_fma_f32 v[158:159], v[126:127], v[206:207], v[234:235]
	v_pk_fma_f32 v[156:157], v[124:125], v[208:209], v[232:233]
	v_pk_fma_f32 v[144:145], v[120:121], v[202:203], v[220:221]
	v_pk_fma_f32 v[124:125], v[116:117], v[160:161], v[152:153]
	v_pk_fma_f32 v[120:121], v[112:113], v[164:165], v[148:149]
	global_store_dwordx4 v[212:213], v[156:159], off nt
	global_store_dwordx4 v[212:213], v[144:147], off offset:16 nt
	s_cbranch_vccnz .LBB0_823
	v_pk_mul_f32 v[116:117], v[194:195], v[156:157]
	v_pk_mul_f32 v[122:123], v[200:201], v[146:147]
	v_cvt_pk_bf16_f32 v220, v116, v117
	v_mul_f32_e32 v116, v157, v157
	v_mul_f32_e32 v117, v159, v159
	v_fmac_f32_e32 v116, v156, v156
	v_fmac_f32_e32 v117, v158, v158
	v_pk_mul_f32 v[112:113], v[196:197], v[158:159]
	v_pk_mul_f32 v[126:127], v[186:187], v[144:145]
	v_cvt_pk_bf16_f32 v221, v112, v113
	v_add_f32_e32 v116, v116, v117
	v_cvt_pk_bf16_f32 v222, v126, v127
	v_cvt_pk_bf16_f32 v223, v122, v123
	v_mul_f32_e32 v117, v145, v145
	v_mul_f32_e32 v122, v147, v147
	v_fmac_f32_e32 v117, v144, v144
	v_fmac_f32_e32 v122, v146, v146
	v_lshl_add_u64 v[112:113], v[176:177], 1, s[52:53]
	v_add_f32_e32 v117, v117, v122
	v_pk_fma_f32 v[126:127], v[118:119], v[162:163], v[154:155]
	v_pk_fma_f32 v[122:123], v[114:115], v[166:167], v[150:151]
	v_pk_mul_f32 v[144:145], v[190:191], v[124:125]
	v_pk_mul_f32 v[146:147], v[188:189], v[120:121]
	global_store_dwordx4 v[112:113], v[220:223], off
	v_add_f32_e32 v152, v116, v117
	global_store_dwordx4 v[212:213], v[124:127], off offset:512 nt
	global_store_dwordx4 v[212:213], v[120:123], off offset:528 nt
	v_pk_mul_f32 v[116:117], v[192:193], v[126:127]
	v_pk_mul_f32 v[148:149], v[198:199], v[122:123]
	v_cvt_pk_bf16_f32 v144, v144, v145
	v_cvt_pk_bf16_f32 v145, v116, v117
	v_cvt_pk_bf16_f32 v146, v146, v147
	v_mul_f32_e32 v116, v123, v123
	v_cvt_pk_bf16_f32 v147, v148, v149
	global_store_dwordx4 v[112:113], v[144:147], off offset:256
	v_mul_f32_e32 v112, v125, v125
	v_mul_f32_e32 v113, v127, v127
	v_fmac_f32_e32 v112, v124, v124
	v_fmac_f32_e32 v113, v126, v126
	v_add_f32_e32 v112, v112, v113
	v_mul_f32_e32 v113, v121, v121
	v_fmac_f32_e32 v113, v120, v120
	v_fmac_f32_e32 v116, v122, v122
	v_add_f32_e32 v113, v113, v116
	v_add_f32_e32 v112, v112, v113
	v_add_f32_e32 v112, v152, v112
	v_mov_b32_e32 v113, v112
	s_nop 1
	v_permlane16_swap_b32_e32 v112, v113
	v_add_f32_e32 v112, v112, v113
	v_mov_b32_e32 v113, v112
	s_nop 1
	v_permlane32_swap_b32_e32 v112, v113
	s_and_saveexec_b64 s[54:55], s[4:5]
	s_cbranch_execz .LBB0_783
	v_add_f32_e32 v116, v112, v113
	v_lshrrev_b32_e32 v112, 4, v176
	s_lshl_b32 s64, s17, 2
	v_and_b32_e32 v112, 0xfffffc0, v112
	v_mov_b32_e32 v113, v177
	s_ashr_i32 s65, s64, 31
	v_lshl_add_u64 v[112:113], s[50:51], 0, v[112:113]
	v_lshl_add_u64 v[112:113], s[64:65], 2, v[112:113]
	s_lshl_b32 s44, s72, 2
	v_lshl_add_u64 v[112:113], v[112:113], 0, s[44:45]
	global_store_dword v[112:113], v116, off

.LBB0_790:
	s_mov_b64 s[54:55], 0x20000
	v_add_co_u32_e32 v98, vcc, 0x20000, v210
	v_lshl_add_u64 v[96:97], v[210:211], 0, s[54:55]
	s_nop 0
	v_addc_co_u32_e32 v99, vcc, 0, v211, vcc
	s_mov_b64 s[54:55], 0x20200
	global_load_dwordx4 v[120:123], v[98:99], off nt
	global_load_dwordx4 v[130:133], v[96:97], off offset:16 nt
	v_lshl_add_u64 v[96:97], v[210:211], 0, s[54:55]
	global_load_dwordx4 v[116:119], v[98:99], off offset:512 nt
	global_load_dwordx4 v[112:115], v[96:97], off offset:16 nt
	s_mov_b64 s[54:55], 0x30000
	v_add_co_u32_e32 v98, vcc, 0x30000, v210
	v_lshl_add_u64 v[96:97], v[210:211], 0, s[54:55]
	s_nop 0
	v_addc_co_u32_e32 v99, vcc, 0, v211, vcc
	s_mov_b64 s[54:55], 0x30200
	global_load_dwordx4 v[108:111], v[98:99], off nt
	global_load_dwordx4 v[104:107], v[96:97], off offset:16 nt
	v_lshl_add_u64 v[96:97], v[210:211], 0, s[54:55]
	global_load_dwordx4 v[100:103], v[98:99], off offset:512 nt
	s_nop 0
	global_load_dwordx4 v[96:99], v[96:97], off offset:16 nt
	s_mov_b64 s[98:99], 0x60000
	v_lshl_add_u64 v[226:227], v[226:227], 0, s[98:99]
	global_load_dword v236, v[226:227], off
	v_add_u32_e32 v128, 0x8000, v176
	v_mov_b32_e32 v129, v177
	s_and_b64 vcc, exec, s[8:9]
	s_waitcnt vmcnt(8)
	v_pk_fma_f32 v[126:127], v[94:95], v[206:207], v[122:123]
	v_pk_fma_f32 v[124:125], v[92:93], v[208:209], v[120:121]
	s_waitcnt vmcnt(7)
	v_pk_fma_f32 v[120:121], v[88:89], v[202:203], v[130:131]
	v_lshl_add_u64 v[88:89], v[128:129], 2, s[40:41]
	v_pk_fma_f32 v[122:123], v[90:91], v[204:205], v[132:133]
	global_store_dwordx4 v[88:89], v[124:127], off nt
	global_store_dwordx4 v[88:89], v[120:123], off offset:16 nt
	v_add_u32_e32 v130, 0x8080, v176
	s_waitcnt vmcnt(8)
	v_pk_fma_f32 v[88:89], v[84:85], v[160:161], v[116:117]
	s_waitcnt vmcnt(7)
	v_pk_fma_f32 v[92:93], v[80:81], v[164:165], v[112:113]
	s_cbranch_vccnz .LBB0_825
	v_pk_mul_f32 v[80:81], v[196:197], v[126:127]
	v_pk_mul_f32 v[84:85], v[194:195], v[124:125]
	v_pk_mul_f32 v[90:91], v[200:201], v[122:123]
	v_cvt_pk_bf16_f32 v132, v84, v85
	v_cvt_pk_bf16_f32 v133, v80, v81
	v_lshl_add_u64 v[80:81], v[128:129], 1, s[52:53]
	v_pk_mul_f32 v[94:95], v[186:187], v[120:121]
	v_mul_f32_e32 v84, v123, v123
	v_cvt_pk_bf16_f32 v134, v94, v95
	v_cvt_pk_bf16_f32 v135, v90, v91
	global_store_dwordx4 v[80:81], v[132:135], off
	v_mul_f32_e32 v80, v125, v125
	v_mul_f32_e32 v81, v127, v127
	v_fmac_f32_e32 v80, v124, v124
	v_fmac_f32_e32 v81, v126, v126
	v_add_f32_e32 v80, v80, v81
	v_mul_f32_e32 v81, v121, v121
	v_fmac_f32_e32 v81, v120, v120
	v_fmac_f32_e32 v84, v122, v122
	v_add_f32_e32 v81, v81, v84
	v_mov_b32_e32 v131, v177
	v_add_f32_e32 v124, v80, v81
	v_pk_fma_f32 v[90:91], v[86:87], v[162:163], v[118:119]
	v_lshl_add_u64 v[80:81], v[130:131], 2, s[40:41]
	v_pk_fma_f32 v[94:95], v[82:83], v[166:167], v[114:115]
	global_store_dwordx4 v[80:81], v[88:91], off nt
	global_store_dwordx4 v[80:81], v[92:95], off offset:16 nt
	v_pk_mul_f32 v[80:81], v[192:193], v[90:91]
	v_pk_mul_f32 v[84:85], v[190:191], v[88:89]
	v_pk_mul_f32 v[112:113], v[198:199], v[94:95]
	v_cvt_pk_bf16_f32 v120, v84, v85
	v_cvt_pk_bf16_f32 v121, v80, v81
	v_lshl_add_u64 v[80:81], v[130:131], 1, s[52:53]
	v_pk_mul_f32 v[116:117], v[188:189], v[92:93]
	v_mul_f32_e32 v84, v95, v95
	v_cvt_pk_bf16_f32 v122, v116, v117
	v_cvt_pk_bf16_f32 v123, v112, v113
	global_store_dwordx4 v[80:81], v[120:123], off
	v_mul_f32_e32 v80, v89, v89
	v_mul_f32_e32 v81, v91, v91
	v_fmac_f32_e32 v80, v88, v88
	v_fmac_f32_e32 v81, v90, v90
	v_add_f32_e32 v80, v80, v81
	v_mul_f32_e32 v81, v93, v93
	v_fmac_f32_e32 v81, v92, v92
	v_fmac_f32_e32 v84, v94, v94
	v_add_f32_e32 v81, v81, v84
	v_add_f32_e32 v80, v80, v81
	v_add_f32_e32 v80, v124, v80
	v_mov_b32_e32 v81, v80
	s_nop 1
	v_permlane16_swap_b32_e32 v80, v81
	v_add_f32_e32 v80, v80, v81
	v_mov_b32_e32 v81, v80
	s_nop 1
	v_permlane32_swap_b32_e32 v80, v81
	s_and_saveexec_b64 s[54:55], s[4:5]
	s_cbranch_execz .LBB0_793
	v_add_f32_e32 v84, v80, v81
	v_lshrrev_b32_e32 v80, 4, v128
	s_lshl_b32 s64, s17, 2
	v_and_b32_e32 v80, 0xfffffc0, v80
	v_mov_b32_e32 v81, v177
	s_ashr_i32 s65, s64, 31
	v_lshl_add_u64 v[80:81], s[50:51], 0, v[80:81]
	v_lshl_add_u64 v[80:81], s[64:65], 2, v[80:81]
	s_lshl_b32 s44, s72, 2
	v_lshl_add_u64 v[80:81], v[80:81], 0, s[44:45]
	global_store_dword v[80:81], v84, off

.LBB0_795:
	s_nop 0
	v_add_u32_e32 v88, 0xc000, v176
	v_mov_b32_e32 v89, v177
	s_waitcnt vmcnt(6)
	v_pk_fma_f32 v[80:81], v[78:79], v[206:207], v[110:111]
	v_pk_fma_f32 v[78:79], v[76:77], v[208:209], v[108:109]
	s_waitcnt vmcnt(5)
	v_pk_fma_f32 v[82:83], v[72:73], v[202:203], v[104:105]
	v_lshl_add_u64 v[72:73], v[88:89], 2, s[40:41]
	v_pk_fma_f32 v[84:85], v[74:75], v[204:205], v[106:107]
	global_store_dwordx4 v[72:73], v[78:81], off nt
	global_store_dwordx4 v[72:73], v[82:85], off offset:16 nt
	s_and_b64 vcc, exec, s[8:9]
	v_add_u32_e32 v86, 0xc080, v176
	s_waitcnt vmcnt(6)
	v_pk_fma_f32 v[76:77], v[68:69], v[160:161], v[100:101]
	s_waitcnt vmcnt(5)
	v_pk_fma_f32 v[72:73], v[64:65], v[164:165], v[96:97]
	s_cbranch_vccnz .LBB0_826
	v_pk_mul_f32 v[64:65], v[196:197], v[80:81]
	v_pk_mul_f32 v[68:69], v[194:195], v[78:79]
	v_pk_mul_f32 v[92:93], v[186:187], v[82:83]
	v_cvt_pk_bf16_f32 v90, v68, v69
	v_cvt_pk_bf16_f32 v91, v64, v65
	v_lshl_add_u64 v[64:65], v[88:89], 1, s[52:53]
	v_pk_mul_f32 v[74:75], v[200:201], v[84:85]
	v_cvt_pk_bf16_f32 v92, v92, v93
	v_mul_f32_e32 v68, v85, v85
	v_cvt_pk_bf16_f32 v93, v74, v75
	global_store_dwordx4 v[64:65], v[90:93], off
	v_mul_f32_e32 v64, v79, v79
	v_mul_f32_e32 v65, v81, v81
	v_fmac_f32_e32 v64, v78, v78
	v_fmac_f32_e32 v65, v80, v80
	v_add_f32_e32 v64, v64, v65
	v_mul_f32_e32 v65, v83, v83
	v_fmac_f32_e32 v65, v82, v82
	v_fmac_f32_e32 v68, v84, v84
	v_add_f32_e32 v65, v65, v68
	v_mov_b32_e32 v87, v177
	v_add_f32_e32 v89, v64, v65
	v_pk_fma_f32 v[78:79], v[70:71], v[162:163], v[102:103]
	v_lshl_add_u64 v[64:65], v[86:87], 2, s[40:41]
	v_pk_fma_f32 v[74:75], v[66:67], v[166:167], v[98:99]
	global_store_dwordx4 v[64:65], v[76:79], off nt
	global_store_dwordx4 v[64:65], v[72:75], off offset:16 nt
	v_pk_mul_f32 v[64:65], v[192:193], v[78:79]
	v_pk_mul_f32 v[68:69], v[190:191], v[76:77]
	v_pk_mul_f32 v[82:83], v[188:189], v[72:73]
	v_cvt_pk_bf16_f32 v80, v68, v69
	v_cvt_pk_bf16_f32 v81, v64, v65
	v_lshl_add_u64 v[64:65], v[86:87], 1, s[52:53]
	v_pk_mul_f32 v[84:85], v[198:199], v[74:75]
	v_cvt_pk_bf16_f32 v82, v82, v83
	v_mul_f32_e32 v68, v75, v75
	v_cvt_pk_bf16_f32 v83, v84, v85
	global_store_dwordx4 v[64:65], v[80:83], off
	v_mul_f32_e32 v64, v77, v77
	v_mul_f32_e32 v65, v79, v79
	v_fmac_f32_e32 v64, v76, v76
	v_fmac_f32_e32 v65, v78, v78
	v_add_f32_e32 v64, v64, v65
	v_mul_f32_e32 v65, v73, v73
	v_fmac_f32_e32 v65, v72, v72
	v_fmac_f32_e32 v68, v74, v74
	v_add_f32_e32 v65, v65, v68
	v_add_f32_e32 v64, v64, v65
	v_add_f32_e32 v64, v89, v64
	v_mov_b32_e32 v65, v64
	s_nop 1
	v_permlane16_swap_b32_e32 v64, v65
	v_add_f32_e32 v64, v64, v65
	v_mov_b32_e32 v65, v64
	s_nop 1
	v_permlane32_swap_b32_e32 v64, v65
	s_and_saveexec_b64 s[54:55], s[4:5]
	s_cbranch_execz .LBB0_798
	v_add_f32_e32 v68, v64, v65
	v_lshrrev_b32_e32 v64, 4, v88
	s_lshl_b32 s64, s17, 2
	v_and_b32_e32 v64, 0xfffffc0, v64
	v_mov_b32_e32 v65, v177
	s_ashr_i32 s65, s64, 31
	v_lshl_add_u64 v[64:65], s[50:51], 0, v[64:65]
	v_lshl_add_u64 v[64:65], s[64:65], 2, v[64:65]
	s_lshl_b32 s44, s72, 2
	v_lshl_add_u64 v[64:65], v[64:65], 0, s[44:45]
	global_store_dword v[64:65], v68, off

.LBB0_800:
	s_mov_b64 s[54:55], 0x80000
	v_add_co_u32_e32 v66, vcc, 0x80000, v210
	v_lshl_add_u64 v[64:65], v[210:211], 0, s[54:55]
	s_nop 0
	v_addc_co_u32_e32 v67, vcc, 0, v211, vcc
	s_mov_b64 s[54:55], 0x80200
	global_load_dwordx4 v[88:91], v[66:67], off nt
	global_load_dwordx4 v[98:101], v[64:65], off offset:16 nt
	v_lshl_add_u64 v[64:65], v[210:211], 0, s[54:55]
	global_load_dwordx4 v[84:87], v[66:67], off offset:512 nt
	global_load_dwordx4 v[80:83], v[64:65], off offset:16 nt
	s_mov_b64 s[54:55], 0x90000
	v_add_co_u32_e32 v66, vcc, 0x90000, v210
	v_lshl_add_u64 v[64:65], v[210:211], 0, s[54:55]
	s_nop 0
	v_addc_co_u32_e32 v67, vcc, 0, v211, vcc
	s_mov_b64 s[54:55], 0x90200
	global_load_dwordx4 v[76:79], v[66:67], off nt
	global_load_dwordx4 v[72:75], v[64:65], off offset:16 nt
	v_lshl_add_u64 v[64:65], v[210:211], 0, s[54:55]
	global_load_dwordx4 v[68:71], v[66:67], off offset:512 nt
	s_nop 0
	global_load_dwordx4 v[64:67], v[64:65], off offset:16 nt
	s_mov_b64 s[98:99], 0x20000
	v_lshl_add_u64 v[226:227], v[226:227], 0, s[98:99]
	global_load_dword v236, v[226:227], off
	v_add_u32_e32 v96, 0x20000, v176
	v_mov_b32_e32 v97, v177
	s_and_b64 vcc, exec, s[8:9]
	s_waitcnt vmcnt(8)
	v_pk_fma_f32 v[94:95], v[62:63], v[206:207], v[90:91]
	v_pk_fma_f32 v[92:93], v[60:61], v[208:209], v[88:89]
	s_waitcnt vmcnt(7)
	v_pk_fma_f32 v[88:89], v[56:57], v[202:203], v[98:99]
	v_lshl_add_u64 v[56:57], v[96:97], 2, s[40:41]
	v_pk_fma_f32 v[90:91], v[58:59], v[204:205], v[100:101]
	global_store_dwordx4 v[56:57], v[92:95], off nt
	global_store_dwordx4 v[56:57], v[88:91], off offset:16 nt
	v_add_u32_e32 v98, 0x20080, v176
	s_waitcnt vmcnt(8)
	v_pk_fma_f32 v[56:57], v[52:53], v[160:161], v[84:85]
	s_waitcnt vmcnt(7)
	v_pk_fma_f32 v[60:61], v[48:49], v[164:165], v[80:81]
	s_cbranch_vccnz .LBB0_827
	v_pk_mul_f32 v[48:49], v[196:197], v[94:95]
	v_pk_mul_f32 v[52:53], v[194:195], v[92:93]
	v_pk_mul_f32 v[58:59], v[200:201], v[90:91]
	v_cvt_pk_bf16_f32 v100, v52, v53
	v_cvt_pk_bf16_f32 v101, v48, v49
	v_lshl_add_u64 v[48:49], v[96:97], 1, s[52:53]
	v_pk_mul_f32 v[62:63], v[186:187], v[88:89]
	v_mul_f32_e32 v52, v91, v91
	v_cvt_pk_bf16_f32 v102, v62, v63
	v_cvt_pk_bf16_f32 v103, v58, v59
	global_store_dwordx4 v[48:49], v[100:103], off
	v_mul_f32_e32 v48, v93, v93
	v_mul_f32_e32 v49, v95, v95
	v_fmac_f32_e32 v48, v92, v92
	v_fmac_f32_e32 v49, v94, v94
	v_add_f32_e32 v48, v48, v49
	v_mul_f32_e32 v49, v89, v89
	v_fmac_f32_e32 v49, v88, v88
	v_fmac_f32_e32 v52, v90, v90
	v_add_f32_e32 v49, v49, v52
	v_mov_b32_e32 v99, v177
	v_add_f32_e32 v92, v48, v49
	v_pk_fma_f32 v[58:59], v[54:55], v[162:163], v[86:87]
	v_lshl_add_u64 v[48:49], v[98:99], 2, s[40:41]
	v_pk_fma_f32 v[62:63], v[50:51], v[166:167], v[82:83]
	global_store_dwordx4 v[48:49], v[56:59], off nt
	global_store_dwordx4 v[48:49], v[60:63], off offset:16 nt
	v_pk_mul_f32 v[48:49], v[192:193], v[58:59]
	v_pk_mul_f32 v[52:53], v[190:191], v[56:57]
	v_pk_mul_f32 v[80:81], v[198:199], v[62:63]
	v_cvt_pk_bf16_f32 v88, v52, v53
	v_cvt_pk_bf16_f32 v89, v48, v49
	v_lshl_add_u64 v[48:49], v[98:99], 1, s[52:53]
	v_pk_mul_f32 v[84:85], v[188:189], v[60:61]
	v_mul_f32_e32 v52, v63, v63
	v_cvt_pk_bf16_f32 v90, v84, v85
	v_cvt_pk_bf16_f32 v91, v80, v81
	global_store_dwordx4 v[48:49], v[88:91], off
	v_mul_f32_e32 v48, v57, v57
	v_mul_f32_e32 v49, v59, v59
	v_fmac_f32_e32 v48, v56, v56
	v_fmac_f32_e32 v49, v58, v58
	v_add_f32_e32 v48, v48, v49
	v_mul_f32_e32 v49, v61, v61
	v_fmac_f32_e32 v49, v60, v60
	v_fmac_f32_e32 v52, v62, v62
	v_add_f32_e32 v49, v49, v52
	v_add_f32_e32 v48, v48, v49
	v_add_f32_e32 v48, v92, v48
	v_mov_b32_e32 v49, v48
	s_nop 1
	v_permlane16_swap_b32_e32 v48, v49
	v_add_f32_e32 v48, v48, v49
	v_mov_b32_e32 v49, v48
	s_nop 1
	v_permlane32_swap_b32_e32 v48, v49
	s_and_saveexec_b64 s[54:55], s[4:5]
	s_cbranch_execz .LBB0_803
	v_add_f32_e32 v52, v48, v49
	v_lshrrev_b32_e32 v48, 4, v96
	s_lshl_b32 s64, s17, 2
	v_and_b32_e32 v48, 0xfffffc0, v48
	v_mov_b32_e32 v49, v177
	s_ashr_i32 s65, s64, 31
	v_lshl_add_u64 v[48:49], s[50:51], 0, v[48:49]
	v_lshl_add_u64 v[48:49], s[64:65], 2, v[48:49]
	s_lshl_b32 s44, s72, 2
	v_lshl_add_u64 v[48:49], v[48:49], 0, s[44:45]
	global_store_dword v[48:49], v52, off

.LBB0_805:
	s_nop 0
	v_add_u32_e32 v56, 0x24000, v176
	v_mov_b32_e32 v57, v177
	s_waitcnt vmcnt(6)
	v_pk_fma_f32 v[48:49], v[46:47], v[206:207], v[78:79]
	v_pk_fma_f32 v[46:47], v[44:45], v[208:209], v[76:77]
	s_waitcnt vmcnt(5)
	v_pk_fma_f32 v[50:51], v[40:41], v[202:203], v[72:73]
	v_lshl_add_u64 v[40:41], v[56:57], 2, s[40:41]
	v_pk_fma_f32 v[52:53], v[42:43], v[204:205], v[74:75]
	global_store_dwordx4 v[40:41], v[46:49], off nt
	global_store_dwordx4 v[40:41], v[50:53], off offset:16 nt
	s_and_b64 vcc, exec, s[8:9]
	v_add_u32_e32 v54, 0x24080, v176
	s_waitcnt vmcnt(6)
	v_pk_fma_f32 v[44:45], v[36:37], v[160:161], v[68:69]
	s_waitcnt vmcnt(5)
	v_pk_fma_f32 v[40:41], v[32:33], v[164:165], v[64:65]
	s_cbranch_vccnz .LBB0_828
	v_pk_mul_f32 v[32:33], v[196:197], v[48:49]
	v_pk_mul_f32 v[36:37], v[194:195], v[46:47]
	v_pk_mul_f32 v[60:61], v[186:187], v[50:51]
	v_cvt_pk_bf16_f32 v58, v36, v37
	v_cvt_pk_bf16_f32 v59, v32, v33
	v_lshl_add_u64 v[32:33], v[56:57], 1, s[52:53]
	v_pk_mul_f32 v[42:43], v[200:201], v[52:53]
	v_cvt_pk_bf16_f32 v60, v60, v61
	v_mul_f32_e32 v36, v53, v53
	v_cvt_pk_bf16_f32 v61, v42, v43
	global_store_dwordx4 v[32:33], v[58:61], off
	v_mul_f32_e32 v32, v47, v47
	v_mul_f32_e32 v33, v49, v49
	v_fmac_f32_e32 v32, v46, v46
	v_fmac_f32_e32 v33, v48, v48
	v_add_f32_e32 v32, v32, v33
	v_mul_f32_e32 v33, v51, v51
	v_fmac_f32_e32 v33, v50, v50
	v_fmac_f32_e32 v36, v52, v52
	v_add_f32_e32 v33, v33, v36
	v_mov_b32_e32 v55, v177
	v_add_f32_e32 v57, v32, v33
	v_pk_fma_f32 v[46:47], v[38:39], v[162:163], v[70:71]
	v_lshl_add_u64 v[32:33], v[54:55], 2, s[40:41]
	v_pk_fma_f32 v[42:43], v[34:35], v[166:167], v[66:67]
	global_store_dwordx4 v[32:33], v[44:47], off nt
	global_store_dwordx4 v[32:33], v[40:43], off offset:16 nt
	v_pk_mul_f32 v[32:33], v[192:193], v[46:47]
	v_pk_mul_f32 v[36:37], v[190:191], v[44:45]
	v_pk_mul_f32 v[50:51], v[188:189], v[40:41]
	v_cvt_pk_bf16_f32 v48, v36, v37
	v_cvt_pk_bf16_f32 v49, v32, v33
	v_lshl_add_u64 v[32:33], v[54:55], 1, s[52:53]
	v_pk_mul_f32 v[52:53], v[198:199], v[42:43]
	v_cvt_pk_bf16_f32 v50, v50, v51
	v_mul_f32_e32 v36, v43, v43
	v_cvt_pk_bf16_f32 v51, v52, v53
	global_store_dwordx4 v[32:33], v[48:51], off
	v_mul_f32_e32 v32, v45, v45
	v_mul_f32_e32 v33, v47, v47
	v_fmac_f32_e32 v32, v44, v44
	v_fmac_f32_e32 v33, v46, v46
	v_add_f32_e32 v32, v32, v33
	v_mul_f32_e32 v33, v41, v41
	v_fmac_f32_e32 v33, v40, v40
	v_fmac_f32_e32 v36, v42, v42
	v_add_f32_e32 v33, v33, v36
	v_add_f32_e32 v32, v32, v33
	v_add_f32_e32 v32, v57, v32
	v_mov_b32_e32 v33, v32
	s_nop 1
	v_permlane16_swap_b32_e32 v32, v33
	v_add_f32_e32 v32, v32, v33
	v_mov_b32_e32 v33, v32
	s_nop 1
	v_permlane32_swap_b32_e32 v32, v33
	s_and_saveexec_b64 s[54:55], s[4:5]
	s_cbranch_execz .LBB0_808
	v_add_f32_e32 v36, v32, v33
	v_lshrrev_b32_e32 v32, 4, v56
	s_lshl_b32 s64, s17, 2
	v_and_b32_e32 v32, 0xfffffc0, v32
	v_mov_b32_e32 v33, v177
	s_ashr_i32 s65, s64, 31
	v_lshl_add_u64 v[32:33], s[50:51], 0, v[32:33]
	v_lshl_add_u64 v[32:33], s[64:65], 2, v[32:33]
	s_lshl_b32 s44, s72, 2
	v_lshl_add_u64 v[32:33], v[32:33], 0, s[44:45]
	global_store_dword v[32:33], v36, off

.Lres_pre_skip_c1:
	s_lshl_b32 s40, s54, 8
	s_add_i32 s44, s40, 0xffff8000
	s_ashr_i32 s41, s40, 31
	s_lshl_b64 s[50:51], s[44:45], 12
	s_add_u32 s27, s14, s50
	s_addc_u32 s52, s15, s51
	s_lshl_b64 s[50:51], s[40:41], 12
	s_add_u32 s53, s10, s50
	s_addc_u32 s55, s11, s51
	s_cmpk_lt_i32 s54, 0x80
	s_cselect_b32 s51, s41, 0
	s_cselect_b32 s50, s40, s44
	s_cselect_b32 s44, s21, s47
	s_cselect_b32 s63, s20, s46
	s_cselect_b32 s54, s40, s40
	s_cselect_b32 s41, s55, s52
	s_cselect_b32 s40, s53, s27
	s_lshl_b64 s[52:53], s[50:51], 12
	s_add_u32 s52, s63, s52
	v_add_u32_e32 v176, v128, v230
	s_addc_u32 s53, s44, s53
	v_lshlrev_b64 v[178:179], 2, v[176:177]
	v_lshl_add_u64 v[210:211], s[52:53], 0, v[178:179]
	s_mov_b32 s27, 0x10000
	s_mov_b64 s[52:53], 0x10000
	v_add_co_u32_e32 v130, vcc, s27, v210
	v_lshl_add_u64 v[128:129], v[210:211], 0, s[52:53]
	s_nop 0
	v_addc_co_u32_e32 v131, vcc, 0, v211, vcc
	s_mov_b64 s[52:53], 0x10200
	global_load_dwordx4 v[220:223], v[210:211], off offset:16 nt
	global_load_dwordx4 v[234:237], v[210:211], off nt
	global_load_dwordx4 v[148:151], v[210:211], off offset:528 nt
	global_load_dwordx4 v[152:155], v[210:211], off offset:512 nt
	global_load_dwordx4 v[140:143], v[130:131], off nt
	global_load_dwordx4 v[136:139], v[128:129], off offset:16 nt
	v_lshl_add_u64 v[128:129], v[210:211], 0, s[52:53]
	global_load_dwordx4 v[132:135], v[130:131], off offset:512 nt
	s_nop 0
	global_load_dwordx4 v[128:131], v[128:129], off offset:16 nt
	v_mbcnt_lo_u32_b32 v226, -1, 0
	v_mbcnt_hi_u32_b32 v226, -1, v226
	v_lshrrev_b32_e32 v226, 4, v226
	v_lshrrev_b32_e32 v227, 1, v226
	v_and_b32_e32 v233, 1, v226
	v_lshlrev_b32_e32 v227, 16, v227
	v_lshl_add_u32 v227, v233, 9, v227
	v_lshlrev_b32_e32 v226, 5, v226
	v_sub_u32_e32 v226, v227, v226
	v_add_u32_e32 v226, 0x20000, v226
	v_mov_b32_e32 v227, 0
	v_lshl_add_u64 v[226:227], v[210:211], 0, v[226:227]
	global_load_dword v233, v[226:227], off
	s_waitcnt vmcnt(1) lgkmcnt(0)
	s_andn2_b64 vcc, exec, s[24:25]
	s_cbranch_vccnz .Lres_zero_c1
	v_pk_add_f32 v[186:187], v[186:187], 1.0 op_sel_hi:[1,0]
	v_pk_add_f32 v[188:189], v[188:189], 1.0 op_sel_hi:[1,0]
	v_pk_add_f32 v[190:191], v[190:191], 1.0 op_sel_hi:[1,0]
	v_pk_add_f32 v[192:193], v[192:193], 1.0 op_sel_hi:[1,0]
	v_pk_add_f32 v[194:195], v[194:195], 1.0 op_sel_hi:[1,0]
	v_pk_add_f32 v[196:197], v[196:197], 1.0 op_sel_hi:[1,0]
	v_pk_add_f32 v[198:199], v[198:199], 1.0 op_sel_hi:[1,0]
	v_pk_add_f32 v[200:201], v[200:201], 1.0 op_sel_hi:[1,0]
	v_pk_mul_f32 v[238:239], v[238:239], v[186:187]
	v_pk_mul_f32 v[240:241], v[240:241], v[188:189]
	v_pk_mul_f32 v[242:243], v[242:243], v[190:191]
	v_pk_mul_f32 v[244:245], v[244:245], v[192:193]
	v_pk_mul_f32 v[246:247], v[246:247], v[194:195]
	v_pk_mul_f32 v[248:249], v[248:249], v[196:197]
	v_pk_mul_f32 v[250:251], v[250:251], v[198:199]
	v_pk_mul_f32 v[252:253], v[252:253], v[200:201]
	v_mov_b32_e32 v194, v238
	v_mov_b32_e32 v195, v239
	v_mov_b32_e32 v196, v240
	v_mov_b32_e32 v197, v241
	v_mov_b32_e32 v186, v242
	v_mov_b32_e32 v187, v243
	v_mov_b32_e32 v200, v244
	v_mov_b32_e32 v201, v245
	v_mov_b32_e32 v190, v246
	v_mov_b32_e32 v191, v247
	v_mov_b32_e32 v192, v248
	v_mov_b32_e32 v193, v249
	v_mov_b32_e32 v188, v250
	v_mov_b32_e32 v189, v251
	v_mov_b32_e32 v198, v252
	v_mov_b32_e32 v199, v253
	s_branch .Lres_done_c1

.Lres_done_c1:
	s_mov_b32 s55, s51
	s_lshl_b64 s[50:51], s[54:55], 11
	s_add_u32 s52, s60, s50
	s_addc_u32 s53, s61, s51
	s_lshl_b64 s[50:51], s[54:55], 6
	s_waitcnt vmcnt(1) lgkmcnt(0)
	v_pk_mul_f32 v[164:165], v[164:165], 0.5 op_sel_hi:[1,0]
	v_pk_mul_f32 v[160:161], v[160:161], 0.5 op_sel_hi:[1,0]
	v_pk_mul_f32 v[204:205], v[158:159], 0.5 op_sel_hi:[1,0]
	v_pk_mul_f32 v[202:203], v[156:157], 0.5 op_sel_hi:[1,0]
	v_pk_mul_f32 v[208:209], v[146:147], 0.5 op_sel_hi:[1,0]
	v_pk_mul_f32 v[206:207], v[144:145], 0.5 op_sel_hi:[1,0]
	s_add_u32 s50, s70, s50
	v_pk_mul_f32 v[166:167], v[166:167], 0.5 op_sel_hi:[1,0]
	v_pk_mul_f32 v[162:163], v[162:163], 0.5 op_sel_hi:[1,0]
	v_lshl_add_u64 v[212:213], s[40:41], 0, v[178:179]
	s_addc_u32 s51, s71, s51
	s_and_b64 vcc, exec, s[8:9]
	v_pk_fma_f32 v[146:147], v[122:123], v[204:205], v[222:223]
	v_pk_fma_f32 v[158:159], v[126:127], v[208:209], v[236:237]
	v_pk_fma_f32 v[156:157], v[124:125], v[206:207], v[234:235]
	v_pk_fma_f32 v[144:145], v[120:121], v[202:203], v[220:221]
	v_pk_fma_f32 v[124:125], v[116:117], v[160:161], v[152:153]
	v_pk_fma_f32 v[120:121], v[112:113], v[164:165], v[148:149]
	global_store_dwordx4 v[212:213], v[156:159], off nt
	global_store_dwordx4 v[212:213], v[144:147], off offset:16 nt
	s_cbranch_vccnz .LBB0_923
	v_pk_mul_f32 v[116:117], v[194:195], v[156:157]
	v_pk_mul_f32 v[122:123], v[200:201], v[146:147]
	v_cvt_pk_bf16_f32 v220, v116, v117
	v_mul_f32_e32 v116, v157, v157
	v_mul_f32_e32 v117, v159, v159
	v_fmac_f32_e32 v116, v156, v156
	v_fmac_f32_e32 v117, v158, v158
	v_pk_mul_f32 v[112:113], v[196:197], v[158:159]
	v_pk_mul_f32 v[126:127], v[186:187], v[144:145]
	v_cvt_pk_bf16_f32 v221, v112, v113
	v_add_f32_e32 v116, v116, v117
	v_cvt_pk_bf16_f32 v222, v126, v127
	v_cvt_pk_bf16_f32 v223, v122, v123
	v_mul_f32_e32 v117, v145, v145
	v_mul_f32_e32 v122, v147, v147
	v_fmac_f32_e32 v117, v144, v144
	v_fmac_f32_e32 v122, v146, v146
	v_lshl_add_u64 v[112:113], v[176:177], 1, s[52:53]
	v_add_f32_e32 v117, v117, v122
	v_pk_fma_f32 v[126:127], v[118:119], v[162:163], v[154:155]
	v_pk_fma_f32 v[122:123], v[114:115], v[166:167], v[150:151]
	v_pk_mul_f32 v[144:145], v[190:191], v[124:125]
	v_pk_mul_f32 v[146:147], v[188:189], v[120:121]
	global_store_dwordx4 v[112:113], v[220:223], off
	v_add_f32_e32 v152, v116, v117
	global_store_dwordx4 v[212:213], v[124:127], off offset:512 nt
	global_store_dwordx4 v[212:213], v[120:123], off offset:528 nt
	v_pk_mul_f32 v[116:117], v[192:193], v[126:127]
	v_pk_mul_f32 v[148:149], v[198:199], v[122:123]
	v_cvt_pk_bf16_f32 v144, v144, v145
	v_cvt_pk_bf16_f32 v145, v116, v117
	v_cvt_pk_bf16_f32 v146, v146, v147
	v_mul_f32_e32 v116, v123, v123
	v_cvt_pk_bf16_f32 v147, v148, v149
	global_store_dwordx4 v[112:113], v[144:147], off offset:256
	v_mul_f32_e32 v112, v125, v125
	v_mul_f32_e32 v113, v127, v127
	v_fmac_f32_e32 v112, v124, v124
	v_fmac_f32_e32 v113, v126, v126
	v_add_f32_e32 v112, v112, v113
	v_mul_f32_e32 v113, v121, v121
	v_fmac_f32_e32 v113, v120, v120
	v_fmac_f32_e32 v116, v122, v122
	v_add_f32_e32 v113, v113, v116
	v_add_f32_e32 v112, v112, v113
	v_add_f32_e32 v112, v152, v112
	v_mov_b32_e32 v113, v112
	s_nop 1
	v_permlane16_swap_b32_e32 v112, v113
	v_add_f32_e32 v112, v112, v113
	v_mov_b32_e32 v113, v112
	s_nop 1
	v_permlane32_swap_b32_e32 v112, v113
	s_and_saveexec_b64 s[54:55], s[4:5]
	s_cbranch_execz .LBB0_883
	v_add_f32_e32 v116, v112, v113
	v_lshrrev_b32_e32 v112, 4, v176
	s_lshl_b32 s64, s73, 2
	v_and_b32_e32 v112, 0xfffffc0, v112
	v_mov_b32_e32 v113, v177
	s_ashr_i32 s65, s64, 31
	v_lshl_add_u64 v[112:113], s[50:51], 0, v[112:113]
	v_lshl_add_u64 v[112:113], s[64:65], 2, v[112:113]
	s_lshl_b32 s44, s82, 2
	v_lshl_add_u64 v[112:113], v[112:113], 0, s[44:45]
	global_store_dword v[112:113], v116, off

.LBB0_890:
	s_mov_b64 s[54:55], 0x20000
	v_add_co_u32_e32 v98, vcc, 0x20000, v210
	v_lshl_add_u64 v[96:97], v[210:211], 0, s[54:55]
	s_nop 0
	v_addc_co_u32_e32 v99, vcc, 0, v211, vcc
	s_mov_b64 s[54:55], 0x20200
	global_load_dwordx4 v[120:123], v[98:99], off nt
	global_load_dwordx4 v[130:133], v[96:97], off offset:16 nt
	v_lshl_add_u64 v[96:97], v[210:211], 0, s[54:55]
	global_load_dwordx4 v[116:119], v[98:99], off offset:512 nt
	global_load_dwordx4 v[112:115], v[96:97], off offset:16 nt
	s_mov_b64 s[54:55], 0x30000
	v_add_co_u32_e32 v98, vcc, 0x30000, v210
	v_lshl_add_u64 v[96:97], v[210:211], 0, s[54:55]
	s_nop 0
	v_addc_co_u32_e32 v99, vcc, 0, v211, vcc
	s_mov_b64 s[54:55], 0x30200
	global_load_dwordx4 v[108:111], v[98:99], off nt
	global_load_dwordx4 v[104:107], v[96:97], off offset:16 nt
	v_lshl_add_u64 v[96:97], v[210:211], 0, s[54:55]
	global_load_dwordx4 v[100:103], v[98:99], off offset:512 nt
	s_nop 0
	global_load_dwordx4 v[96:99], v[96:97], off offset:16 nt
	s_mov_b64 s[98:99], 0x60000
	v_lshl_add_u64 v[226:227], v[226:227], 0, s[98:99]
	global_load_dword v233, v[226:227], off
	v_add_u32_e32 v128, 0x8000, v176
	v_mov_b32_e32 v129, v177
	s_and_b64 vcc, exec, s[8:9]
	s_waitcnt vmcnt(8)
	v_pk_fma_f32 v[126:127], v[94:95], v[208:209], v[122:123]
	v_pk_fma_f32 v[124:125], v[92:93], v[206:207], v[120:121]
	s_waitcnt vmcnt(7)
	v_pk_fma_f32 v[120:121], v[88:89], v[202:203], v[130:131]
	v_lshl_add_u64 v[88:89], v[128:129], 2, s[40:41]
	v_pk_fma_f32 v[122:123], v[90:91], v[204:205], v[132:133]
	global_store_dwordx4 v[88:89], v[124:127], off nt
	global_store_dwordx4 v[88:89], v[120:123], off offset:16 nt
	v_add_u32_e32 v130, 0x8080, v176
	s_waitcnt vmcnt(8)
	v_pk_fma_f32 v[88:89], v[84:85], v[160:161], v[116:117]
	s_waitcnt vmcnt(7)
	v_pk_fma_f32 v[92:93], v[80:81], v[164:165], v[112:113]
	s_cbranch_vccnz .LBB0_925
	v_pk_mul_f32 v[80:81], v[196:197], v[126:127]
	v_pk_mul_f32 v[84:85], v[194:195], v[124:125]
	v_pk_mul_f32 v[90:91], v[200:201], v[122:123]
	v_cvt_pk_bf16_f32 v132, v84, v85
	v_cvt_pk_bf16_f32 v133, v80, v81
	v_lshl_add_u64 v[80:81], v[128:129], 1, s[52:53]
	v_pk_mul_f32 v[94:95], v[186:187], v[120:121]
	v_mul_f32_e32 v84, v123, v123
	v_cvt_pk_bf16_f32 v134, v94, v95
	v_cvt_pk_bf16_f32 v135, v90, v91
	global_store_dwordx4 v[80:81], v[132:135], off
	v_mul_f32_e32 v80, v125, v125
	v_mul_f32_e32 v81, v127, v127
	v_fmac_f32_e32 v80, v124, v124
	v_fmac_f32_e32 v81, v126, v126
	v_add_f32_e32 v80, v80, v81
	v_mul_f32_e32 v81, v121, v121
	v_fmac_f32_e32 v81, v120, v120
	v_fmac_f32_e32 v84, v122, v122
	v_add_f32_e32 v81, v81, v84
	v_mov_b32_e32 v131, v177
	v_add_f32_e32 v124, v80, v81
	v_pk_fma_f32 v[90:91], v[86:87], v[162:163], v[118:119]
	v_lshl_add_u64 v[80:81], v[130:131], 2, s[40:41]
	v_pk_fma_f32 v[94:95], v[82:83], v[166:167], v[114:115]
	global_store_dwordx4 v[80:81], v[88:91], off nt
	global_store_dwordx4 v[80:81], v[92:95], off offset:16 nt
	v_pk_mul_f32 v[80:81], v[192:193], v[90:91]
	v_pk_mul_f32 v[84:85], v[190:191], v[88:89]
	v_pk_mul_f32 v[112:113], v[198:199], v[94:95]
	v_cvt_pk_bf16_f32 v120, v84, v85
	v_cvt_pk_bf16_f32 v121, v80, v81
	v_lshl_add_u64 v[80:81], v[130:131], 1, s[52:53]
	v_pk_mul_f32 v[116:117], v[188:189], v[92:93]
	v_mul_f32_e32 v84, v95, v95
	v_cvt_pk_bf16_f32 v122, v116, v117
	v_cvt_pk_bf16_f32 v123, v112, v113
	global_store_dwordx4 v[80:81], v[120:123], off
	v_mul_f32_e32 v80, v89, v89
	v_mul_f32_e32 v81, v91, v91
	v_fmac_f32_e32 v80, v88, v88
	v_fmac_f32_e32 v81, v90, v90
	v_add_f32_e32 v80, v80, v81
	v_mul_f32_e32 v81, v93, v93
	v_fmac_f32_e32 v81, v92, v92
	v_fmac_f32_e32 v84, v94, v94
	v_add_f32_e32 v81, v81, v84
	v_add_f32_e32 v80, v80, v81
	v_add_f32_e32 v80, v124, v80
	v_mov_b32_e32 v81, v80
	s_nop 1
	v_permlane16_swap_b32_e32 v80, v81
	v_add_f32_e32 v80, v80, v81
	v_mov_b32_e32 v81, v80
	s_nop 1
	v_permlane32_swap_b32_e32 v80, v81
	s_and_saveexec_b64 s[54:55], s[4:5]
	s_cbranch_execz .LBB0_893
	v_add_f32_e32 v84, v80, v81
	v_lshrrev_b32_e32 v80, 4, v128
	s_lshl_b32 s64, s73, 2
	v_and_b32_e32 v80, 0xfffffc0, v80
	v_mov_b32_e32 v81, v177
	s_ashr_i32 s65, s64, 31
	v_lshl_add_u64 v[80:81], s[50:51], 0, v[80:81]
	v_lshl_add_u64 v[80:81], s[64:65], 2, v[80:81]
	s_lshl_b32 s44, s82, 2
	v_lshl_add_u64 v[80:81], v[80:81], 0, s[44:45]
	global_store_dword v[80:81], v84, off

.LBB0_895:
	s_nop 0
	v_add_u32_e32 v88, 0xc000, v176
	v_mov_b32_e32 v89, v177
	s_waitcnt vmcnt(6)
	v_pk_fma_f32 v[80:81], v[78:79], v[208:209], v[110:111]
	v_pk_fma_f32 v[78:79], v[76:77], v[206:207], v[108:109]
	s_waitcnt vmcnt(5)
	v_pk_fma_f32 v[82:83], v[72:73], v[202:203], v[104:105]
	v_lshl_add_u64 v[72:73], v[88:89], 2, s[40:41]
	v_pk_fma_f32 v[84:85], v[74:75], v[204:205], v[106:107]
	global_store_dwordx4 v[72:73], v[78:81], off nt
	global_store_dwordx4 v[72:73], v[82:85], off offset:16 nt
	s_and_b64 vcc, exec, s[8:9]
	v_add_u32_e32 v86, 0xc080, v176
	s_waitcnt vmcnt(6)
	v_pk_fma_f32 v[76:77], v[68:69], v[160:161], v[100:101]
	s_waitcnt vmcnt(5)
	v_pk_fma_f32 v[72:73], v[64:65], v[164:165], v[96:97]
	s_cbranch_vccnz .LBB0_926
	v_pk_mul_f32 v[64:65], v[196:197], v[80:81]
	v_pk_mul_f32 v[68:69], v[194:195], v[78:79]
	v_pk_mul_f32 v[92:93], v[186:187], v[82:83]
	v_cvt_pk_bf16_f32 v90, v68, v69
	v_cvt_pk_bf16_f32 v91, v64, v65
	v_lshl_add_u64 v[64:65], v[88:89], 1, s[52:53]
	v_pk_mul_f32 v[74:75], v[200:201], v[84:85]
	v_cvt_pk_bf16_f32 v92, v92, v93
	v_mul_f32_e32 v68, v85, v85
	v_cvt_pk_bf16_f32 v93, v74, v75
	global_store_dwordx4 v[64:65], v[90:93], off
	v_mul_f32_e32 v64, v79, v79
	v_mul_f32_e32 v65, v81, v81
	v_fmac_f32_e32 v64, v78, v78
	v_fmac_f32_e32 v65, v80, v80
	v_add_f32_e32 v64, v64, v65
	v_mul_f32_e32 v65, v83, v83
	v_fmac_f32_e32 v65, v82, v82
	v_fmac_f32_e32 v68, v84, v84
	v_add_f32_e32 v65, v65, v68
	v_mov_b32_e32 v87, v177
	v_add_f32_e32 v89, v64, v65
	v_pk_fma_f32 v[78:79], v[70:71], v[162:163], v[102:103]
	v_lshl_add_u64 v[64:65], v[86:87], 2, s[40:41]
	v_pk_fma_f32 v[74:75], v[66:67], v[166:167], v[98:99]
	global_store_dwordx4 v[64:65], v[76:79], off nt
	global_store_dwordx4 v[64:65], v[72:75], off offset:16 nt
	v_pk_mul_f32 v[64:65], v[192:193], v[78:79]
	v_pk_mul_f32 v[68:69], v[190:191], v[76:77]
	v_pk_mul_f32 v[82:83], v[188:189], v[72:73]
	v_cvt_pk_bf16_f32 v80, v68, v69
	v_cvt_pk_bf16_f32 v81, v64, v65
	v_lshl_add_u64 v[64:65], v[86:87], 1, s[52:53]
	v_pk_mul_f32 v[84:85], v[198:199], v[74:75]
	v_cvt_pk_bf16_f32 v82, v82, v83
	v_mul_f32_e32 v68, v75, v75
	v_cvt_pk_bf16_f32 v83, v84, v85
	global_store_dwordx4 v[64:65], v[80:83], off
	v_mul_f32_e32 v64, v77, v77
	v_mul_f32_e32 v65, v79, v79
	v_fmac_f32_e32 v64, v76, v76
	v_fmac_f32_e32 v65, v78, v78
	v_add_f32_e32 v64, v64, v65
	v_mul_f32_e32 v65, v73, v73
	v_fmac_f32_e32 v65, v72, v72
	v_fmac_f32_e32 v68, v74, v74
	v_add_f32_e32 v65, v65, v68
	v_add_f32_e32 v64, v64, v65
	v_add_f32_e32 v64, v89, v64
	v_mov_b32_e32 v65, v64
	s_nop 1
	v_permlane16_swap_b32_e32 v64, v65
	v_add_f32_e32 v64, v64, v65
	v_mov_b32_e32 v65, v64
	s_nop 1
	v_permlane32_swap_b32_e32 v64, v65
	s_and_saveexec_b64 s[54:55], s[4:5]
	s_cbranch_execz .LBB0_898
	v_add_f32_e32 v68, v64, v65
	v_lshrrev_b32_e32 v64, 4, v88
	s_lshl_b32 s64, s73, 2
	v_and_b32_e32 v64, 0xfffffc0, v64
	v_mov_b32_e32 v65, v177
	s_ashr_i32 s65, s64, 31
	v_lshl_add_u64 v[64:65], s[50:51], 0, v[64:65]
	v_lshl_add_u64 v[64:65], s[64:65], 2, v[64:65]
	s_lshl_b32 s44, s82, 2
	v_lshl_add_u64 v[64:65], v[64:65], 0, s[44:45]
	global_store_dword v[64:65], v68, off

.LBB0_900:
	s_mov_b64 s[54:55], 0x80000
	v_add_co_u32_e32 v66, vcc, 0x80000, v210
	v_lshl_add_u64 v[64:65], v[210:211], 0, s[54:55]
	s_nop 0
	v_addc_co_u32_e32 v67, vcc, 0, v211, vcc
	s_mov_b64 s[54:55], 0x80200
	global_load_dwordx4 v[88:91], v[66:67], off nt
	global_load_dwordx4 v[98:101], v[64:65], off offset:16 nt
	v_lshl_add_u64 v[64:65], v[210:211], 0, s[54:55]
	global_load_dwordx4 v[84:87], v[66:67], off offset:512 nt
	global_load_dwordx4 v[80:83], v[64:65], off offset:16 nt
	s_mov_b64 s[54:55], 0x90000
	v_add_co_u32_e32 v66, vcc, 0x90000, v210
	v_lshl_add_u64 v[64:65], v[210:211], 0, s[54:55]
	s_nop 0
	v_addc_co_u32_e32 v67, vcc, 0, v211, vcc
	s_mov_b64 s[54:55], 0x90200
	global_load_dwordx4 v[76:79], v[66:67], off nt
	global_load_dwordx4 v[72:75], v[64:65], off offset:16 nt
	v_lshl_add_u64 v[64:65], v[210:211], 0, s[54:55]
	global_load_dwordx4 v[68:71], v[66:67], off offset:512 nt
	s_nop 0
	global_load_dwordx4 v[64:67], v[64:65], off offset:16 nt
	s_mov_b64 s[98:99], 0x20000
	v_lshl_add_u64 v[226:227], v[226:227], 0, s[98:99]
	global_load_dword v233, v[226:227], off
	v_add_u32_e32 v96, 0x20000, v176
	v_mov_b32_e32 v97, v177
	s_and_b64 vcc, exec, s[8:9]
	s_waitcnt vmcnt(8)
	v_pk_fma_f32 v[94:95], v[62:63], v[208:209], v[90:91]
	v_pk_fma_f32 v[92:93], v[60:61], v[206:207], v[88:89]
	s_waitcnt vmcnt(7)
	v_pk_fma_f32 v[88:89], v[56:57], v[202:203], v[98:99]
	v_lshl_add_u64 v[56:57], v[96:97], 2, s[40:41]
	v_pk_fma_f32 v[90:91], v[58:59], v[204:205], v[100:101]
	global_store_dwordx4 v[56:57], v[92:95], off nt
	global_store_dwordx4 v[56:57], v[88:91], off offset:16 nt
	v_add_u32_e32 v98, 0x20080, v176
	s_waitcnt vmcnt(8)
	v_pk_fma_f32 v[56:57], v[52:53], v[160:161], v[84:85]
	s_waitcnt vmcnt(7)
	v_pk_fma_f32 v[60:61], v[48:49], v[164:165], v[80:81]
	s_cbranch_vccnz .LBB0_927
	v_pk_mul_f32 v[48:49], v[196:197], v[94:95]
	v_pk_mul_f32 v[52:53], v[194:195], v[92:93]
	v_pk_mul_f32 v[58:59], v[200:201], v[90:91]
	v_cvt_pk_bf16_f32 v100, v52, v53
	v_cvt_pk_bf16_f32 v101, v48, v49
	v_lshl_add_u64 v[48:49], v[96:97], 1, s[52:53]
	v_pk_mul_f32 v[62:63], v[186:187], v[88:89]
	v_mul_f32_e32 v52, v91, v91
	v_cvt_pk_bf16_f32 v102, v62, v63
	v_cvt_pk_bf16_f32 v103, v58, v59
	global_store_dwordx4 v[48:49], v[100:103], off
	v_mul_f32_e32 v48, v93, v93
	v_mul_f32_e32 v49, v95, v95
	v_fmac_f32_e32 v48, v92, v92
	v_fmac_f32_e32 v49, v94, v94
	v_add_f32_e32 v48, v48, v49
	v_mul_f32_e32 v49, v89, v89
	v_fmac_f32_e32 v49, v88, v88
	v_fmac_f32_e32 v52, v90, v90
	v_add_f32_e32 v49, v49, v52
	v_mov_b32_e32 v99, v177
	v_add_f32_e32 v92, v48, v49
	v_pk_fma_f32 v[58:59], v[54:55], v[162:163], v[86:87]
	v_lshl_add_u64 v[48:49], v[98:99], 2, s[40:41]
	v_pk_fma_f32 v[62:63], v[50:51], v[166:167], v[82:83]
	global_store_dwordx4 v[48:49], v[56:59], off nt
	global_store_dwordx4 v[48:49], v[60:63], off offset:16 nt
	v_pk_mul_f32 v[48:49], v[192:193], v[58:59]
	v_pk_mul_f32 v[52:53], v[190:191], v[56:57]
	v_pk_mul_f32 v[80:81], v[198:199], v[62:63]
	v_cvt_pk_bf16_f32 v88, v52, v53
	v_cvt_pk_bf16_f32 v89, v48, v49
	v_lshl_add_u64 v[48:49], v[98:99], 1, s[52:53]
	v_pk_mul_f32 v[84:85], v[188:189], v[60:61]
	v_mul_f32_e32 v52, v63, v63
	v_cvt_pk_bf16_f32 v90, v84, v85
	v_cvt_pk_bf16_f32 v91, v80, v81
	global_store_dwordx4 v[48:49], v[88:91], off
	v_mul_f32_e32 v48, v57, v57
	v_mul_f32_e32 v49, v59, v59
	v_fmac_f32_e32 v48, v56, v56
	v_fmac_f32_e32 v49, v58, v58
	v_add_f32_e32 v48, v48, v49
	v_mul_f32_e32 v49, v61, v61
	v_fmac_f32_e32 v49, v60, v60
	v_fmac_f32_e32 v52, v62, v62
	v_add_f32_e32 v49, v49, v52
	v_add_f32_e32 v48, v48, v49
	v_add_f32_e32 v48, v92, v48
	v_mov_b32_e32 v49, v48
	s_nop 1
	v_permlane16_swap_b32_e32 v48, v49
	v_add_f32_e32 v48, v48, v49
	v_mov_b32_e32 v49, v48
	s_nop 1
	v_permlane32_swap_b32_e32 v48, v49
	s_and_saveexec_b64 s[54:55], s[4:5]
	s_cbranch_execz .LBB0_903
	v_add_f32_e32 v52, v48, v49
	v_lshrrev_b32_e32 v48, 4, v96
	s_lshl_b32 s64, s73, 2
	v_and_b32_e32 v48, 0xfffffc0, v48
	v_mov_b32_e32 v49, v177
	s_ashr_i32 s65, s64, 31
	v_lshl_add_u64 v[48:49], s[50:51], 0, v[48:49]
	v_lshl_add_u64 v[48:49], s[64:65], 2, v[48:49]
	s_lshl_b32 s44, s82, 2
	v_lshl_add_u64 v[48:49], v[48:49], 0, s[44:45]
	global_store_dword v[48:49], v52, off

.LBB0_905:
	s_nop 0
	v_add_u32_e32 v56, 0x24000, v176
	v_mov_b32_e32 v57, v177
	s_waitcnt vmcnt(6)
	v_pk_fma_f32 v[48:49], v[46:47], v[208:209], v[78:79]
	v_pk_fma_f32 v[46:47], v[44:45], v[206:207], v[76:77]
	s_waitcnt vmcnt(5)
	v_pk_fma_f32 v[50:51], v[40:41], v[202:203], v[72:73]
	v_lshl_add_u64 v[40:41], v[56:57], 2, s[40:41]
	v_pk_fma_f32 v[52:53], v[42:43], v[204:205], v[74:75]
	global_store_dwordx4 v[40:41], v[46:49], off nt
	global_store_dwordx4 v[40:41], v[50:53], off offset:16 nt
	s_and_b64 vcc, exec, s[8:9]
	v_add_u32_e32 v54, 0x24080, v176
	s_waitcnt vmcnt(6)
	v_pk_fma_f32 v[44:45], v[36:37], v[160:161], v[68:69]
	s_waitcnt vmcnt(5)
	v_pk_fma_f32 v[40:41], v[32:33], v[164:165], v[64:65]
	s_cbranch_vccnz .LBB0_928
	v_pk_mul_f32 v[32:33], v[196:197], v[48:49]
	v_pk_mul_f32 v[36:37], v[194:195], v[46:47]
	v_pk_mul_f32 v[60:61], v[186:187], v[50:51]
	v_cvt_pk_bf16_f32 v58, v36, v37
	v_cvt_pk_bf16_f32 v59, v32, v33
	v_lshl_add_u64 v[32:33], v[56:57], 1, s[52:53]
	v_pk_mul_f32 v[42:43], v[200:201], v[52:53]
	v_cvt_pk_bf16_f32 v60, v60, v61
	v_mul_f32_e32 v36, v53, v53
	v_cvt_pk_bf16_f32 v61, v42, v43
	global_store_dwordx4 v[32:33], v[58:61], off
	v_mul_f32_e32 v32, v47, v47
	v_mul_f32_e32 v33, v49, v49
	v_fmac_f32_e32 v32, v46, v46
	v_fmac_f32_e32 v33, v48, v48
	v_add_f32_e32 v32, v32, v33
	v_mul_f32_e32 v33, v51, v51
	v_fmac_f32_e32 v33, v50, v50
	v_fmac_f32_e32 v36, v52, v52
	v_add_f32_e32 v33, v33, v36
	v_mov_b32_e32 v55, v177
	v_add_f32_e32 v57, v32, v33
	v_pk_fma_f32 v[46:47], v[38:39], v[162:163], v[70:71]
	v_lshl_add_u64 v[32:33], v[54:55], 2, s[40:41]
	v_pk_fma_f32 v[42:43], v[34:35], v[166:167], v[66:67]
	global_store_dwordx4 v[32:33], v[44:47], off nt
	global_store_dwordx4 v[32:33], v[40:43], off offset:16 nt
	v_pk_mul_f32 v[32:33], v[192:193], v[46:47]
	v_pk_mul_f32 v[36:37], v[190:191], v[44:45]
	v_pk_mul_f32 v[50:51], v[188:189], v[40:41]
	v_cvt_pk_bf16_f32 v48, v36, v37
	v_cvt_pk_bf16_f32 v49, v32, v33
	v_lshl_add_u64 v[32:33], v[54:55], 1, s[52:53]
	v_pk_mul_f32 v[52:53], v[198:199], v[42:43]
	v_cvt_pk_bf16_f32 v50, v50, v51
	v_mul_f32_e32 v36, v43, v43
	v_cvt_pk_bf16_f32 v51, v52, v53
	global_store_dwordx4 v[32:33], v[48:51], off
	v_mul_f32_e32 v32, v45, v45
	v_mul_f32_e32 v33, v47, v47
	v_fmac_f32_e32 v32, v44, v44
	v_fmac_f32_e32 v33, v46, v46
	v_add_f32_e32 v32, v32, v33
	v_mul_f32_e32 v33, v41, v41
	v_fmac_f32_e32 v33, v40, v40
	v_fmac_f32_e32 v36, v42, v42
	v_add_f32_e32 v33, v33, v36
	v_add_f32_e32 v32, v32, v33
	v_add_f32_e32 v32, v57, v32
	v_mov_b32_e32 v33, v32
	s_nop 1
	v_permlane16_swap_b32_e32 v32, v33
	v_add_f32_e32 v32, v32, v33
	v_mov_b32_e32 v33, v32
	s_nop 1
	v_permlane32_swap_b32_e32 v32, v33
	s_and_saveexec_b64 s[54:55], s[4:5]
	s_cbranch_execz .LBB0_908
	v_add_f32_e32 v36, v32, v33
	v_lshrrev_b32_e32 v32, 4, v56
	s_lshl_b32 s64, s73, 2
	v_and_b32_e32 v32, 0xfffffc0, v32
	v_mov_b32_e32 v33, v177
	s_ashr_i32 s65, s64, 31
	v_lshl_add_u64 v[32:33], s[50:51], 0, v[32:33]
	v_lshl_add_u64 v[32:33], s[64:65], 2, v[32:33]
	s_lshl_b32 s44, s82, 2
	v_lshl_add_u64 v[32:33], v[32:33], 0, s[44:45]
	global_store_dword v[32:33], v36, off

.Lres_pre_skip_c2:
	s_lshl_b32 s38, s52, 8
	s_add_i32 s44, s38, 0xffff8000
	s_ashr_i32 s39, s38, 31
	s_lshl_b64 s[40:41], s[44:45], 12
	s_add_u32 s50, s14, s40
	s_addc_u32 s51, s15, s41
	s_lshl_b64 s[40:41], s[38:39], 12
	s_add_u32 s53, s10, s40
	s_addc_u32 s64, s11, s41
	s_cmpk_lt_i32 s52, 0x80
	s_cselect_b32 s41, s39, 0
	s_cselect_b32 s40, s38, s44
	s_cselect_b32 s44, s19, s47
	s_cselect_b32 s65, s18, s46
	s_cselect_b32 s52, s38, s38
	s_cselect_b32 s39, s64, s51
	s_cselect_b32 s38, s53, s50
	s_lshl_b64 s[50:51], s[40:41], 12
	s_add_u32 s50, s65, s50
	v_add_u32_e32 v176, v230, v144
	s_addc_u32 s51, s44, s51
	v_lshlrev_b64 v[178:179], 2, v[176:177]
	v_lshl_add_u64 v[210:211], s[50:51], 0, v[178:179]
	s_mov_b32 s40, 0x10000
	s_mov_b64 s[50:51], 0x10000
	v_add_co_u32_e32 v146, vcc, s40, v210
	v_lshl_add_u64 v[144:145], v[210:211], 0, s[50:51]
	s_nop 0
	v_addc_co_u32_e32 v147, vcc, 0, v211, vcc
	s_mov_b64 s[50:51], 0x10200
	global_load_dwordx4 v[168:171], v[210:211], off offset:16 nt
	global_load_dwordx4 v[172:175], v[210:211], off nt
	global_load_dwordx4 v[160:163], v[210:211], off offset:528 nt
	global_load_dwordx4 v[164:167], v[210:211], off offset:512 nt
	global_load_dwordx4 v[156:159], v[146:147], off nt
	global_load_dwordx4 v[152:155], v[144:145], off offset:16 nt
	v_lshl_add_u64 v[144:145], v[210:211], 0, s[50:51]
	global_load_dwordx4 v[148:151], v[146:147], off offset:512 nt
	s_nop 0
	global_load_dwordx4 v[144:147], v[144:145], off offset:16 nt
	v_mbcnt_lo_u32_b32 v226, -1, 0
	v_mbcnt_hi_u32_b32 v226, -1, v226
	v_lshrrev_b32_e32 v226, 4, v226
	v_lshrrev_b32_e32 v227, 1, v226
	v_and_b32_e32 v233, 1, v226
	v_lshlrev_b32_e32 v227, 16, v227
	v_lshl_add_u32 v227, v233, 9, v227
	v_lshlrev_b32_e32 v226, 5, v226
	v_sub_u32_e32 v226, v227, v226
	v_add_u32_e32 v226, 0x20000, v226
	v_mov_b32_e32 v227, 0
	v_lshl_add_u64 v[226:227], v[210:211], 0, v[226:227]
	global_load_dword v233, v[226:227], off
	s_waitcnt vmcnt(1) lgkmcnt(0)
	s_andn2_b64 vcc, exec, s[26:27]
	s_cbranch_vccnz .Lres_zero_c2
	v_pk_add_f32 v[194:195], v[194:195], 1.0 op_sel_hi:[1,0]
	v_pk_add_f32 v[196:197], v[196:197], 1.0 op_sel_hi:[1,0]
	v_pk_add_f32 v[198:199], v[198:199], 1.0 op_sel_hi:[1,0]
	v_pk_add_f32 v[200:201], v[200:201], 1.0 op_sel_hi:[1,0]
	v_pk_add_f32 v[202:203], v[202:203], 1.0 op_sel_hi:[1,0]
	v_pk_add_f32 v[204:205], v[204:205], 1.0 op_sel_hi:[1,0]
	v_pk_add_f32 v[206:207], v[206:207], 1.0 op_sel_hi:[1,0]
	v_pk_add_f32 v[208:209], v[208:209], 1.0 op_sel_hi:[1,0]
	v_pk_mul_f32 v[238:239], v[238:239], v[194:195]
	v_pk_mul_f32 v[240:241], v[240:241], v[196:197]
	v_pk_mul_f32 v[242:243], v[242:243], v[198:199]
	v_pk_mul_f32 v[244:245], v[244:245], v[200:201]
	v_pk_mul_f32 v[246:247], v[246:247], v[202:203]
	v_pk_mul_f32 v[248:249], v[248:249], v[204:205]
	v_pk_mul_f32 v[250:251], v[250:251], v[206:207]
	v_pk_mul_f32 v[252:253], v[252:253], v[208:209]
	v_mov_b32_e32 v202, v238
	v_mov_b32_e32 v203, v239
	v_mov_b32_e32 v204, v240
	v_mov_b32_e32 v205, v241
	v_mov_b32_e32 v194, v242
	v_mov_b32_e32 v195, v243
	v_mov_b32_e32 v208, v244
	v_mov_b32_e32 v209, v245
	v_mov_b32_e32 v198, v246
	v_mov_b32_e32 v199, v247
	v_mov_b32_e32 v200, v248
	v_mov_b32_e32 v201, v249
	v_mov_b32_e32 v196, v250
	v_mov_b32_e32 v197, v251
	v_mov_b32_e32 v206, v252
	v_mov_b32_e32 v207, v253
	s_branch .Lres_done_c2

.Lres_done_c2:
	s_mov_b32 s53, s41
	s_lshl_b64 s[40:41], s[52:53], 11
	s_add_u32 s50, s58, s40
	s_addc_u32 s51, s59, s41
	s_lshl_b64 s[40:41], s[52:53], 6
	s_add_u32 s40, s70, s40
	v_lshl_add_u64 v[212:213], s[38:39], 0, v[178:179]
	s_addc_u32 s41, s71, s41
	s_and_b64 vcc, exec, s[8:9]
	s_waitcnt vmcnt(1) lgkmcnt(0)
	v_pk_fma_f32 v[170:171], v[138:139], v[70:71], v[170:171]
	v_pk_fma_f32 v[174:175], v[142:143], v[66:67], v[174:175]
	v_pk_fma_f32 v[172:173], v[140:141], v[64:65], v[172:173]
	v_pk_fma_f32 v[168:169], v[136:137], v[68:69], v[168:169]
	v_pk_fma_f32 v[140:141], v[132:133], v[56:57], v[164:165]
	v_pk_fma_f32 v[136:137], v[124:125], v[60:61], v[160:161]
	global_store_dwordx4 v[212:213], v[172:175], off nt
	global_store_dwordx4 v[212:213], v[168:171], off offset:16 nt
	s_cbranch_vccnz .LBB0_1007
	v_pk_mul_f32 v[132:133], v[202:203], v[172:173]
	v_pk_mul_f32 v[138:139], v[208:209], v[170:171]
	v_cvt_pk_bf16_f32 v220, v132, v133
	v_mul_f32_e32 v132, v173, v173
	v_mul_f32_e32 v133, v175, v175
	v_fmac_f32_e32 v132, v172, v172
	v_fmac_f32_e32 v133, v174, v174
	v_pk_mul_f32 v[124:125], v[204:205], v[174:175]
	v_pk_mul_f32 v[142:143], v[194:195], v[168:169]
	v_cvt_pk_bf16_f32 v221, v124, v125
	v_add_f32_e32 v132, v132, v133
	v_cvt_pk_bf16_f32 v222, v142, v143
	v_cvt_pk_bf16_f32 v223, v138, v139
	v_mul_f32_e32 v133, v169, v169
	v_mul_f32_e32 v138, v171, v171
	v_fmac_f32_e32 v133, v168, v168
	v_fmac_f32_e32 v138, v170, v170
	v_lshl_add_u64 v[124:125], v[176:177], 1, s[50:51]
	v_add_f32_e32 v133, v133, v138
	v_pk_fma_f32 v[142:143], v[134:135], v[58:59], v[166:167]
	v_pk_fma_f32 v[138:139], v[126:127], v[62:63], v[162:163]
	v_pk_mul_f32 v[170:171], v[196:197], v[136:137]
	global_store_dwordx4 v[124:125], v[220:223], off
	v_add_f32_e32 v172, v132, v133
	global_store_dwordx4 v[212:213], v[140:143], off offset:512 nt
	global_store_dwordx4 v[212:213], v[136:139], off offset:528 nt
	v_pk_mul_f32 v[132:133], v[200:201], v[142:143]
	v_pk_mul_f32 v[160:161], v[198:199], v[140:141]
	v_pk_mul_f32 v[164:165], v[206:207], v[138:139]
	v_cvt_pk_bf16_f32 v168, v160, v161
	v_cvt_pk_bf16_f32 v169, v132, v133
	v_cvt_pk_bf16_f32 v170, v170, v171
	v_mul_f32_e32 v132, v139, v139
	v_cvt_pk_bf16_f32 v171, v164, v165
	global_store_dwordx4 v[124:125], v[168:171], off offset:256
	v_mul_f32_e32 v124, v141, v141
	v_mul_f32_e32 v125, v143, v143
	v_fmac_f32_e32 v124, v140, v140
	v_fmac_f32_e32 v125, v142, v142
	v_add_f32_e32 v124, v124, v125
	v_mul_f32_e32 v125, v137, v137
	v_fmac_f32_e32 v125, v136, v136
	v_fmac_f32_e32 v132, v138, v138
	v_add_f32_e32 v125, v125, v132
	v_add_f32_e32 v124, v124, v125
	v_add_f32_e32 v124, v172, v124
	v_mov_b32_e32 v125, v124
	s_nop 1
	v_permlane16_swap_b32_e32 v124, v125
	v_add_f32_e32 v124, v124, v125
	v_mov_b32_e32 v125, v124
	s_nop 1
	v_permlane32_swap_b32_e32 v124, v125
	s_and_saveexec_b64 s[52:53], s[4:5]
	s_cbranch_execz .LBB0_967
	v_add_f32_e32 v132, v124, v125
	v_lshrrev_b32_e32 v124, 4, v176
	s_lshl_b32 s64, s17, 2
	v_and_b32_e32 v124, 0xfffffc0, v124
	v_mov_b32_e32 v125, v177
	s_ashr_i32 s65, s64, 31
	v_lshl_add_u64 v[124:125], s[40:41], 0, v[124:125]
	v_lshl_add_u64 v[124:125], s[64:65], 2, v[124:125]
	s_lshl_b32 s44, s68, 2
	v_lshl_add_u64 v[124:125], v[124:125], 0, s[44:45]
	global_store_dword v[124:125], v132, off

.LBB0_974:
	s_mov_b64 s[52:53], 0x20000
	v_add_co_u32_e32 v114, vcc, 0x20000, v210
	v_lshl_add_u64 v[112:113], v[210:211], 0, s[52:53]
	s_nop 0
	v_addc_co_u32_e32 v115, vcc, 0, v211, vcc
	s_mov_b64 s[52:53], 0x20200
	global_load_dwordx4 v[136:139], v[114:115], off nt
	global_load_dwordx4 v[146:149], v[112:113], off offset:16 nt
	v_lshl_add_u64 v[112:113], v[210:211], 0, s[52:53]
	global_load_dwordx4 v[132:135], v[114:115], off offset:512 nt
	global_load_dwordx4 v[128:131], v[112:113], off offset:16 nt
	s_mov_b64 s[52:53], 0x30000
	v_add_co_u32_e32 v114, vcc, 0x30000, v210
	v_lshl_add_u64 v[112:113], v[210:211], 0, s[52:53]
	s_nop 0
	v_addc_co_u32_e32 v115, vcc, 0, v211, vcc
	s_mov_b64 s[52:53], 0x30200
	global_load_dwordx4 v[124:127], v[114:115], off nt
	global_load_dwordx4 v[120:123], v[112:113], off offset:16 nt
	v_lshl_add_u64 v[112:113], v[210:211], 0, s[52:53]
	global_load_dwordx4 v[116:119], v[114:115], off offset:512 nt
	s_nop 0
	global_load_dwordx4 v[112:115], v[112:113], off offset:16 nt
	s_mov_b64 s[98:99], 0x60000
	v_lshl_add_u64 v[226:227], v[226:227], 0, s[98:99]
	global_load_dword v233, v[226:227], off
	v_add_u32_e32 v144, 0x8000, v176
	v_mov_b32_e32 v145, v177
	s_and_b64 vcc, exec, s[8:9]
	s_waitcnt vmcnt(8)
	v_pk_fma_f32 v[142:143], v[110:111], v[66:67], v[138:139]
	v_pk_fma_f32 v[140:141], v[108:109], v[64:65], v[136:137]
	s_waitcnt vmcnt(7)
	v_pk_fma_f32 v[136:137], v[104:105], v[68:69], v[146:147]
	v_lshl_add_u64 v[104:105], v[144:145], 2, s[38:39]
	v_pk_fma_f32 v[138:139], v[106:107], v[70:71], v[148:149]
	global_store_dwordx4 v[104:105], v[140:143], off nt
	global_store_dwordx4 v[104:105], v[136:139], off offset:16 nt
	v_add_u32_e32 v146, 0x8080, v176
	s_waitcnt vmcnt(8)
	v_pk_fma_f32 v[104:105], v[100:101], v[56:57], v[132:133]
	s_waitcnt vmcnt(7)
	v_pk_fma_f32 v[108:109], v[96:97], v[60:61], v[128:129]
	s_cbranch_vccnz .LBB0_1009
	v_pk_mul_f32 v[96:97], v[204:205], v[142:143]
	v_pk_mul_f32 v[100:101], v[202:203], v[140:141]
	v_pk_mul_f32 v[106:107], v[208:209], v[138:139]
	v_cvt_pk_bf16_f32 v148, v100, v101
	v_cvt_pk_bf16_f32 v149, v96, v97
	v_lshl_add_u64 v[96:97], v[144:145], 1, s[50:51]
	v_pk_mul_f32 v[110:111], v[194:195], v[136:137]
	v_mul_f32_e32 v100, v139, v139
	v_cvt_pk_bf16_f32 v150, v110, v111
	v_cvt_pk_bf16_f32 v151, v106, v107
	global_store_dwordx4 v[96:97], v[148:151], off
	v_mul_f32_e32 v96, v141, v141
	v_mul_f32_e32 v97, v143, v143
	v_fmac_f32_e32 v96, v140, v140
	v_fmac_f32_e32 v97, v142, v142
	v_add_f32_e32 v96, v96, v97
	v_mul_f32_e32 v97, v137, v137
	v_fmac_f32_e32 v97, v136, v136
	v_fmac_f32_e32 v100, v138, v138
	v_add_f32_e32 v97, v97, v100
	v_mov_b32_e32 v147, v177
	v_add_f32_e32 v140, v96, v97
	v_pk_fma_f32 v[106:107], v[102:103], v[58:59], v[134:135]
	v_lshl_add_u64 v[96:97], v[146:147], 2, s[38:39]
	v_pk_fma_f32 v[110:111], v[98:99], v[62:63], v[130:131]
	global_store_dwordx4 v[96:97], v[104:107], off nt
	global_store_dwordx4 v[96:97], v[108:111], off offset:16 nt
	v_pk_mul_f32 v[96:97], v[200:201], v[106:107]
	v_pk_mul_f32 v[100:101], v[198:199], v[104:105]
	v_pk_mul_f32 v[128:129], v[206:207], v[110:111]
	v_cvt_pk_bf16_f32 v136, v100, v101
	v_cvt_pk_bf16_f32 v137, v96, v97
	v_lshl_add_u64 v[96:97], v[146:147], 1, s[50:51]
	v_pk_mul_f32 v[132:133], v[196:197], v[108:109]
	v_mul_f32_e32 v100, v111, v111
	v_cvt_pk_bf16_f32 v138, v132, v133
	v_cvt_pk_bf16_f32 v139, v128, v129
	global_store_dwordx4 v[96:97], v[136:139], off
	v_mul_f32_e32 v96, v105, v105
	v_mul_f32_e32 v97, v107, v107
	v_fmac_f32_e32 v96, v104, v104
	v_fmac_f32_e32 v97, v106, v106
	v_add_f32_e32 v96, v96, v97
	v_mul_f32_e32 v97, v109, v109
	v_fmac_f32_e32 v97, v108, v108
	v_fmac_f32_e32 v100, v110, v110
	v_add_f32_e32 v97, v97, v100
	v_add_f32_e32 v96, v96, v97
	v_add_f32_e32 v96, v140, v96
	v_mov_b32_e32 v97, v96
	s_nop 1
	v_permlane16_swap_b32_e32 v96, v97
	v_add_f32_e32 v96, v96, v97
	v_mov_b32_e32 v97, v96
	s_nop 1
	v_permlane32_swap_b32_e32 v96, v97
	s_and_saveexec_b64 s[52:53], s[4:5]
	s_cbranch_execz .LBB0_977
	v_add_f32_e32 v100, v96, v97
	v_lshrrev_b32_e32 v96, 4, v144
	s_lshl_b32 s64, s17, 2
	v_and_b32_e32 v96, 0xfffffc0, v96
	v_mov_b32_e32 v97, v177
	s_ashr_i32 s65, s64, 31
	v_lshl_add_u64 v[96:97], s[40:41], 0, v[96:97]
	v_lshl_add_u64 v[96:97], s[64:65], 2, v[96:97]
	s_lshl_b32 s44, s68, 2
	v_lshl_add_u64 v[96:97], v[96:97], 0, s[44:45]
	global_store_dword v[96:97], v100, off

.LBB0_979:
	s_nop 0
	v_add_u32_e32 v104, 0xc000, v176
	v_mov_b32_e32 v105, v177
	s_waitcnt vmcnt(6)
	v_pk_fma_f32 v[96:97], v[94:95], v[66:67], v[126:127]
	v_pk_fma_f32 v[94:95], v[92:93], v[64:65], v[124:125]
	s_waitcnt vmcnt(5)
	v_pk_fma_f32 v[98:99], v[88:89], v[68:69], v[120:121]
	v_lshl_add_u64 v[88:89], v[104:105], 2, s[38:39]
	v_pk_fma_f32 v[100:101], v[90:91], v[70:71], v[122:123]
	global_store_dwordx4 v[88:89], v[94:97], off nt
	global_store_dwordx4 v[88:89], v[98:101], off offset:16 nt
	s_and_b64 vcc, exec, s[8:9]
	v_add_u32_e32 v102, 0xc080, v176
	s_waitcnt vmcnt(6)
	v_pk_fma_f32 v[92:93], v[84:85], v[56:57], v[116:117]
	s_waitcnt vmcnt(5)
	v_pk_fma_f32 v[88:89], v[80:81], v[60:61], v[112:113]
	s_cbranch_vccnz .LBB0_1010
	v_pk_mul_f32 v[80:81], v[204:205], v[96:97]
	v_pk_mul_f32 v[84:85], v[202:203], v[94:95]
	v_pk_mul_f32 v[108:109], v[194:195], v[98:99]
	v_cvt_pk_bf16_f32 v106, v84, v85
	v_cvt_pk_bf16_f32 v107, v80, v81
	v_lshl_add_u64 v[80:81], v[104:105], 1, s[50:51]
	v_pk_mul_f32 v[90:91], v[208:209], v[100:101]
	v_cvt_pk_bf16_f32 v108, v108, v109
	v_mul_f32_e32 v84, v101, v101
	v_cvt_pk_bf16_f32 v109, v90, v91
	global_store_dwordx4 v[80:81], v[106:109], off
	v_mul_f32_e32 v80, v95, v95
	v_mul_f32_e32 v81, v97, v97
	v_fmac_f32_e32 v80, v94, v94
	v_fmac_f32_e32 v81, v96, v96
	v_add_f32_e32 v80, v80, v81
	v_mul_f32_e32 v81, v99, v99
	v_fmac_f32_e32 v81, v98, v98
	v_fmac_f32_e32 v84, v100, v100
	v_add_f32_e32 v81, v81, v84
	v_mov_b32_e32 v103, v177
	v_add_f32_e32 v105, v80, v81
	v_pk_fma_f32 v[94:95], v[86:87], v[58:59], v[118:119]
	v_lshl_add_u64 v[80:81], v[102:103], 2, s[38:39]
	v_pk_fma_f32 v[90:91], v[82:83], v[62:63], v[114:115]
	global_store_dwordx4 v[80:81], v[92:95], off nt
	global_store_dwordx4 v[80:81], v[88:91], off offset:16 nt
	v_pk_mul_f32 v[80:81], v[200:201], v[94:95]
	v_pk_mul_f32 v[84:85], v[198:199], v[92:93]
	v_pk_mul_f32 v[98:99], v[196:197], v[88:89]
	v_cvt_pk_bf16_f32 v96, v84, v85
	v_cvt_pk_bf16_f32 v97, v80, v81
	v_lshl_add_u64 v[80:81], v[102:103], 1, s[50:51]
	v_pk_mul_f32 v[100:101], v[206:207], v[90:91]
	v_cvt_pk_bf16_f32 v98, v98, v99
	v_mul_f32_e32 v84, v91, v91
	v_cvt_pk_bf16_f32 v99, v100, v101
	global_store_dwordx4 v[80:81], v[96:99], off
	v_mul_f32_e32 v80, v93, v93
	v_mul_f32_e32 v81, v95, v95
	v_fmac_f32_e32 v80, v92, v92
	v_fmac_f32_e32 v81, v94, v94
	v_add_f32_e32 v80, v80, v81
	v_mul_f32_e32 v81, v89, v89
	v_fmac_f32_e32 v81, v88, v88
	v_fmac_f32_e32 v84, v90, v90
	v_add_f32_e32 v81, v81, v84
	v_add_f32_e32 v80, v80, v81
	v_add_f32_e32 v80, v105, v80
	v_mov_b32_e32 v81, v80
	s_nop 1
	v_permlane16_swap_b32_e32 v80, v81
	v_add_f32_e32 v80, v80, v81
	v_mov_b32_e32 v81, v80
	s_nop 1
	v_permlane32_swap_b32_e32 v80, v81
	s_and_saveexec_b64 s[52:53], s[4:5]
	s_cbranch_execz .LBB0_982
	v_add_f32_e32 v84, v80, v81
	v_lshrrev_b32_e32 v80, 4, v104
	s_lshl_b32 s64, s17, 2
	v_and_b32_e32 v80, 0xfffffc0, v80
	v_mov_b32_e32 v81, v177
	s_ashr_i32 s65, s64, 31
	v_lshl_add_u64 v[80:81], s[40:41], 0, v[80:81]
	v_lshl_add_u64 v[80:81], s[64:65], 2, v[80:81]
	s_lshl_b32 s44, s68, 2
	v_lshl_add_u64 v[80:81], v[80:81], 0, s[44:45]
	global_store_dword v[80:81], v84, off

.LBB0_984:
	s_mov_b64 s[52:53], 0x80000
	v_add_co_u32_e32 v82, vcc, 0x80000, v210
	v_lshl_add_u64 v[80:81], v[210:211], 0, s[52:53]
	s_nop 0
	v_addc_co_u32_e32 v83, vcc, 0, v211, vcc
	s_mov_b64 s[52:53], 0x80200
	global_load_dwordx4 v[104:107], v[82:83], off nt
	global_load_dwordx4 v[114:117], v[80:81], off offset:16 nt
	v_lshl_add_u64 v[80:81], v[210:211], 0, s[52:53]
	global_load_dwordx4 v[100:103], v[82:83], off offset:512 nt
	global_load_dwordx4 v[96:99], v[80:81], off offset:16 nt
	s_mov_b64 s[52:53], 0x90000
	v_add_co_u32_e32 v82, vcc, 0x90000, v210
	v_lshl_add_u64 v[80:81], v[210:211], 0, s[52:53]
	s_nop 0
	v_addc_co_u32_e32 v83, vcc, 0, v211, vcc
	s_mov_b64 s[52:53], 0x90200
	global_load_dwordx4 v[92:95], v[82:83], off nt
	global_load_dwordx4 v[88:91], v[80:81], off offset:16 nt
	v_lshl_add_u64 v[80:81], v[210:211], 0, s[52:53]
	global_load_dwordx4 v[84:87], v[82:83], off offset:512 nt
	s_nop 0
	global_load_dwordx4 v[80:83], v[80:81], off offset:16 nt
	s_mov_b64 s[98:99], 0x20000
	v_lshl_add_u64 v[226:227], v[226:227], 0, s[98:99]
	global_load_dword v233, v[226:227], off
	v_add_u32_e32 v112, 0x20000, v176
	v_mov_b32_e32 v113, v177
	s_and_b64 vcc, exec, s[8:9]
	s_waitcnt vmcnt(8)
	v_pk_fma_f32 v[110:111], v[78:79], v[66:67], v[106:107]
	v_pk_fma_f32 v[108:109], v[76:77], v[64:65], v[104:105]
	s_waitcnt vmcnt(7)
	v_pk_fma_f32 v[104:105], v[72:73], v[68:69], v[114:115]
	v_lshl_add_u64 v[72:73], v[112:113], 2, s[38:39]
	v_pk_fma_f32 v[106:107], v[74:75], v[70:71], v[116:117]
	global_store_dwordx4 v[72:73], v[108:111], off nt
	global_store_dwordx4 v[72:73], v[104:107], off offset:16 nt
	v_add_u32_e32 v114, 0x20080, v176
	s_waitcnt vmcnt(8)
	v_pk_fma_f32 v[72:73], v[52:53], v[56:57], v[100:101]
	s_waitcnt vmcnt(7)
	v_pk_fma_f32 v[76:77], v[48:49], v[60:61], v[96:97]
	s_cbranch_vccnz .LBB0_1011
	v_pk_mul_f32 v[48:49], v[204:205], v[110:111]
	v_pk_mul_f32 v[52:53], v[202:203], v[108:109]
	v_pk_mul_f32 v[74:75], v[208:209], v[106:107]
	v_cvt_pk_bf16_f32 v116, v52, v53
	v_cvt_pk_bf16_f32 v117, v48, v49
	v_lshl_add_u64 v[48:49], v[112:113], 1, s[50:51]
	v_pk_mul_f32 v[78:79], v[194:195], v[104:105]
	v_mul_f32_e32 v52, v107, v107
	v_cvt_pk_bf16_f32 v118, v78, v79
	v_cvt_pk_bf16_f32 v119, v74, v75
	global_store_dwordx4 v[48:49], v[116:119], off
	v_mul_f32_e32 v48, v109, v109
	v_mul_f32_e32 v49, v111, v111
	v_fmac_f32_e32 v48, v108, v108
	v_fmac_f32_e32 v49, v110, v110
	v_add_f32_e32 v48, v48, v49
	v_mul_f32_e32 v49, v105, v105
	v_fmac_f32_e32 v49, v104, v104
	v_fmac_f32_e32 v52, v106, v106
	v_add_f32_e32 v49, v49, v52
	v_mov_b32_e32 v115, v177
	v_add_f32_e32 v108, v48, v49
	v_pk_fma_f32 v[74:75], v[54:55], v[58:59], v[102:103]
	v_lshl_add_u64 v[48:49], v[114:115], 2, s[38:39]
	v_pk_fma_f32 v[78:79], v[50:51], v[62:63], v[98:99]
	global_store_dwordx4 v[48:49], v[72:75], off nt
	global_store_dwordx4 v[48:49], v[76:79], off offset:16 nt
	v_pk_mul_f32 v[48:49], v[200:201], v[74:75]
	v_pk_mul_f32 v[52:53], v[198:199], v[72:73]
	v_pk_mul_f32 v[96:97], v[206:207], v[78:79]
	v_cvt_pk_bf16_f32 v104, v52, v53
	v_cvt_pk_bf16_f32 v105, v48, v49
	v_lshl_add_u64 v[48:49], v[114:115], 1, s[50:51]
	v_pk_mul_f32 v[100:101], v[196:197], v[76:77]
	v_mul_f32_e32 v52, v79, v79
	v_cvt_pk_bf16_f32 v106, v100, v101
	v_cvt_pk_bf16_f32 v107, v96, v97
	global_store_dwordx4 v[48:49], v[104:107], off
	v_mul_f32_e32 v48, v73, v73
	v_mul_f32_e32 v49, v75, v75
	v_fmac_f32_e32 v48, v72, v72
	v_fmac_f32_e32 v49, v74, v74
	v_add_f32_e32 v48, v48, v49
	v_mul_f32_e32 v49, v77, v77
	v_fmac_f32_e32 v49, v76, v76
	v_fmac_f32_e32 v52, v78, v78
	v_add_f32_e32 v49, v49, v52
	v_add_f32_e32 v48, v48, v49
	v_add_f32_e32 v48, v108, v48
	v_mov_b32_e32 v49, v48
	s_nop 1
	v_permlane16_swap_b32_e32 v48, v49
	v_add_f32_e32 v48, v48, v49
	v_mov_b32_e32 v49, v48
	s_nop 1
	v_permlane32_swap_b32_e32 v48, v49
	s_and_saveexec_b64 s[52:53], s[4:5]
	s_cbranch_execz .LBB0_987
	v_add_f32_e32 v52, v48, v49
	v_lshrrev_b32_e32 v48, 4, v112
	s_lshl_b32 s64, s17, 2
	v_and_b32_e32 v48, 0xfffffc0, v48
	v_mov_b32_e32 v49, v177
	s_ashr_i32 s65, s64, 31
	v_lshl_add_u64 v[48:49], s[40:41], 0, v[48:49]
	v_lshl_add_u64 v[48:49], s[64:65], 2, v[48:49]
	s_lshl_b32 s44, s68, 2
	v_lshl_add_u64 v[48:49], v[48:49], 0, s[44:45]
	global_store_dword v[48:49], v52, off

.LBB0_989:
	s_nop 0
	v_add_u32_e32 v72, 0x24000, v176
	v_mov_b32_e32 v73, v177
	s_waitcnt vmcnt(6)
	v_pk_fma_f32 v[48:49], v[46:47], v[66:67], v[94:95]
	v_pk_fma_f32 v[46:47], v[44:45], v[64:65], v[92:93]
	s_waitcnt vmcnt(5)
	v_pk_fma_f32 v[50:51], v[40:41], v[68:69], v[88:89]
	v_lshl_add_u64 v[40:41], v[72:73], 2, s[38:39]
	v_pk_fma_f32 v[52:53], v[42:43], v[70:71], v[90:91]
	global_store_dwordx4 v[40:41], v[46:49], off nt
	global_store_dwordx4 v[40:41], v[50:53], off offset:16 nt
	s_and_b64 vcc, exec, s[8:9]
	v_add_u32_e32 v54, 0x24080, v176
	s_waitcnt vmcnt(6)
	v_pk_fma_f32 v[44:45], v[36:37], v[56:57], v[84:85]
	s_waitcnt vmcnt(5)
	v_pk_fma_f32 v[40:41], v[32:33], v[60:61], v[80:81]
	s_cbranch_vccnz .LBB0_1012
	v_pk_mul_f32 v[32:33], v[204:205], v[48:49]
	v_pk_mul_f32 v[36:37], v[202:203], v[46:47]
	v_pk_mul_f32 v[76:77], v[194:195], v[50:51]
	v_cvt_pk_bf16_f32 v74, v36, v37
	v_cvt_pk_bf16_f32 v75, v32, v33
	v_lshl_add_u64 v[32:33], v[72:73], 1, s[50:51]
	v_pk_mul_f32 v[42:43], v[208:209], v[52:53]
	v_cvt_pk_bf16_f32 v76, v76, v77
	v_mul_f32_e32 v36, v53, v53
	v_cvt_pk_bf16_f32 v77, v42, v43
	global_store_dwordx4 v[32:33], v[74:77], off
	v_mul_f32_e32 v32, v47, v47
	v_mul_f32_e32 v33, v49, v49
	v_fmac_f32_e32 v32, v46, v46
	v_fmac_f32_e32 v33, v48, v48
	v_add_f32_e32 v32, v32, v33
	v_mul_f32_e32 v33, v51, v51
	v_fmac_f32_e32 v33, v50, v50
	v_fmac_f32_e32 v36, v52, v52
	v_add_f32_e32 v33, v33, v36
	v_mov_b32_e32 v55, v177
	v_add_f32_e32 v73, v32, v33
	v_pk_fma_f32 v[46:47], v[38:39], v[58:59], v[86:87]
	v_lshl_add_u64 v[32:33], v[54:55], 2, s[38:39]
	v_pk_fma_f32 v[42:43], v[34:35], v[62:63], v[82:83]
	global_store_dwordx4 v[32:33], v[44:47], off nt
	global_store_dwordx4 v[32:33], v[40:43], off offset:16 nt
	v_pk_mul_f32 v[32:33], v[200:201], v[46:47]
	v_pk_mul_f32 v[36:37], v[198:199], v[44:45]
	v_pk_mul_f32 v[50:51], v[196:197], v[40:41]
	v_cvt_pk_bf16_f32 v48, v36, v37
	v_cvt_pk_bf16_f32 v49, v32, v33
	v_lshl_add_u64 v[32:33], v[54:55], 1, s[50:51]
	v_pk_mul_f32 v[52:53], v[206:207], v[42:43]
	v_cvt_pk_bf16_f32 v50, v50, v51
	v_mul_f32_e32 v36, v43, v43
	v_cvt_pk_bf16_f32 v51, v52, v53
	global_store_dwordx4 v[32:33], v[48:51], off
	v_mul_f32_e32 v32, v45, v45
	v_mul_f32_e32 v33, v47, v47
	v_fmac_f32_e32 v32, v44, v44
	v_fmac_f32_e32 v33, v46, v46
	v_add_f32_e32 v32, v32, v33
	v_mul_f32_e32 v33, v41, v41
	v_fmac_f32_e32 v33, v40, v40
	v_fmac_f32_e32 v36, v42, v42
	v_add_f32_e32 v33, v33, v36
	v_add_f32_e32 v32, v32, v33
	v_add_f32_e32 v32, v73, v32
	v_mov_b32_e32 v33, v32
	s_nop 1
	v_permlane16_swap_b32_e32 v32, v33
	v_add_f32_e32 v32, v32, v33
	v_mov_b32_e32 v33, v32
	s_nop 1
	v_permlane32_swap_b32_e32 v32, v33
	s_and_saveexec_b64 s[52:53], s[4:5]
	s_cbranch_execz .LBB0_992
	v_add_f32_e32 v36, v32, v33
	v_lshrrev_b32_e32 v32, 4, v72
	s_lshl_b32 s64, s17, 2
	v_and_b32_e32 v32, 0xfffffc0, v32
	v_mov_b32_e32 v33, v177
	s_ashr_i32 s65, s64, 31
	v_lshl_add_u64 v[32:33], s[40:41], 0, v[32:33]
	v_lshl_add_u64 v[32:33], s[64:65], 2, v[32:33]
	s_lshl_b32 s44, s68, 2
	v_lshl_add_u64 v[32:33], v[32:33], 0, s[44:45]
	global_store_dword v[32:33], v36, off

.Lres_pre_skip_c3:
	s_lshl_b32 s38, s52, 8
	s_add_i32 s44, s38, 0xffff8000
	s_ashr_i32 s39, s38, 31
	s_lshl_b64 s[40:41], s[44:45], 12
	s_add_u32 s25, s14, s40
	s_addc_u32 s50, s15, s41
	s_lshl_b64 s[40:41], s[38:39], 12
	s_add_u32 s51, s10, s40
	s_addc_u32 s53, s11, s41
	s_cmpk_lt_i32 s52, 0x80
	s_cselect_b32 s41, s39, 0
	s_cselect_b32 s40, s38, s44
	s_cselect_b32 s44, s19, s47
	s_cselect_b32 s63, s18, s46
	s_cselect_b32 s52, s38, s38
	s_cselect_b32 s39, s53, s50
	s_cselect_b32 s38, s51, s25
	s_lshl_b64 s[50:51], s[40:41], 12
	s_add_u32 s50, s63, s50
	v_add_u32_e32 v176, v144, v230
	s_addc_u32 s51, s44, s51
	v_lshlrev_b64 v[178:179], 2, v[176:177]
	v_lshl_add_u64 v[210:211], s[50:51], 0, v[178:179]
	s_mov_b32 s25, 0x10000
	s_mov_b64 s[50:51], 0x10000
	v_add_co_u32_e32 v146, vcc, s25, v210
	v_lshl_add_u64 v[144:145], v[210:211], 0, s[50:51]
	s_nop 0
	v_addc_co_u32_e32 v147, vcc, 0, v211, vcc
	s_mov_b64 s[50:51], 0x10200
	global_load_dwordx4 v[168:171], v[210:211], off offset:16 nt
	global_load_dwordx4 v[172:175], v[210:211], off nt
	global_load_dwordx4 v[160:163], v[210:211], off offset:528 nt
	global_load_dwordx4 v[164:167], v[210:211], off offset:512 nt
	global_load_dwordx4 v[156:159], v[146:147], off nt
	global_load_dwordx4 v[152:155], v[144:145], off offset:16 nt
	v_lshl_add_u64 v[144:145], v[210:211], 0, s[50:51]
	global_load_dwordx4 v[148:151], v[146:147], off offset:512 nt
	s_nop 0
	global_load_dwordx4 v[144:147], v[144:145], off offset:16 nt
	v_mbcnt_lo_u32_b32 v226, -1, 0
	v_mbcnt_hi_u32_b32 v226, -1, v226
	v_lshrrev_b32_e32 v226, 4, v226
	v_lshrrev_b32_e32 v227, 1, v226
	v_and_b32_e32 v233, 1, v226
	v_lshlrev_b32_e32 v227, 16, v227
	v_lshl_add_u32 v227, v233, 9, v227
	v_lshlrev_b32_e32 v226, 5, v226
	v_sub_u32_e32 v226, v227, v226
	v_add_u32_e32 v226, 0x20000, v226
	v_mov_b32_e32 v227, 0
	v_lshl_add_u64 v[226:227], v[210:211], 0, v[226:227]
	global_load_dword v233, v[226:227], off
	s_waitcnt vmcnt(1) lgkmcnt(0)
	s_andn2_b64 vcc, exec, s[22:23]
	s_cbranch_vccnz .Lres_zero_c3
	v_pk_add_f32 v[194:195], v[194:195], 1.0 op_sel_hi:[1,0]
	v_pk_add_f32 v[196:197], v[196:197], 1.0 op_sel_hi:[1,0]
	v_pk_add_f32 v[198:199], v[198:199], 1.0 op_sel_hi:[1,0]
	v_pk_add_f32 v[200:201], v[200:201], 1.0 op_sel_hi:[1,0]
	v_pk_add_f32 v[202:203], v[202:203], 1.0 op_sel_hi:[1,0]
	v_pk_add_f32 v[204:205], v[204:205], 1.0 op_sel_hi:[1,0]
	v_pk_add_f32 v[206:207], v[206:207], 1.0 op_sel_hi:[1,0]
	v_pk_add_f32 v[208:209], v[208:209], 1.0 op_sel_hi:[1,0]
	v_pk_mul_f32 v[238:239], v[238:239], v[194:195]
	v_pk_mul_f32 v[240:241], v[240:241], v[196:197]
	v_pk_mul_f32 v[242:243], v[242:243], v[198:199]
	v_pk_mul_f32 v[244:245], v[244:245], v[200:201]
	v_pk_mul_f32 v[246:247], v[246:247], v[202:203]
	v_pk_mul_f32 v[248:249], v[248:249], v[204:205]
	v_pk_mul_f32 v[250:251], v[250:251], v[206:207]
	v_pk_mul_f32 v[252:253], v[252:253], v[208:209]
	v_mov_b32_e32 v202, v238
	v_mov_b32_e32 v203, v239
	v_mov_b32_e32 v204, v240
	v_mov_b32_e32 v205, v241
	v_mov_b32_e32 v194, v242
	v_mov_b32_e32 v195, v243
	v_mov_b32_e32 v208, v244
	v_mov_b32_e32 v209, v245
	v_mov_b32_e32 v198, v246
	v_mov_b32_e32 v199, v247
	v_mov_b32_e32 v200, v248
	v_mov_b32_e32 v201, v249
	v_mov_b32_e32 v196, v250
	v_mov_b32_e32 v197, v251
	v_mov_b32_e32 v206, v252
	v_mov_b32_e32 v207, v253
	s_branch .Lres_done_c3

.Lres_done_c3:
	s_mov_b32 s53, s41
	s_lshl_b64 s[40:41], s[52:53], 11
	s_add_u32 s50, s58, s40
	s_addc_u32 s51, s59, s41
	s_lshl_b64 s[40:41], s[52:53], 6
	s_add_u32 s40, s70, s40
	v_lshl_add_u64 v[212:213], s[38:39], 0, v[178:179]
	s_addc_u32 s41, s71, s41
	s_and_b64 vcc, exec, s[8:9]
	s_waitcnt vmcnt(1) lgkmcnt(0)
	v_pk_fma_f32 v[170:171], v[138:139], v[110:111], v[170:171]
	v_pk_fma_f32 v[174:175], v[142:143], v[106:107], v[174:175]
	v_pk_fma_f32 v[172:173], v[140:141], v[104:105], v[172:173]
	v_pk_fma_f32 v[168:169], v[136:137], v[108:109], v[168:169]
	v_pk_fma_f32 v[140:141], v[132:133], v[88:89], v[164:165]
	v_pk_fma_f32 v[136:137], v[128:129], v[92:93], v[160:161]
	global_store_dwordx4 v[212:213], v[172:175], off nt
	global_store_dwordx4 v[212:213], v[168:171], off offset:16 nt
	s_cbranch_vccnz .LBB0_1106
	v_pk_mul_f32 v[132:133], v[202:203], v[172:173]
	v_pk_mul_f32 v[138:139], v[208:209], v[170:171]
	v_cvt_pk_bf16_f32 v220, v132, v133
	v_mul_f32_e32 v132, v173, v173
	v_mul_f32_e32 v133, v175, v175
	v_fmac_f32_e32 v132, v172, v172
	v_fmac_f32_e32 v133, v174, v174
	v_pk_mul_f32 v[128:129], v[204:205], v[174:175]
	v_pk_mul_f32 v[142:143], v[194:195], v[168:169]
	v_cvt_pk_bf16_f32 v221, v128, v129
	v_add_f32_e32 v132, v132, v133
	v_cvt_pk_bf16_f32 v222, v142, v143
	v_cvt_pk_bf16_f32 v223, v138, v139
	v_mul_f32_e32 v133, v169, v169
	v_mul_f32_e32 v138, v171, v171
	v_fmac_f32_e32 v133, v168, v168
	v_fmac_f32_e32 v138, v170, v170
	v_lshl_add_u64 v[128:129], v[176:177], 1, s[50:51]
	v_add_f32_e32 v133, v133, v138
	v_pk_fma_f32 v[142:143], v[134:135], v[90:91], v[166:167]
	v_pk_fma_f32 v[138:139], v[130:131], v[94:95], v[162:163]
	v_pk_mul_f32 v[170:171], v[196:197], v[136:137]
	global_store_dwordx4 v[128:129], v[220:223], off
	v_add_f32_e32 v172, v132, v133
	global_store_dwordx4 v[212:213], v[140:143], off offset:512 nt
	global_store_dwordx4 v[212:213], v[136:139], off offset:528 nt
	v_pk_mul_f32 v[132:133], v[200:201], v[142:143]
	v_pk_mul_f32 v[160:161], v[198:199], v[140:141]
	v_pk_mul_f32 v[164:165], v[206:207], v[138:139]
	v_cvt_pk_bf16_f32 v168, v160, v161
	v_cvt_pk_bf16_f32 v169, v132, v133
	v_cvt_pk_bf16_f32 v170, v170, v171
	v_mul_f32_e32 v132, v139, v139
	v_cvt_pk_bf16_f32 v171, v164, v165
	global_store_dwordx4 v[128:129], v[168:171], off offset:256
	v_mul_f32_e32 v128, v141, v141
	v_mul_f32_e32 v129, v143, v143
	v_fmac_f32_e32 v128, v140, v140
	v_fmac_f32_e32 v129, v142, v142
	v_add_f32_e32 v128, v128, v129
	v_mul_f32_e32 v129, v137, v137
	v_fmac_f32_e32 v129, v136, v136
	v_fmac_f32_e32 v132, v138, v138
	v_add_f32_e32 v129, v129, v132
	v_add_f32_e32 v128, v128, v129
	v_add_f32_e32 v128, v172, v128
	v_mov_b32_e32 v129, v128
	s_nop 1
	v_permlane16_swap_b32_e32 v128, v129
	v_add_f32_e32 v128, v128, v129
	v_mov_b32_e32 v129, v128
	s_nop 1
	v_permlane32_swap_b32_e32 v128, v129
	s_and_saveexec_b64 s[52:53], s[4:5]
	s_cbranch_execz .LBB0_1066
	v_add_f32_e32 v132, v128, v129
	v_lshrrev_b32_e32 v128, 4, v176
	s_lshl_b32 s64, s69, 2
	v_and_b32_e32 v128, 0xfffffc0, v128
	v_mov_b32_e32 v129, v177
	s_ashr_i32 s65, s64, 31
	v_lshl_add_u64 v[128:129], s[40:41], 0, v[128:129]
	v_lshl_add_u64 v[128:129], s[64:65], 2, v[128:129]
	s_lshl_b32 s44, s80, 2
	v_lshl_add_u64 v[128:129], v[128:129], 0, s[44:45]
	global_store_dword v[128:129], v132, off

.LBB0_1073:
	s_mov_b64 s[52:53], 0x20000
	v_add_co_u32_e32 v114, vcc, 0x20000, v210
	v_lshl_add_u64 v[112:113], v[210:211], 0, s[52:53]
	s_nop 0
	v_addc_co_u32_e32 v115, vcc, 0, v211, vcc
	s_mov_b64 s[52:53], 0x20200
	global_load_dwordx4 v[136:139], v[114:115], off nt
	global_load_dwordx4 v[146:149], v[112:113], off offset:16 nt
	v_lshl_add_u64 v[112:113], v[210:211], 0, s[52:53]
	global_load_dwordx4 v[132:135], v[114:115], off offset:512 nt
	global_load_dwordx4 v[128:131], v[112:113], off offset:16 nt
	s_mov_b64 s[52:53], 0x30000
	v_add_co_u32_e32 v114, vcc, 0x30000, v210
	v_lshl_add_u64 v[112:113], v[210:211], 0, s[52:53]
	s_nop 0
	v_addc_co_u32_e32 v115, vcc, 0, v211, vcc
	s_mov_b64 s[52:53], 0x30200
	global_load_dwordx4 v[124:127], v[114:115], off nt
	global_load_dwordx4 v[120:123], v[112:113], off offset:16 nt
	v_lshl_add_u64 v[112:113], v[210:211], 0, s[52:53]
	global_load_dwordx4 v[116:119], v[114:115], off offset:512 nt
	s_nop 0
	global_load_dwordx4 v[112:115], v[112:113], off offset:16 nt
	s_mov_b64 s[98:99], 0x60000
	v_lshl_add_u64 v[226:227], v[226:227], 0, s[98:99]
	global_load_dword v233, v[226:227], off
	v_add_u32_e32 v144, 0x8000, v176
	v_mov_b32_e32 v145, v177
	s_and_b64 vcc, exec, s[8:9]
	s_waitcnt vmcnt(8)
	v_pk_fma_f32 v[142:143], v[102:103], v[106:107], v[138:139]
	v_pk_fma_f32 v[140:141], v[100:101], v[104:105], v[136:137]
	s_waitcnt vmcnt(7)
	v_pk_fma_f32 v[136:137], v[96:97], v[108:109], v[146:147]
	v_lshl_add_u64 v[96:97], v[144:145], 2, s[38:39]
	v_pk_fma_f32 v[138:139], v[98:99], v[110:111], v[148:149]
	global_store_dwordx4 v[96:97], v[140:143], off nt
	global_store_dwordx4 v[96:97], v[136:139], off offset:16 nt
	v_add_u32_e32 v146, 0x8080, v176
	s_waitcnt vmcnt(8)
	v_pk_fma_f32 v[96:97], v[84:85], v[88:89], v[132:133]
	s_waitcnt vmcnt(7)
	v_pk_fma_f32 v[100:101], v[80:81], v[92:93], v[128:129]
	s_cbranch_vccnz .LBB0_1108
	v_pk_mul_f32 v[80:81], v[204:205], v[142:143]
	v_pk_mul_f32 v[84:85], v[202:203], v[140:141]
	v_pk_mul_f32 v[98:99], v[208:209], v[138:139]
	v_cvt_pk_bf16_f32 v148, v84, v85
	v_cvt_pk_bf16_f32 v149, v80, v81
	v_lshl_add_u64 v[80:81], v[144:145], 1, s[50:51]
	v_pk_mul_f32 v[102:103], v[194:195], v[136:137]
	v_mul_f32_e32 v84, v139, v139
	v_cvt_pk_bf16_f32 v150, v102, v103
	v_cvt_pk_bf16_f32 v151, v98, v99
	global_store_dwordx4 v[80:81], v[148:151], off
	v_mul_f32_e32 v80, v141, v141
	v_mul_f32_e32 v81, v143, v143
	v_fmac_f32_e32 v80, v140, v140
	v_fmac_f32_e32 v81, v142, v142
	v_add_f32_e32 v80, v80, v81
	v_mul_f32_e32 v81, v137, v137
	v_fmac_f32_e32 v81, v136, v136
	v_fmac_f32_e32 v84, v138, v138
	v_add_f32_e32 v81, v81, v84
	v_mov_b32_e32 v147, v177
	v_add_f32_e32 v140, v80, v81
	v_pk_fma_f32 v[98:99], v[86:87], v[90:91], v[134:135]
	v_lshl_add_u64 v[80:81], v[146:147], 2, s[38:39]
	v_pk_fma_f32 v[102:103], v[82:83], v[94:95], v[130:131]
	global_store_dwordx4 v[80:81], v[96:99], off nt
	global_store_dwordx4 v[80:81], v[100:103], off offset:16 nt
	v_pk_mul_f32 v[80:81], v[200:201], v[98:99]
	v_pk_mul_f32 v[84:85], v[198:199], v[96:97]
	v_pk_mul_f32 v[128:129], v[206:207], v[102:103]
	v_cvt_pk_bf16_f32 v136, v84, v85
	v_cvt_pk_bf16_f32 v137, v80, v81
	v_lshl_add_u64 v[80:81], v[146:147], 1, s[50:51]
	v_pk_mul_f32 v[132:133], v[196:197], v[100:101]
	v_mul_f32_e32 v84, v103, v103
	v_cvt_pk_bf16_f32 v138, v132, v133
	v_cvt_pk_bf16_f32 v139, v128, v129
	global_store_dwordx4 v[80:81], v[136:139], off
	v_mul_f32_e32 v80, v97, v97
	v_mul_f32_e32 v81, v99, v99
	v_fmac_f32_e32 v80, v96, v96
	v_fmac_f32_e32 v81, v98, v98
	v_add_f32_e32 v80, v80, v81
	v_mul_f32_e32 v81, v101, v101
	v_fmac_f32_e32 v81, v100, v100
	v_fmac_f32_e32 v84, v102, v102
	v_add_f32_e32 v81, v81, v84
	v_add_f32_e32 v80, v80, v81
	v_add_f32_e32 v80, v140, v80
	v_mov_b32_e32 v81, v80
	s_nop 1
	v_permlane16_swap_b32_e32 v80, v81
	v_add_f32_e32 v80, v80, v81
	v_mov_b32_e32 v81, v80
	s_nop 1
	v_permlane32_swap_b32_e32 v80, v81
	s_and_saveexec_b64 s[52:53], s[4:5]
	s_cbranch_execz .LBB0_1076
	v_add_f32_e32 v84, v80, v81
	v_lshrrev_b32_e32 v80, 4, v144
	s_lshl_b32 s64, s69, 2
	v_and_b32_e32 v80, 0xfffffc0, v80
	v_mov_b32_e32 v81, v177
	s_ashr_i32 s65, s64, 31
	v_lshl_add_u64 v[80:81], s[40:41], 0, v[80:81]
	v_lshl_add_u64 v[80:81], s[64:65], 2, v[80:81]
	s_lshl_b32 s44, s80, 2
	v_lshl_add_u64 v[80:81], v[80:81], 0, s[44:45]
	global_store_dword v[80:81], v84, off

.LBB0_1078:
	s_nop 0
	v_add_u32_e32 v96, 0xc000, v176
	v_mov_b32_e32 v97, v177
	s_waitcnt vmcnt(6)
	v_pk_fma_f32 v[80:81], v[78:79], v[106:107], v[126:127]
	v_pk_fma_f32 v[78:79], v[76:77], v[104:105], v[124:125]
	s_waitcnt vmcnt(5)
	v_pk_fma_f32 v[82:83], v[72:73], v[108:109], v[120:121]
	v_lshl_add_u64 v[72:73], v[96:97], 2, s[38:39]
	v_pk_fma_f32 v[84:85], v[74:75], v[110:111], v[122:123]
	global_store_dwordx4 v[72:73], v[78:81], off nt
	global_store_dwordx4 v[72:73], v[82:85], off offset:16 nt
	s_and_b64 vcc, exec, s[8:9]
	v_add_u32_e32 v86, 0xc080, v176
	s_waitcnt vmcnt(6)
	v_pk_fma_f32 v[76:77], v[68:69], v[88:89], v[116:117]
	s_waitcnt vmcnt(5)
	v_pk_fma_f32 v[72:73], v[64:65], v[92:93], v[112:113]
	s_cbranch_vccnz .LBB0_1109
	v_pk_mul_f32 v[64:65], v[204:205], v[80:81]
	v_pk_mul_f32 v[68:69], v[202:203], v[78:79]
	v_pk_mul_f32 v[100:101], v[194:195], v[82:83]
	v_cvt_pk_bf16_f32 v98, v68, v69
	v_cvt_pk_bf16_f32 v99, v64, v65
	v_lshl_add_u64 v[64:65], v[96:97], 1, s[50:51]
	v_pk_mul_f32 v[74:75], v[208:209], v[84:85]
	v_cvt_pk_bf16_f32 v100, v100, v101
	v_mul_f32_e32 v68, v85, v85
	v_cvt_pk_bf16_f32 v101, v74, v75
	global_store_dwordx4 v[64:65], v[98:101], off
	v_mul_f32_e32 v64, v79, v79
	v_mul_f32_e32 v65, v81, v81
	v_fmac_f32_e32 v64, v78, v78
	v_fmac_f32_e32 v65, v80, v80
	v_add_f32_e32 v64, v64, v65
	v_mul_f32_e32 v65, v83, v83
	v_fmac_f32_e32 v65, v82, v82
	v_fmac_f32_e32 v68, v84, v84
	v_add_f32_e32 v65, v65, v68
	v_mov_b32_e32 v87, v177
	v_add_f32_e32 v97, v64, v65
	v_pk_fma_f32 v[78:79], v[70:71], v[90:91], v[118:119]
	v_lshl_add_u64 v[64:65], v[86:87], 2, s[38:39]
	v_pk_fma_f32 v[74:75], v[66:67], v[94:95], v[114:115]
	global_store_dwordx4 v[64:65], v[76:79], off nt
	global_store_dwordx4 v[64:65], v[72:75], off offset:16 nt
	v_pk_mul_f32 v[64:65], v[200:201], v[78:79]
	v_pk_mul_f32 v[68:69], v[198:199], v[76:77]
	v_pk_mul_f32 v[82:83], v[196:197], v[72:73]
	v_cvt_pk_bf16_f32 v80, v68, v69
	v_cvt_pk_bf16_f32 v81, v64, v65
	v_lshl_add_u64 v[64:65], v[86:87], 1, s[50:51]
	v_pk_mul_f32 v[84:85], v[206:207], v[74:75]
	v_cvt_pk_bf16_f32 v82, v82, v83
	v_mul_f32_e32 v68, v75, v75
	v_cvt_pk_bf16_f32 v83, v84, v85
	global_store_dwordx4 v[64:65], v[80:83], off
	v_mul_f32_e32 v64, v77, v77
	v_mul_f32_e32 v65, v79, v79
	v_fmac_f32_e32 v64, v76, v76
	v_fmac_f32_e32 v65, v78, v78
	v_add_f32_e32 v64, v64, v65
	v_mul_f32_e32 v65, v73, v73
	v_fmac_f32_e32 v65, v72, v72
	v_fmac_f32_e32 v68, v74, v74
	v_add_f32_e32 v65, v65, v68
	v_add_f32_e32 v64, v64, v65
	v_add_f32_e32 v64, v97, v64
	v_mov_b32_e32 v65, v64
	s_nop 1
	v_permlane16_swap_b32_e32 v64, v65
	v_add_f32_e32 v64, v64, v65
	v_mov_b32_e32 v65, v64
	s_nop 1
	v_permlane32_swap_b32_e32 v64, v65
	s_and_saveexec_b64 s[52:53], s[4:5]
	s_cbranch_execz .LBB0_1081
	v_add_f32_e32 v68, v64, v65
	v_lshrrev_b32_e32 v64, 4, v96
	s_lshl_b32 s64, s69, 2
	v_and_b32_e32 v64, 0xfffffc0, v64
	v_mov_b32_e32 v65, v177
	s_ashr_i32 s65, s64, 31
	v_lshl_add_u64 v[64:65], s[40:41], 0, v[64:65]
	v_lshl_add_u64 v[64:65], s[64:65], 2, v[64:65]
	s_lshl_b32 s44, s80, 2
	v_lshl_add_u64 v[64:65], v[64:65], 0, s[44:45]
	global_store_dword v[64:65], v68, off

.LBB0_1083:
	s_mov_b64 s[52:53], 0x80000
	v_add_co_u32_e32 v66, vcc, 0x80000, v210
	v_lshl_add_u64 v[64:65], v[210:211], 0, s[52:53]
	s_nop 0
	v_addc_co_u32_e32 v67, vcc, 0, v211, vcc
	s_mov_b64 s[52:53], 0x80200
	global_load_dwordx4 v[96:99], v[66:67], off nt
	global_load_dwordx4 v[114:117], v[64:65], off offset:16 nt
	v_lshl_add_u64 v[64:65], v[210:211], 0, s[52:53]
	global_load_dwordx4 v[84:87], v[66:67], off offset:512 nt
	global_load_dwordx4 v[80:83], v[64:65], off offset:16 nt
	s_mov_b64 s[52:53], 0x90000
	v_add_co_u32_e32 v66, vcc, 0x90000, v210
	v_lshl_add_u64 v[64:65], v[210:211], 0, s[52:53]
	s_nop 0
	v_addc_co_u32_e32 v67, vcc, 0, v211, vcc
	s_mov_b64 s[52:53], 0x90200
	global_load_dwordx4 v[76:79], v[66:67], off nt
	global_load_dwordx4 v[72:75], v[64:65], off offset:16 nt
	v_lshl_add_u64 v[64:65], v[210:211], 0, s[52:53]
	global_load_dwordx4 v[68:71], v[66:67], off offset:512 nt
	s_nop 0
	global_load_dwordx4 v[64:67], v[64:65], off offset:16 nt
	s_mov_b64 s[98:99], 0x20000
	v_lshl_add_u64 v[226:227], v[226:227], 0, s[98:99]
	global_load_dword v233, v[226:227], off
	v_add_u32_e32 v112, 0x20000, v176
	v_mov_b32_e32 v113, v177
	s_and_b64 vcc, exec, s[8:9]
	s_waitcnt vmcnt(8)
	v_pk_fma_f32 v[102:103], v[62:63], v[106:107], v[98:99]
	v_pk_fma_f32 v[100:101], v[60:61], v[104:105], v[96:97]
	s_waitcnt vmcnt(7)
	v_pk_fma_f32 v[96:97], v[56:57], v[108:109], v[114:115]
	v_lshl_add_u64 v[56:57], v[112:113], 2, s[38:39]
	v_pk_fma_f32 v[98:99], v[58:59], v[110:111], v[116:117]
	global_store_dwordx4 v[56:57], v[100:103], off nt
	global_store_dwordx4 v[56:57], v[96:99], off offset:16 nt
	v_add_u32_e32 v114, 0x20080, v176
	s_waitcnt vmcnt(8)
	v_pk_fma_f32 v[56:57], v[52:53], v[88:89], v[84:85]
	s_waitcnt vmcnt(7)
	v_pk_fma_f32 v[60:61], v[48:49], v[92:93], v[80:81]
	s_cbranch_vccnz .LBB0_1110
	v_pk_mul_f32 v[48:49], v[204:205], v[102:103]
	v_pk_mul_f32 v[52:53], v[202:203], v[100:101]
	v_pk_mul_f32 v[58:59], v[208:209], v[98:99]
	v_cvt_pk_bf16_f32 v116, v52, v53
	v_cvt_pk_bf16_f32 v117, v48, v49
	v_lshl_add_u64 v[48:49], v[112:113], 1, s[50:51]
	v_pk_mul_f32 v[62:63], v[194:195], v[96:97]
	v_mul_f32_e32 v52, v99, v99
	v_cvt_pk_bf16_f32 v118, v62, v63
	v_cvt_pk_bf16_f32 v119, v58, v59
	global_store_dwordx4 v[48:49], v[116:119], off
	v_mul_f32_e32 v48, v101, v101
	v_mul_f32_e32 v49, v103, v103
	v_fmac_f32_e32 v48, v100, v100
	v_fmac_f32_e32 v49, v102, v102
	v_add_f32_e32 v48, v48, v49
	v_mul_f32_e32 v49, v97, v97
	v_fmac_f32_e32 v49, v96, v96
	v_fmac_f32_e32 v52, v98, v98
	v_add_f32_e32 v49, v49, v52
	v_mov_b32_e32 v115, v177
	v_add_f32_e32 v100, v48, v49
	v_pk_fma_f32 v[58:59], v[54:55], v[90:91], v[86:87]
	v_lshl_add_u64 v[48:49], v[114:115], 2, s[38:39]
	v_pk_fma_f32 v[62:63], v[50:51], v[94:95], v[82:83]
	global_store_dwordx4 v[48:49], v[56:59], off nt
	global_store_dwordx4 v[48:49], v[60:63], off offset:16 nt
	v_pk_mul_f32 v[48:49], v[200:201], v[58:59]
	v_pk_mul_f32 v[52:53], v[198:199], v[56:57]
	v_pk_mul_f32 v[80:81], v[206:207], v[62:63]
	v_cvt_pk_bf16_f32 v96, v52, v53
	v_cvt_pk_bf16_f32 v97, v48, v49
	v_lshl_add_u64 v[48:49], v[114:115], 1, s[50:51]
	v_pk_mul_f32 v[84:85], v[196:197], v[60:61]
	v_mul_f32_e32 v52, v63, v63
	v_cvt_pk_bf16_f32 v98, v84, v85
	v_cvt_pk_bf16_f32 v99, v80, v81
	global_store_dwordx4 v[48:49], v[96:99], off
	v_mul_f32_e32 v48, v57, v57
	v_mul_f32_e32 v49, v59, v59
	v_fmac_f32_e32 v48, v56, v56
	v_fmac_f32_e32 v49, v58, v58
	v_add_f32_e32 v48, v48, v49
	v_mul_f32_e32 v49, v61, v61
	v_fmac_f32_e32 v49, v60, v60
	v_fmac_f32_e32 v52, v62, v62
	v_add_f32_e32 v49, v49, v52
	v_add_f32_e32 v48, v48, v49
	v_add_f32_e32 v48, v100, v48
	v_mov_b32_e32 v49, v48
	s_nop 1
	v_permlane16_swap_b32_e32 v48, v49
	v_add_f32_e32 v48, v48, v49
	v_mov_b32_e32 v49, v48
	s_nop 1
	v_permlane32_swap_b32_e32 v48, v49
	s_and_saveexec_b64 s[52:53], s[4:5]
	s_cbranch_execz .LBB0_1086
	v_add_f32_e32 v52, v48, v49
	v_lshrrev_b32_e32 v48, 4, v112
	s_lshl_b32 s64, s69, 2
	v_and_b32_e32 v48, 0xfffffc0, v48
	v_mov_b32_e32 v49, v177
	s_ashr_i32 s65, s64, 31
	v_lshl_add_u64 v[48:49], s[40:41], 0, v[48:49]
	v_lshl_add_u64 v[48:49], s[64:65], 2, v[48:49]
	s_lshl_b32 s44, s80, 2
	v_lshl_add_u64 v[48:49], v[48:49], 0, s[44:45]
	global_store_dword v[48:49], v52, off

.LBB0_1088:
	s_nop 0
	v_add_u32_e32 v56, 0x24000, v176
	v_mov_b32_e32 v57, v177
	s_waitcnt vmcnt(6)
	v_pk_fma_f32 v[48:49], v[46:47], v[106:107], v[78:79]
	v_pk_fma_f32 v[46:47], v[44:45], v[104:105], v[76:77]
	s_waitcnt vmcnt(5)
	v_pk_fma_f32 v[50:51], v[40:41], v[108:109], v[72:73]
	v_lshl_add_u64 v[40:41], v[56:57], 2, s[38:39]
	v_pk_fma_f32 v[52:53], v[42:43], v[110:111], v[74:75]
	global_store_dwordx4 v[40:41], v[46:49], off nt
	global_store_dwordx4 v[40:41], v[50:53], off offset:16 nt
	s_and_b64 vcc, exec, s[8:9]
	v_add_u32_e32 v54, 0x24080, v176
	s_waitcnt vmcnt(6)
	v_pk_fma_f32 v[44:45], v[36:37], v[88:89], v[68:69]
	s_waitcnt vmcnt(5)
	v_pk_fma_f32 v[40:41], v[32:33], v[92:93], v[64:65]
	s_cbranch_vccnz .LBB0_1111
	v_pk_mul_f32 v[32:33], v[204:205], v[48:49]
	v_pk_mul_f32 v[36:37], v[202:203], v[46:47]
	v_pk_mul_f32 v[60:61], v[194:195], v[50:51]
	v_cvt_pk_bf16_f32 v58, v36, v37
	v_cvt_pk_bf16_f32 v59, v32, v33
	v_lshl_add_u64 v[32:33], v[56:57], 1, s[50:51]
	v_pk_mul_f32 v[42:43], v[208:209], v[52:53]
	v_cvt_pk_bf16_f32 v60, v60, v61
	v_mul_f32_e32 v36, v53, v53
	v_cvt_pk_bf16_f32 v61, v42, v43
	global_store_dwordx4 v[32:33], v[58:61], off
	v_mul_f32_e32 v32, v47, v47
	v_mul_f32_e32 v33, v49, v49
	v_fmac_f32_e32 v32, v46, v46
	v_fmac_f32_e32 v33, v48, v48
	v_add_f32_e32 v32, v32, v33
	v_mul_f32_e32 v33, v51, v51
	v_fmac_f32_e32 v33, v50, v50
	v_fmac_f32_e32 v36, v52, v52
	v_add_f32_e32 v33, v33, v36
	v_mov_b32_e32 v55, v177
	v_add_f32_e32 v57, v32, v33
	v_pk_fma_f32 v[46:47], v[38:39], v[90:91], v[70:71]
	v_lshl_add_u64 v[32:33], v[54:55], 2, s[38:39]
	v_pk_fma_f32 v[42:43], v[34:35], v[94:95], v[66:67]
	global_store_dwordx4 v[32:33], v[44:47], off nt
	global_store_dwordx4 v[32:33], v[40:43], off offset:16 nt
	v_pk_mul_f32 v[32:33], v[200:201], v[46:47]
	v_pk_mul_f32 v[36:37], v[198:199], v[44:45]
	v_pk_mul_f32 v[50:51], v[196:197], v[40:41]
	v_cvt_pk_bf16_f32 v48, v36, v37
	v_cvt_pk_bf16_f32 v49, v32, v33
	v_lshl_add_u64 v[32:33], v[54:55], 1, s[50:51]
	v_pk_mul_f32 v[52:53], v[206:207], v[42:43]
	v_cvt_pk_bf16_f32 v50, v50, v51
	v_mul_f32_e32 v36, v43, v43
	v_cvt_pk_bf16_f32 v51, v52, v53
	global_store_dwordx4 v[32:33], v[48:51], off
	v_mul_f32_e32 v32, v45, v45
	v_mul_f32_e32 v33, v47, v47
	v_fmac_f32_e32 v32, v44, v44
	v_fmac_f32_e32 v33, v46, v46
	v_add_f32_e32 v32, v32, v33
	v_mul_f32_e32 v33, v41, v41
	v_fmac_f32_e32 v33, v40, v40
	v_fmac_f32_e32 v36, v42, v42
	v_add_f32_e32 v33, v33, v36
	v_add_f32_e32 v32, v32, v33
	v_add_f32_e32 v32, v57, v32
	v_mov_b32_e32 v33, v32
	s_nop 1
	v_permlane16_swap_b32_e32 v32, v33
	v_add_f32_e32 v32, v32, v33
	v_mov_b32_e32 v33, v32
	s_nop 1
	v_permlane32_swap_b32_e32 v32, v33
	s_and_saveexec_b64 s[52:53], s[4:5]
	s_cbranch_execz .LBB0_1091
	v_add_f32_e32 v36, v32, v33
	v_lshrrev_b32_e32 v32, 4, v56
	s_lshl_b32 s64, s69, 2
	v_and_b32_e32 v32, 0xfffffc0, v32
	v_mov_b32_e32 v33, v177
	s_ashr_i32 s65, s64, 31
	v_lshl_add_u64 v[32:33], s[40:41], 0, v[32:33]
	v_lshl_add_u64 v[32:33], s[64:65], 2, v[32:33]
	s_lshl_b32 s44, s80, 2
	v_lshl_add_u64 v[32:33], v[32:33], 0, s[44:45]
	global_store_dword v[32:33], v36, off

.Lres_pre_skip_c4:
	s_lshl_b32 s42, s40, 8
	s_add_i32 s44, s42, 0xffff8000
	s_ashr_i32 s43, s42, 31
	s_lshl_b64 s[50:51], s[44:45], 12
	s_add_u32 s25, s14, s50
	s_addc_u32 s27, s15, s51
	s_lshl_b64 s[50:51], s[42:43], 12
	s_add_u32 s52, s10, s50
	s_addc_u32 s41, s11, s51
	s_cmpk_lt_i32 s40, 0x80
	s_cselect_b32 s51, s43, 0
	s_cselect_b32 s50, s42, s44
	s_cselect_b32 s43, s1, s47
	s_cselect_b32 s44, s0, s46
	s_cselect_b32 s42, s42, s42
	s_cselect_b32 s41, s41, s27
	s_cselect_b32 s40, s52, s25
	s_lshl_b64 s[52:53], s[50:51], 12
	s_add_u32 s52, s44, s52
	v_add_u32_e32 v176, v230, v144
	s_addc_u32 s53, s43, s53
	v_lshlrev_b64 v[178:179], 2, v[176:177]
	v_lshl_add_u64 v[210:211], s[52:53], 0, v[178:179]
	s_mov_b32 s25, 0x10000
	s_mov_b64 s[52:53], 0x10000
	v_add_co_u32_e32 v146, vcc, s25, v210
	v_lshl_add_u64 v[144:145], v[210:211], 0, s[52:53]
	s_nop 0
	v_addc_co_u32_e32 v147, vcc, 0, v211, vcc
	s_mov_b64 s[52:53], 0x10200
	global_load_dwordx4 v[168:171], v[210:211], off offset:16 nt
	global_load_dwordx4 v[172:175], v[210:211], off nt
	global_load_dwordx4 v[160:163], v[210:211], off offset:528 nt
	global_load_dwordx4 v[164:167], v[210:211], off offset:512 nt
	global_load_dwordx4 v[156:159], v[146:147], off nt
	global_load_dwordx4 v[152:155], v[144:145], off offset:16 nt
	v_lshl_add_u64 v[144:145], v[210:211], 0, s[52:53]
	global_load_dwordx4 v[148:151], v[146:147], off offset:512 nt
	s_nop 0
	global_load_dwordx4 v[144:147], v[144:145], off offset:16 nt
	v_mbcnt_lo_u32_b32 v226, -1, 0
	v_mbcnt_hi_u32_b32 v226, -1, v226
	v_lshrrev_b32_e32 v226, 4, v226
	v_lshrrev_b32_e32 v227, 1, v226
	v_and_b32_e32 v233, 1, v226
	v_lshlrev_b32_e32 v227, 16, v227
	v_lshl_add_u32 v227, v233, 9, v227
	v_lshlrev_b32_e32 v226, 5, v226
	v_sub_u32_e32 v226, v227, v226
	v_add_u32_e32 v226, 0x20000, v226
	v_mov_b32_e32 v227, 0
	v_lshl_add_u64 v[226:227], v[210:211], 0, v[226:227]
	global_load_dword v233, v[226:227], off
	s_waitcnt vmcnt(1) lgkmcnt(0)
	s_andn2_b64 vcc, exec, s[22:23]
	s_cbranch_vccnz .Lres_zero_c4
	v_pk_add_f32 v[194:195], v[194:195], 1.0 op_sel_hi:[1,0]
	v_pk_add_f32 v[196:197], v[196:197], 1.0 op_sel_hi:[1,0]
	v_pk_add_f32 v[198:199], v[198:199], 1.0 op_sel_hi:[1,0]
	v_pk_add_f32 v[200:201], v[200:201], 1.0 op_sel_hi:[1,0]
	v_pk_add_f32 v[202:203], v[202:203], 1.0 op_sel_hi:[1,0]
	v_pk_add_f32 v[204:205], v[204:205], 1.0 op_sel_hi:[1,0]
	v_pk_add_f32 v[206:207], v[206:207], 1.0 op_sel_hi:[1,0]
	v_pk_add_f32 v[208:209], v[208:209], 1.0 op_sel_hi:[1,0]
	v_pk_mul_f32 v[238:239], v[238:239], v[194:195]
	v_pk_mul_f32 v[240:241], v[240:241], v[196:197]
	v_pk_mul_f32 v[242:243], v[242:243], v[198:199]
	v_pk_mul_f32 v[244:245], v[244:245], v[200:201]
	v_pk_mul_f32 v[246:247], v[246:247], v[202:203]
	v_pk_mul_f32 v[248:249], v[248:249], v[204:205]
	v_pk_mul_f32 v[250:251], v[250:251], v[206:207]
	v_pk_mul_f32 v[252:253], v[252:253], v[208:209]
	v_mov_b32_e32 v202, v238
	v_mov_b32_e32 v203, v239
	v_mov_b32_e32 v204, v240
	v_mov_b32_e32 v205, v241
	v_mov_b32_e32 v194, v242
	v_mov_b32_e32 v195, v243
	v_mov_b32_e32 v208, v244
	v_mov_b32_e32 v209, v245
	v_mov_b32_e32 v198, v246
	v_mov_b32_e32 v199, v247
	v_mov_b32_e32 v200, v248
	v_mov_b32_e32 v201, v249
	v_mov_b32_e32 v196, v250
	v_mov_b32_e32 v197, v251
	v_mov_b32_e32 v206, v252
	v_mov_b32_e32 v207, v253
	s_branch .Lres_done_c4

.Lres_done_c4:
	s_mov_b32 s43, s51
	s_lshl_b64 s[50:51], s[42:43], 11
	s_add_u32 s50, s60, s50
	s_addc_u32 s51, s61, s51
	s_lshl_b64 s[42:43], s[42:43], 6
	s_add_u32 s42, s70, s42
	v_lshl_add_u64 v[212:213], s[40:41], 0, v[178:179]
	s_addc_u32 s43, s71, s43
	s_and_b64 vcc, exec, s[6:7]
	s_waitcnt vmcnt(1) lgkmcnt(0)
	v_pk_fma_f32 v[170:171], v[138:139], v[70:71], v[170:171]
	v_pk_fma_f32 v[174:175], v[142:143], v[66:67], v[174:175]
	v_pk_fma_f32 v[172:173], v[140:141], v[64:65], v[172:173]
	v_pk_fma_f32 v[168:169], v[136:137], v[68:69], v[168:169]
	v_pk_fma_f32 v[140:141], v[132:133], v[56:57], v[164:165]
	v_pk_fma_f32 v[136:137], v[124:125], v[60:61], v[160:161]
	global_store_dwordx4 v[212:213], v[172:175], off nt
	global_store_dwordx4 v[212:213], v[168:171], off offset:16 nt
	s_cbranch_vccnz .LBB0_1185
	v_pk_mul_f32 v[132:133], v[202:203], v[172:173]
	v_pk_mul_f32 v[138:139], v[208:209], v[170:171]
	v_cvt_pk_bf16_f32 v220, v132, v133
	v_mul_f32_e32 v132, v173, v173
	v_mul_f32_e32 v133, v175, v175
	v_fmac_f32_e32 v132, v172, v172
	v_fmac_f32_e32 v133, v174, v174
	v_pk_mul_f32 v[124:125], v[204:205], v[174:175]
	v_pk_mul_f32 v[142:143], v[194:195], v[168:169]
	v_cvt_pk_bf16_f32 v221, v124, v125
	v_add_f32_e32 v132, v132, v133
	v_cvt_pk_bf16_f32 v222, v142, v143
	v_cvt_pk_bf16_f32 v223, v138, v139
	v_mul_f32_e32 v133, v169, v169
	v_mul_f32_e32 v138, v171, v171
	v_fmac_f32_e32 v133, v168, v168
	v_fmac_f32_e32 v138, v170, v170
	v_lshl_add_u64 v[124:125], v[176:177], 1, s[50:51]
	v_add_f32_e32 v133, v133, v138
	v_pk_fma_f32 v[142:143], v[134:135], v[58:59], v[166:167]
	v_pk_fma_f32 v[138:139], v[126:127], v[62:63], v[162:163]
	v_pk_mul_f32 v[170:171], v[196:197], v[136:137]
	global_store_dwordx4 v[124:125], v[220:223], off
	v_add_f32_e32 v172, v132, v133
	global_store_dwordx4 v[212:213], v[140:143], off offset:512 nt
	global_store_dwordx4 v[212:213], v[136:139], off offset:528 nt
	v_pk_mul_f32 v[132:133], v[200:201], v[142:143]
	v_pk_mul_f32 v[160:161], v[198:199], v[140:141]
	v_pk_mul_f32 v[164:165], v[206:207], v[138:139]
	v_cvt_pk_bf16_f32 v168, v160, v161
	v_cvt_pk_bf16_f32 v169, v132, v133
	v_cvt_pk_bf16_f32 v170, v170, v171
	v_mul_f32_e32 v132, v139, v139
	v_cvt_pk_bf16_f32 v171, v164, v165
	global_store_dwordx4 v[124:125], v[168:171], off offset:256
	v_mul_f32_e32 v124, v141, v141
	v_mul_f32_e32 v125, v143, v143
	v_fmac_f32_e32 v124, v140, v140
	v_fmac_f32_e32 v125, v142, v142
	v_add_f32_e32 v124, v124, v125
	v_mul_f32_e32 v125, v137, v137
	v_fmac_f32_e32 v125, v136, v136
	v_fmac_f32_e32 v132, v138, v138
	v_add_f32_e32 v125, v125, v132
	v_add_f32_e32 v124, v124, v125
	v_add_f32_e32 v124, v172, v124
	v_mov_b32_e32 v125, v124
	s_nop 1
	v_permlane16_swap_b32_e32 v124, v125
	v_add_f32_e32 v124, v124, v125
	v_mov_b32_e32 v125, v124
	s_nop 1
	v_permlane32_swap_b32_e32 v124, v125
	s_and_saveexec_b64 s[52:53], s[2:3]
	s_cbranch_execz .LBB0_1145
	v_add_f32_e32 v132, v124, v125
	v_lshrrev_b32_e32 v124, 4, v176
	s_lshl_b32 s64, s16, 2
	v_and_b32_e32 v124, 0xfffffc0, v124
	v_mov_b32_e32 v125, v177
	s_ashr_i32 s65, s64, 31
	v_lshl_add_u64 v[124:125], s[42:43], 0, v[124:125]
	v_lshl_add_u64 v[124:125], s[64:65], 2, v[124:125]
	s_lshl_b32 s44, s74, 2
	v_lshl_add_u64 v[124:125], v[124:125], 0, s[44:45]
	global_store_dword v[124:125], v132, off

.LBB0_1152:
	s_mov_b64 s[52:53], 0x20000
	v_add_co_u32_e32 v114, vcc, 0x20000, v210
	v_lshl_add_u64 v[112:113], v[210:211], 0, s[52:53]
	s_nop 0
	v_addc_co_u32_e32 v115, vcc, 0, v211, vcc
	s_mov_b64 s[52:53], 0x20200
	global_load_dwordx4 v[136:139], v[114:115], off nt
	global_load_dwordx4 v[146:149], v[112:113], off offset:16 nt
	v_lshl_add_u64 v[112:113], v[210:211], 0, s[52:53]
	global_load_dwordx4 v[132:135], v[114:115], off offset:512 nt
	global_load_dwordx4 v[128:131], v[112:113], off offset:16 nt
	s_mov_b64 s[52:53], 0x30000
	v_add_co_u32_e32 v114, vcc, 0x30000, v210
	v_lshl_add_u64 v[112:113], v[210:211], 0, s[52:53]
	s_nop 0
	v_addc_co_u32_e32 v115, vcc, 0, v211, vcc
	s_mov_b64 s[52:53], 0x30200
	global_load_dwordx4 v[124:127], v[114:115], off nt
	global_load_dwordx4 v[120:123], v[112:113], off offset:16 nt
	v_lshl_add_u64 v[112:113], v[210:211], 0, s[52:53]
	global_load_dwordx4 v[116:119], v[114:115], off offset:512 nt
	s_nop 0
	global_load_dwordx4 v[112:115], v[112:113], off offset:16 nt
	s_mov_b64 s[98:99], 0x60000
	v_lshl_add_u64 v[226:227], v[226:227], 0, s[98:99]
	global_load_dword v233, v[226:227], off
	v_add_u32_e32 v144, 0x8000, v176
	v_mov_b32_e32 v145, v177
	s_and_b64 vcc, exec, s[6:7]
	s_waitcnt vmcnt(8)
	v_pk_fma_f32 v[142:143], v[110:111], v[66:67], v[138:139]
	v_pk_fma_f32 v[140:141], v[108:109], v[64:65], v[136:137]
	s_waitcnt vmcnt(7)
	v_pk_fma_f32 v[136:137], v[104:105], v[68:69], v[146:147]
	v_lshl_add_u64 v[104:105], v[144:145], 2, s[40:41]
	v_pk_fma_f32 v[138:139], v[106:107], v[70:71], v[148:149]
	global_store_dwordx4 v[104:105], v[140:143], off nt
	global_store_dwordx4 v[104:105], v[136:139], off offset:16 nt
	v_add_u32_e32 v146, 0x8080, v176
	s_waitcnt vmcnt(8)
	v_pk_fma_f32 v[104:105], v[100:101], v[56:57], v[132:133]
	s_waitcnt vmcnt(7)
	v_pk_fma_f32 v[108:109], v[96:97], v[60:61], v[128:129]
	s_cbranch_vccnz .LBB0_1187
	v_pk_mul_f32 v[96:97], v[204:205], v[142:143]
	v_pk_mul_f32 v[100:101], v[202:203], v[140:141]
	v_pk_mul_f32 v[106:107], v[208:209], v[138:139]
	v_cvt_pk_bf16_f32 v148, v100, v101
	v_cvt_pk_bf16_f32 v149, v96, v97
	v_lshl_add_u64 v[96:97], v[144:145], 1, s[50:51]
	v_pk_mul_f32 v[110:111], v[194:195], v[136:137]
	v_mul_f32_e32 v100, v139, v139
	v_cvt_pk_bf16_f32 v150, v110, v111
	v_cvt_pk_bf16_f32 v151, v106, v107
	global_store_dwordx4 v[96:97], v[148:151], off
	v_mul_f32_e32 v96, v141, v141
	v_mul_f32_e32 v97, v143, v143
	v_fmac_f32_e32 v96, v140, v140
	v_fmac_f32_e32 v97, v142, v142
	v_add_f32_e32 v96, v96, v97
	v_mul_f32_e32 v97, v137, v137
	v_fmac_f32_e32 v97, v136, v136
	v_fmac_f32_e32 v100, v138, v138
	v_add_f32_e32 v97, v97, v100
	v_mov_b32_e32 v147, v177
	v_add_f32_e32 v140, v96, v97
	v_pk_fma_f32 v[106:107], v[102:103], v[58:59], v[134:135]
	v_lshl_add_u64 v[96:97], v[146:147], 2, s[40:41]
	v_pk_fma_f32 v[110:111], v[98:99], v[62:63], v[130:131]
	global_store_dwordx4 v[96:97], v[104:107], off nt
	global_store_dwordx4 v[96:97], v[108:111], off offset:16 nt
	v_pk_mul_f32 v[96:97], v[200:201], v[106:107]
	v_pk_mul_f32 v[100:101], v[198:199], v[104:105]
	v_pk_mul_f32 v[128:129], v[206:207], v[110:111]
	v_cvt_pk_bf16_f32 v136, v100, v101
	v_cvt_pk_bf16_f32 v137, v96, v97
	v_lshl_add_u64 v[96:97], v[146:147], 1, s[50:51]
	v_pk_mul_f32 v[132:133], v[196:197], v[108:109]
	v_mul_f32_e32 v100, v111, v111
	v_cvt_pk_bf16_f32 v138, v132, v133
	v_cvt_pk_bf16_f32 v139, v128, v129
	global_store_dwordx4 v[96:97], v[136:139], off
	v_mul_f32_e32 v96, v105, v105
	v_mul_f32_e32 v97, v107, v107
	v_fmac_f32_e32 v96, v104, v104
	v_fmac_f32_e32 v97, v106, v106
	v_add_f32_e32 v96, v96, v97
	v_mul_f32_e32 v97, v109, v109
	v_fmac_f32_e32 v97, v108, v108
	v_fmac_f32_e32 v100, v110, v110
	v_add_f32_e32 v97, v97, v100
	v_add_f32_e32 v96, v96, v97
	v_add_f32_e32 v96, v140, v96
	v_mov_b32_e32 v97, v96
	s_nop 1
	v_permlane16_swap_b32_e32 v96, v97
	v_add_f32_e32 v96, v96, v97
	v_mov_b32_e32 v97, v96
	s_nop 1
	v_permlane32_swap_b32_e32 v96, v97
	s_and_saveexec_b64 s[52:53], s[2:3]
	s_cbranch_execz .LBB0_1155
	v_add_f32_e32 v100, v96, v97
	v_lshrrev_b32_e32 v96, 4, v144
	s_lshl_b32 s64, s16, 2
	v_and_b32_e32 v96, 0xfffffc0, v96
	v_mov_b32_e32 v97, v177
	s_ashr_i32 s65, s64, 31
	v_lshl_add_u64 v[96:97], s[42:43], 0, v[96:97]
	v_lshl_add_u64 v[96:97], s[64:65], 2, v[96:97]
	s_lshl_b32 s44, s74, 2
	v_lshl_add_u64 v[96:97], v[96:97], 0, s[44:45]
	global_store_dword v[96:97], v100, off

.LBB0_1157:
	s_nop 0
	v_add_u32_e32 v104, 0xc000, v176
	v_mov_b32_e32 v105, v177
	s_waitcnt vmcnt(6)
	v_pk_fma_f32 v[96:97], v[94:95], v[66:67], v[126:127]
	v_pk_fma_f32 v[94:95], v[92:93], v[64:65], v[124:125]
	s_waitcnt vmcnt(5)
	v_pk_fma_f32 v[98:99], v[88:89], v[68:69], v[120:121]
	v_lshl_add_u64 v[88:89], v[104:105], 2, s[40:41]
	v_pk_fma_f32 v[100:101], v[90:91], v[70:71], v[122:123]
	global_store_dwordx4 v[88:89], v[94:97], off nt
	global_store_dwordx4 v[88:89], v[98:101], off offset:16 nt
	s_and_b64 vcc, exec, s[6:7]
	v_add_u32_e32 v102, 0xc080, v176
	s_waitcnt vmcnt(6)
	v_pk_fma_f32 v[92:93], v[84:85], v[56:57], v[116:117]
	s_waitcnt vmcnt(5)
	v_pk_fma_f32 v[88:89], v[80:81], v[60:61], v[112:113]
	s_cbranch_vccnz .LBB0_1188
	v_pk_mul_f32 v[80:81], v[204:205], v[96:97]
	v_pk_mul_f32 v[84:85], v[202:203], v[94:95]
	v_pk_mul_f32 v[108:109], v[194:195], v[98:99]
	v_cvt_pk_bf16_f32 v106, v84, v85
	v_cvt_pk_bf16_f32 v107, v80, v81
	v_lshl_add_u64 v[80:81], v[104:105], 1, s[50:51]
	v_pk_mul_f32 v[90:91], v[208:209], v[100:101]
	v_cvt_pk_bf16_f32 v108, v108, v109
	v_mul_f32_e32 v84, v101, v101
	v_cvt_pk_bf16_f32 v109, v90, v91
	global_store_dwordx4 v[80:81], v[106:109], off
	v_mul_f32_e32 v80, v95, v95
	v_mul_f32_e32 v81, v97, v97
	v_fmac_f32_e32 v80, v94, v94
	v_fmac_f32_e32 v81, v96, v96
	v_add_f32_e32 v80, v80, v81
	v_mul_f32_e32 v81, v99, v99
	v_fmac_f32_e32 v81, v98, v98
	v_fmac_f32_e32 v84, v100, v100
	v_add_f32_e32 v81, v81, v84
	v_mov_b32_e32 v103, v177
	v_add_f32_e32 v105, v80, v81
	v_pk_fma_f32 v[94:95], v[86:87], v[58:59], v[118:119]
	v_lshl_add_u64 v[80:81], v[102:103], 2, s[40:41]
	v_pk_fma_f32 v[90:91], v[82:83], v[62:63], v[114:115]
	global_store_dwordx4 v[80:81], v[92:95], off nt
	global_store_dwordx4 v[80:81], v[88:91], off offset:16 nt
	v_pk_mul_f32 v[80:81], v[200:201], v[94:95]
	v_pk_mul_f32 v[84:85], v[198:199], v[92:93]
	v_pk_mul_f32 v[98:99], v[196:197], v[88:89]
	v_cvt_pk_bf16_f32 v96, v84, v85
	v_cvt_pk_bf16_f32 v97, v80, v81
	v_lshl_add_u64 v[80:81], v[102:103], 1, s[50:51]
	v_pk_mul_f32 v[100:101], v[206:207], v[90:91]
	v_cvt_pk_bf16_f32 v98, v98, v99
	v_mul_f32_e32 v84, v91, v91
	v_cvt_pk_bf16_f32 v99, v100, v101
	global_store_dwordx4 v[80:81], v[96:99], off
	v_mul_f32_e32 v80, v93, v93
	v_mul_f32_e32 v81, v95, v95
	v_fmac_f32_e32 v80, v92, v92
	v_fmac_f32_e32 v81, v94, v94
	v_add_f32_e32 v80, v80, v81
	v_mul_f32_e32 v81, v89, v89
	v_fmac_f32_e32 v81, v88, v88
	v_fmac_f32_e32 v84, v90, v90
	v_add_f32_e32 v81, v81, v84
	v_add_f32_e32 v80, v80, v81
	v_add_f32_e32 v80, v105, v80
	v_mov_b32_e32 v81, v80
	s_nop 1
	v_permlane16_swap_b32_e32 v80, v81
	v_add_f32_e32 v80, v80, v81
	v_mov_b32_e32 v81, v80
	s_nop 1
	v_permlane32_swap_b32_e32 v80, v81
	s_and_saveexec_b64 s[52:53], s[2:3]
	s_cbranch_execz .LBB0_1160
	v_add_f32_e32 v84, v80, v81
	v_lshrrev_b32_e32 v80, 4, v104
	s_lshl_b32 s64, s16, 2
	v_and_b32_e32 v80, 0xfffffc0, v80
	v_mov_b32_e32 v81, v177
	s_ashr_i32 s65, s64, 31
	v_lshl_add_u64 v[80:81], s[42:43], 0, v[80:81]
	v_lshl_add_u64 v[80:81], s[64:65], 2, v[80:81]
	s_lshl_b32 s44, s74, 2
	v_lshl_add_u64 v[80:81], v[80:81], 0, s[44:45]
	global_store_dword v[80:81], v84, off

.LBB0_1162:
	s_mov_b64 s[52:53], 0x80000
	v_add_co_u32_e32 v82, vcc, 0x80000, v210
	v_lshl_add_u64 v[80:81], v[210:211], 0, s[52:53]
	s_nop 0
	v_addc_co_u32_e32 v83, vcc, 0, v211, vcc
	s_mov_b64 s[52:53], 0x80200
	global_load_dwordx4 v[104:107], v[82:83], off nt
	global_load_dwordx4 v[114:117], v[80:81], off offset:16 nt
	v_lshl_add_u64 v[80:81], v[210:211], 0, s[52:53]
	global_load_dwordx4 v[100:103], v[82:83], off offset:512 nt
	global_load_dwordx4 v[96:99], v[80:81], off offset:16 nt
	s_mov_b64 s[52:53], 0x90000
	v_add_co_u32_e32 v82, vcc, 0x90000, v210
	v_lshl_add_u64 v[80:81], v[210:211], 0, s[52:53]
	s_nop 0
	v_addc_co_u32_e32 v83, vcc, 0, v211, vcc
	s_mov_b64 s[52:53], 0x90200
	global_load_dwordx4 v[92:95], v[82:83], off nt
	global_load_dwordx4 v[88:91], v[80:81], off offset:16 nt
	v_lshl_add_u64 v[80:81], v[210:211], 0, s[52:53]
	global_load_dwordx4 v[84:87], v[82:83], off offset:512 nt
	s_nop 0
	global_load_dwordx4 v[80:83], v[80:81], off offset:16 nt
	s_mov_b64 s[98:99], 0x20000
	v_lshl_add_u64 v[226:227], v[226:227], 0, s[98:99]
	global_load_dword v233, v[226:227], off
	v_add_u32_e32 v112, 0x20000, v176
	v_mov_b32_e32 v113, v177
	s_and_b64 vcc, exec, s[6:7]
	s_waitcnt vmcnt(8)
	v_pk_fma_f32 v[110:111], v[78:79], v[66:67], v[106:107]
	v_pk_fma_f32 v[108:109], v[76:77], v[64:65], v[104:105]
	s_waitcnt vmcnt(7)
	v_pk_fma_f32 v[104:105], v[72:73], v[68:69], v[114:115]
	v_lshl_add_u64 v[72:73], v[112:113], 2, s[40:41]
	v_pk_fma_f32 v[106:107], v[74:75], v[70:71], v[116:117]
	global_store_dwordx4 v[72:73], v[108:111], off nt
	global_store_dwordx4 v[72:73], v[104:107], off offset:16 nt
	v_add_u32_e32 v114, 0x20080, v176
	s_waitcnt vmcnt(8)
	v_pk_fma_f32 v[72:73], v[52:53], v[56:57], v[100:101]
	s_waitcnt vmcnt(7)
	v_pk_fma_f32 v[76:77], v[48:49], v[60:61], v[96:97]
	s_cbranch_vccnz .LBB0_1189
	v_pk_mul_f32 v[48:49], v[204:205], v[110:111]
	v_pk_mul_f32 v[52:53], v[202:203], v[108:109]
	v_pk_mul_f32 v[74:75], v[208:209], v[106:107]
	v_cvt_pk_bf16_f32 v116, v52, v53
	v_cvt_pk_bf16_f32 v117, v48, v49
	v_lshl_add_u64 v[48:49], v[112:113], 1, s[50:51]
	v_pk_mul_f32 v[78:79], v[194:195], v[104:105]
	v_mul_f32_e32 v52, v107, v107
	v_cvt_pk_bf16_f32 v118, v78, v79
	v_cvt_pk_bf16_f32 v119, v74, v75
	global_store_dwordx4 v[48:49], v[116:119], off
	v_mul_f32_e32 v48, v109, v109
	v_mul_f32_e32 v49, v111, v111
	v_fmac_f32_e32 v48, v108, v108
	v_fmac_f32_e32 v49, v110, v110
	v_add_f32_e32 v48, v48, v49
	v_mul_f32_e32 v49, v105, v105
	v_fmac_f32_e32 v49, v104, v104
	v_fmac_f32_e32 v52, v106, v106
	v_add_f32_e32 v49, v49, v52
	v_mov_b32_e32 v115, v177
	v_add_f32_e32 v108, v48, v49
	v_pk_fma_f32 v[74:75], v[54:55], v[58:59], v[102:103]
	v_lshl_add_u64 v[48:49], v[114:115], 2, s[40:41]
	v_pk_fma_f32 v[78:79], v[50:51], v[62:63], v[98:99]
	global_store_dwordx4 v[48:49], v[72:75], off nt
	global_store_dwordx4 v[48:49], v[76:79], off offset:16 nt
	v_pk_mul_f32 v[48:49], v[200:201], v[74:75]
	v_pk_mul_f32 v[52:53], v[198:199], v[72:73]
	v_pk_mul_f32 v[96:97], v[206:207], v[78:79]
	v_cvt_pk_bf16_f32 v104, v52, v53
	v_cvt_pk_bf16_f32 v105, v48, v49
	v_lshl_add_u64 v[48:49], v[114:115], 1, s[50:51]
	v_pk_mul_f32 v[100:101], v[196:197], v[76:77]
	v_mul_f32_e32 v52, v79, v79
	v_cvt_pk_bf16_f32 v106, v100, v101
	v_cvt_pk_bf16_f32 v107, v96, v97
	global_store_dwordx4 v[48:49], v[104:107], off
	v_mul_f32_e32 v48, v73, v73
	v_mul_f32_e32 v49, v75, v75
	v_fmac_f32_e32 v48, v72, v72
	v_fmac_f32_e32 v49, v74, v74
	v_add_f32_e32 v48, v48, v49
	v_mul_f32_e32 v49, v77, v77
	v_fmac_f32_e32 v49, v76, v76
	v_fmac_f32_e32 v52, v78, v78
	v_add_f32_e32 v49, v49, v52
	v_add_f32_e32 v48, v48, v49
	v_add_f32_e32 v48, v108, v48
	v_mov_b32_e32 v49, v48
	s_nop 1
	v_permlane16_swap_b32_e32 v48, v49
	v_add_f32_e32 v48, v48, v49
	v_mov_b32_e32 v49, v48
	s_nop 1
	v_permlane32_swap_b32_e32 v48, v49
	s_and_saveexec_b64 s[52:53], s[2:3]
	s_cbranch_execz .LBB0_1165
	v_add_f32_e32 v52, v48, v49
	v_lshrrev_b32_e32 v48, 4, v112
	s_lshl_b32 s64, s16, 2
	v_and_b32_e32 v48, 0xfffffc0, v48
	v_mov_b32_e32 v49, v177
	s_ashr_i32 s65, s64, 31
	v_lshl_add_u64 v[48:49], s[42:43], 0, v[48:49]
	v_lshl_add_u64 v[48:49], s[64:65], 2, v[48:49]
	s_lshl_b32 s44, s74, 2
	v_lshl_add_u64 v[48:49], v[48:49], 0, s[44:45]
	global_store_dword v[48:49], v52, off

.LBB0_1167:
	s_nop 0
	v_add_u32_e32 v72, 0x24000, v176
	v_mov_b32_e32 v73, v177
	s_waitcnt vmcnt(6)
	v_pk_fma_f32 v[48:49], v[46:47], v[66:67], v[94:95]
	v_pk_fma_f32 v[46:47], v[44:45], v[64:65], v[92:93]
	s_waitcnt vmcnt(5)
	v_pk_fma_f32 v[50:51], v[40:41], v[68:69], v[88:89]
	v_lshl_add_u64 v[40:41], v[72:73], 2, s[40:41]
	v_pk_fma_f32 v[52:53], v[42:43], v[70:71], v[90:91]
	global_store_dwordx4 v[40:41], v[46:49], off nt
	global_store_dwordx4 v[40:41], v[50:53], off offset:16 nt
	s_and_b64 vcc, exec, s[6:7]
	v_add_u32_e32 v54, 0x24080, v176
	s_waitcnt vmcnt(6)
	v_pk_fma_f32 v[44:45], v[36:37], v[56:57], v[84:85]
	s_waitcnt vmcnt(5)
	v_pk_fma_f32 v[40:41], v[32:33], v[60:61], v[80:81]
	s_cbranch_vccnz .LBB0_1190
	v_pk_mul_f32 v[32:33], v[204:205], v[48:49]
	v_pk_mul_f32 v[36:37], v[202:203], v[46:47]
	v_pk_mul_f32 v[76:77], v[194:195], v[50:51]
	v_cvt_pk_bf16_f32 v74, v36, v37
	v_cvt_pk_bf16_f32 v75, v32, v33
	v_lshl_add_u64 v[32:33], v[72:73], 1, s[50:51]
	v_pk_mul_f32 v[42:43], v[208:209], v[52:53]
	v_cvt_pk_bf16_f32 v76, v76, v77
	v_mul_f32_e32 v36, v53, v53
	v_cvt_pk_bf16_f32 v77, v42, v43
	global_store_dwordx4 v[32:33], v[74:77], off
	v_mul_f32_e32 v32, v47, v47
	v_mul_f32_e32 v33, v49, v49
	v_fmac_f32_e32 v32, v46, v46
	v_fmac_f32_e32 v33, v48, v48
	v_add_f32_e32 v32, v32, v33
	v_mul_f32_e32 v33, v51, v51
	v_fmac_f32_e32 v33, v50, v50
	v_fmac_f32_e32 v36, v52, v52
	v_add_f32_e32 v33, v33, v36
	v_mov_b32_e32 v55, v177
	v_add_f32_e32 v73, v32, v33
	v_pk_fma_f32 v[46:47], v[38:39], v[58:59], v[86:87]
	v_lshl_add_u64 v[32:33], v[54:55], 2, s[40:41]
	v_pk_fma_f32 v[42:43], v[34:35], v[62:63], v[82:83]
	global_store_dwordx4 v[32:33], v[44:47], off nt
	global_store_dwordx4 v[32:33], v[40:43], off offset:16 nt
	v_pk_mul_f32 v[32:33], v[200:201], v[46:47]
	v_pk_mul_f32 v[36:37], v[198:199], v[44:45]
	v_pk_mul_f32 v[50:51], v[196:197], v[40:41]
	v_cvt_pk_bf16_f32 v48, v36, v37
	v_cvt_pk_bf16_f32 v49, v32, v33
	v_lshl_add_u64 v[32:33], v[54:55], 1, s[50:51]
	v_pk_mul_f32 v[52:53], v[206:207], v[42:43]
	v_cvt_pk_bf16_f32 v50, v50, v51
	v_mul_f32_e32 v36, v43, v43
	v_cvt_pk_bf16_f32 v51, v52, v53
	global_store_dwordx4 v[32:33], v[48:51], off
	v_mul_f32_e32 v32, v45, v45
	v_mul_f32_e32 v33, v47, v47
	v_fmac_f32_e32 v32, v44, v44
	v_fmac_f32_e32 v33, v46, v46
	v_add_f32_e32 v32, v32, v33
	v_mul_f32_e32 v33, v41, v41
	v_fmac_f32_e32 v33, v40, v40
	v_fmac_f32_e32 v36, v42, v42
	v_add_f32_e32 v33, v33, v36
	v_add_f32_e32 v32, v32, v33
	v_add_f32_e32 v32, v73, v32
	v_mov_b32_e32 v33, v32
	s_nop 1
	v_permlane16_swap_b32_e32 v32, v33
	v_add_f32_e32 v32, v32, v33
	v_mov_b32_e32 v33, v32
	s_nop 1
	v_permlane32_swap_b32_e32 v32, v33
	s_and_saveexec_b64 s[52:53], s[2:3]
	s_cbranch_execz .LBB0_1170
	v_add_f32_e32 v36, v32, v33
	v_lshrrev_b32_e32 v32, 4, v72
	s_lshl_b32 s64, s16, 2
	v_and_b32_e32 v32, 0xfffffc0, v32
	v_mov_b32_e32 v33, v177
	s_ashr_i32 s65, s64, 31
	v_lshl_add_u64 v[32:33], s[42:43], 0, v[32:33]
	v_lshl_add_u64 v[32:33], s[64:65], 2, v[32:33]
	s_lshl_b32 s44, s74, 2
	v_lshl_add_u64 v[32:33], v[32:33], 0, s[44:45]
	global_store_dword v[32:33], v36, off

.Lres_pre_skip_c5:
	s_lshl_b32 s42, s40, 8
	s_add_i32 s44, s42, 0xffff8000
	s_ashr_i32 s43, s42, 31
	s_lshl_b64 s[50:51], s[44:45], 12
	s_add_u32 s21, s14, s50
	s_addc_u32 s23, s15, s51
	s_lshl_b64 s[50:51], s[42:43], 12
	s_add_u32 s27, s10, s50
	s_addc_u32 s41, s11, s51
	s_cmpk_lt_i32 s40, 0x80
	s_cselect_b32 s51, s43, 0
	s_cselect_b32 s50, s42, s44
	s_cselect_b32 s43, s1, s47
	s_cselect_b32 s44, s0, s46
	s_cselect_b32 s42, s42, s42
	s_cselect_b32 s41, s41, s23
	s_cselect_b32 s40, s27, s21
	s_lshl_b64 s[52:53], s[50:51], 12
	s_add_u32 s52, s44, s52
	v_add_u32_e32 v176, v144, v230
	s_addc_u32 s53, s43, s53
	v_lshlrev_b64 v[178:179], 2, v[176:177]
	v_lshl_add_u64 v[210:211], s[52:53], 0, v[178:179]
	s_mov_b32 s21, 0x10000
	s_mov_b64 s[52:53], 0x10000
	v_add_co_u32_e32 v146, vcc, s21, v210
	v_lshl_add_u64 v[144:145], v[210:211], 0, s[52:53]
	s_nop 0
	v_addc_co_u32_e32 v147, vcc, 0, v211, vcc
	s_mov_b64 s[52:53], 0x10200
	global_load_dwordx4 v[168:171], v[210:211], off offset:16 nt
	global_load_dwordx4 v[172:175], v[210:211], off nt
	global_load_dwordx4 v[160:163], v[210:211], off offset:528 nt
	global_load_dwordx4 v[164:167], v[210:211], off offset:512 nt
	global_load_dwordx4 v[156:159], v[146:147], off nt
	global_load_dwordx4 v[152:155], v[144:145], off offset:16 nt
	v_lshl_add_u64 v[144:145], v[210:211], 0, s[52:53]
	global_load_dwordx4 v[148:151], v[146:147], off offset:512 nt
	s_nop 0
	global_load_dwordx4 v[144:147], v[144:145], off offset:16 nt
	v_mbcnt_lo_u32_b32 v226, -1, 0
	v_mbcnt_hi_u32_b32 v226, -1, v226
	v_lshrrev_b32_e32 v226, 4, v226
	v_lshrrev_b32_e32 v227, 1, v226
	v_and_b32_e32 v233, 1, v226
	v_lshlrev_b32_e32 v227, 16, v227
	v_lshl_add_u32 v227, v233, 9, v227
	v_lshlrev_b32_e32 v226, 5, v226
	v_sub_u32_e32 v226, v227, v226
	v_add_u32_e32 v226, 0x20000, v226
	v_mov_b32_e32 v227, 0
	v_lshl_add_u64 v[226:227], v[210:211], 0, v[226:227]
	global_load_dword v233, v[226:227], off
	s_waitcnt vmcnt(1) lgkmcnt(0)
	s_andn2_b64 vcc, exec, s[18:19]
	s_cbranch_vccnz .Lres_zero_c5
	v_pk_add_f32 v[194:195], v[194:195], 1.0 op_sel_hi:[1,0]
	v_pk_add_f32 v[196:197], v[196:197], 1.0 op_sel_hi:[1,0]
	v_pk_add_f32 v[198:199], v[198:199], 1.0 op_sel_hi:[1,0]
	v_pk_add_f32 v[200:201], v[200:201], 1.0 op_sel_hi:[1,0]
	v_pk_add_f32 v[202:203], v[202:203], 1.0 op_sel_hi:[1,0]
	v_pk_add_f32 v[204:205], v[204:205], 1.0 op_sel_hi:[1,0]
	v_pk_add_f32 v[206:207], v[206:207], 1.0 op_sel_hi:[1,0]
	v_pk_add_f32 v[208:209], v[208:209], 1.0 op_sel_hi:[1,0]
	v_pk_mul_f32 v[238:239], v[238:239], v[194:195]
	v_pk_mul_f32 v[240:241], v[240:241], v[196:197]
	v_pk_mul_f32 v[242:243], v[242:243], v[198:199]
	v_pk_mul_f32 v[244:245], v[244:245], v[200:201]
	v_pk_mul_f32 v[246:247], v[246:247], v[202:203]
	v_pk_mul_f32 v[248:249], v[248:249], v[204:205]
	v_pk_mul_f32 v[250:251], v[250:251], v[206:207]
	v_pk_mul_f32 v[252:253], v[252:253], v[208:209]
	v_mov_b32_e32 v202, v238
	v_mov_b32_e32 v203, v239
	v_mov_b32_e32 v204, v240
	v_mov_b32_e32 v205, v241
	v_mov_b32_e32 v194, v242
	v_mov_b32_e32 v195, v243
	v_mov_b32_e32 v208, v244
	v_mov_b32_e32 v209, v245
	v_mov_b32_e32 v198, v246
	v_mov_b32_e32 v199, v247
	v_mov_b32_e32 v200, v248
	v_mov_b32_e32 v201, v249
	v_mov_b32_e32 v196, v250
	v_mov_b32_e32 v197, v251
	v_mov_b32_e32 v206, v252
	v_mov_b32_e32 v207, v253
	s_branch .Lres_done_c5

.Lres_done_c5:
	s_mov_b32 s43, s51
	s_lshl_b64 s[50:51], s[42:43], 11
	s_add_u32 s50, s60, s50
	s_addc_u32 s51, s61, s51
	s_lshl_b64 s[42:43], s[42:43], 6
	s_add_u32 s42, s70, s42
	v_lshl_add_u64 v[212:213], s[40:41], 0, v[178:179]
	s_addc_u32 s43, s71, s43
	s_and_b64 vcc, exec, s[4:5]
	s_waitcnt vmcnt(1) lgkmcnt(0)
	v_pk_fma_f32 v[170:171], v[138:139], v[110:111], v[170:171]
	v_pk_fma_f32 v[174:175], v[142:143], v[106:107], v[174:175]
	v_pk_fma_f32 v[172:173], v[140:141], v[104:105], v[172:173]
	v_pk_fma_f32 v[168:169], v[136:137], v[108:109], v[168:169]
	v_pk_fma_f32 v[140:141], v[132:133], v[88:89], v[164:165]
	v_pk_fma_f32 v[136:137], v[128:129], v[92:93], v[160:161]
	global_store_dwordx4 v[212:213], v[172:175], off nt
	global_store_dwordx4 v[212:213], v[168:171], off offset:16 nt
	s_cbranch_vccnz .LBB0_1280
	v_pk_mul_f32 v[132:133], v[202:203], v[172:173]
	v_pk_mul_f32 v[138:139], v[208:209], v[170:171]
	v_cvt_pk_bf16_f32 v220, v132, v133
	v_mul_f32_e32 v132, v173, v173
	v_mul_f32_e32 v133, v175, v175
	v_fmac_f32_e32 v132, v172, v172
	v_fmac_f32_e32 v133, v174, v174
	v_pk_mul_f32 v[128:129], v[204:205], v[174:175]
	v_pk_mul_f32 v[142:143], v[194:195], v[168:169]
	v_cvt_pk_bf16_f32 v221, v128, v129
	v_add_f32_e32 v132, v132, v133
	v_cvt_pk_bf16_f32 v222, v142, v143
	v_cvt_pk_bf16_f32 v223, v138, v139
	v_mul_f32_e32 v133, v169, v169
	v_mul_f32_e32 v138, v171, v171
	v_fmac_f32_e32 v133, v168, v168
	v_fmac_f32_e32 v138, v170, v170
	v_lshl_add_u64 v[128:129], v[176:177], 1, s[50:51]
	v_add_f32_e32 v133, v133, v138
	v_pk_fma_f32 v[142:143], v[134:135], v[90:91], v[166:167]
	v_pk_fma_f32 v[138:139], v[130:131], v[94:95], v[162:163]
	v_pk_mul_f32 v[170:171], v[196:197], v[136:137]
	global_store_dwordx4 v[128:129], v[220:223], off
	v_add_f32_e32 v172, v132, v133
	global_store_dwordx4 v[212:213], v[140:143], off offset:512 nt
	global_store_dwordx4 v[212:213], v[136:139], off offset:528 nt
	v_pk_mul_f32 v[132:133], v[200:201], v[142:143]
	v_pk_mul_f32 v[160:161], v[198:199], v[140:141]
	v_pk_mul_f32 v[164:165], v[206:207], v[138:139]
	v_cvt_pk_bf16_f32 v168, v160, v161
	v_cvt_pk_bf16_f32 v169, v132, v133
	v_cvt_pk_bf16_f32 v170, v170, v171
	v_mul_f32_e32 v132, v139, v139
	v_cvt_pk_bf16_f32 v171, v164, v165
	global_store_dwordx4 v[128:129], v[168:171], off offset:256
	v_mul_f32_e32 v128, v141, v141
	v_mul_f32_e32 v129, v143, v143
	v_fmac_f32_e32 v128, v140, v140
	v_fmac_f32_e32 v129, v142, v142
	v_add_f32_e32 v128, v128, v129
	v_mul_f32_e32 v129, v137, v137
	v_fmac_f32_e32 v129, v136, v136
	v_fmac_f32_e32 v132, v138, v138
	v_add_f32_e32 v129, v129, v132
	v_add_f32_e32 v128, v128, v129
	v_add_f32_e32 v128, v172, v128
	v_mov_b32_e32 v129, v128
	s_nop 1
	v_permlane16_swap_b32_e32 v128, v129
	v_add_f32_e32 v128, v128, v129
	v_mov_b32_e32 v129, v128
	s_nop 1
	v_permlane32_swap_b32_e32 v128, v129
	s_and_saveexec_b64 s[52:53], s[2:3]
	s_cbranch_execz .LBB0_1240
	v_add_f32_e32 v132, v128, v129
	v_lshrrev_b32_e32 v128, 4, v176
	s_lshl_b32 s64, s6, 2
	v_and_b32_e32 v128, 0xfffffc0, v128
	v_mov_b32_e32 v129, v177
	s_ashr_i32 s65, s64, 31
	v_lshl_add_u64 v[128:129], s[42:43], 0, v[128:129]
	v_lshl_add_u64 v[128:129], s[64:65], 2, v[128:129]
	s_lshl_b32 s44, s80, 2
	v_lshl_add_u64 v[128:129], v[128:129], 0, s[44:45]
	global_store_dword v[128:129], v132, off

.LBB0_1247:
	s_mov_b64 s[52:53], 0x20000
	v_add_co_u32_e32 v114, vcc, 0x20000, v210
	v_lshl_add_u64 v[112:113], v[210:211], 0, s[52:53]
	s_nop 0
	v_addc_co_u32_e32 v115, vcc, 0, v211, vcc
	s_mov_b64 s[52:53], 0x20200
	global_load_dwordx4 v[136:139], v[114:115], off nt
	global_load_dwordx4 v[146:149], v[112:113], off offset:16 nt
	v_lshl_add_u64 v[112:113], v[210:211], 0, s[52:53]
	global_load_dwordx4 v[132:135], v[114:115], off offset:512 nt
	global_load_dwordx4 v[128:131], v[112:113], off offset:16 nt
	s_mov_b64 s[52:53], 0x30000
	v_add_co_u32_e32 v114, vcc, 0x30000, v210
	v_lshl_add_u64 v[112:113], v[210:211], 0, s[52:53]
	s_nop 0
	v_addc_co_u32_e32 v115, vcc, 0, v211, vcc
	s_mov_b64 s[52:53], 0x30200
	global_load_dwordx4 v[124:127], v[114:115], off nt
	global_load_dwordx4 v[120:123], v[112:113], off offset:16 nt
	v_lshl_add_u64 v[112:113], v[210:211], 0, s[52:53]
	global_load_dwordx4 v[116:119], v[114:115], off offset:512 nt
	s_nop 0
	global_load_dwordx4 v[112:115], v[112:113], off offset:16 nt
	s_mov_b64 s[98:99], 0x60000
	v_lshl_add_u64 v[226:227], v[226:227], 0, s[98:99]
	global_load_dword v233, v[226:227], off
	v_add_u32_e32 v144, 0x8000, v176
	v_mov_b32_e32 v145, v177
	s_and_b64 vcc, exec, s[4:5]
	s_waitcnt vmcnt(8)
	v_pk_fma_f32 v[142:143], v[102:103], v[106:107], v[138:139]
	v_pk_fma_f32 v[140:141], v[100:101], v[104:105], v[136:137]
	s_waitcnt vmcnt(7)
	v_pk_fma_f32 v[136:137], v[96:97], v[108:109], v[146:147]
	v_lshl_add_u64 v[96:97], v[144:145], 2, s[40:41]
	v_pk_fma_f32 v[138:139], v[98:99], v[110:111], v[148:149]
	global_store_dwordx4 v[96:97], v[140:143], off nt
	global_store_dwordx4 v[96:97], v[136:139], off offset:16 nt
	v_add_u32_e32 v146, 0x8080, v176
	s_waitcnt vmcnt(8)
	v_pk_fma_f32 v[96:97], v[84:85], v[88:89], v[132:133]
	s_waitcnt vmcnt(7)
	v_pk_fma_f32 v[100:101], v[80:81], v[92:93], v[128:129]
	s_cbranch_vccnz .LBB0_1282
	v_pk_mul_f32 v[80:81], v[204:205], v[142:143]
	v_pk_mul_f32 v[84:85], v[202:203], v[140:141]
	v_pk_mul_f32 v[98:99], v[208:209], v[138:139]
	v_cvt_pk_bf16_f32 v148, v84, v85
	v_cvt_pk_bf16_f32 v149, v80, v81
	v_lshl_add_u64 v[80:81], v[144:145], 1, s[50:51]
	v_pk_mul_f32 v[102:103], v[194:195], v[136:137]
	v_mul_f32_e32 v84, v139, v139
	v_cvt_pk_bf16_f32 v150, v102, v103
	v_cvt_pk_bf16_f32 v151, v98, v99
	global_store_dwordx4 v[80:81], v[148:151], off
	v_mul_f32_e32 v80, v141, v141
	v_mul_f32_e32 v81, v143, v143
	v_fmac_f32_e32 v80, v140, v140
	v_fmac_f32_e32 v81, v142, v142
	v_add_f32_e32 v80, v80, v81
	v_mul_f32_e32 v81, v137, v137
	v_fmac_f32_e32 v81, v136, v136
	v_fmac_f32_e32 v84, v138, v138
	v_add_f32_e32 v81, v81, v84
	v_mov_b32_e32 v147, v177
	v_add_f32_e32 v140, v80, v81
	v_pk_fma_f32 v[98:99], v[86:87], v[90:91], v[134:135]
	v_lshl_add_u64 v[80:81], v[146:147], 2, s[40:41]
	v_pk_fma_f32 v[102:103], v[82:83], v[94:95], v[130:131]
	global_store_dwordx4 v[80:81], v[96:99], off nt
	global_store_dwordx4 v[80:81], v[100:103], off offset:16 nt
	v_pk_mul_f32 v[80:81], v[200:201], v[98:99]
	v_pk_mul_f32 v[84:85], v[198:199], v[96:97]
	v_pk_mul_f32 v[128:129], v[206:207], v[102:103]
	v_cvt_pk_bf16_f32 v136, v84, v85
	v_cvt_pk_bf16_f32 v137, v80, v81
	v_lshl_add_u64 v[80:81], v[146:147], 1, s[50:51]
	v_pk_mul_f32 v[132:133], v[196:197], v[100:101]
	v_mul_f32_e32 v84, v103, v103
	v_cvt_pk_bf16_f32 v138, v132, v133
	v_cvt_pk_bf16_f32 v139, v128, v129
	global_store_dwordx4 v[80:81], v[136:139], off
	v_mul_f32_e32 v80, v97, v97
	v_mul_f32_e32 v81, v99, v99
	v_fmac_f32_e32 v80, v96, v96
	v_fmac_f32_e32 v81, v98, v98
	v_add_f32_e32 v80, v80, v81
	v_mul_f32_e32 v81, v101, v101
	v_fmac_f32_e32 v81, v100, v100
	v_fmac_f32_e32 v84, v102, v102
	v_add_f32_e32 v81, v81, v84
	v_add_f32_e32 v80, v80, v81
	v_add_f32_e32 v80, v140, v80
	v_mov_b32_e32 v81, v80
	s_nop 1
	v_permlane16_swap_b32_e32 v80, v81
	v_add_f32_e32 v80, v80, v81
	v_mov_b32_e32 v81, v80
	s_nop 1
	v_permlane32_swap_b32_e32 v80, v81
	s_and_saveexec_b64 s[52:53], s[2:3]
	s_cbranch_execz .LBB0_1250
	v_add_f32_e32 v84, v80, v81
	v_lshrrev_b32_e32 v80, 4, v144
	s_lshl_b32 s64, s6, 2
	v_and_b32_e32 v80, 0xfffffc0, v80
	v_mov_b32_e32 v81, v177
	s_ashr_i32 s65, s64, 31
	v_lshl_add_u64 v[80:81], s[42:43], 0, v[80:81]
	v_lshl_add_u64 v[80:81], s[64:65], 2, v[80:81]
	s_lshl_b32 s44, s80, 2
	v_lshl_add_u64 v[80:81], v[80:81], 0, s[44:45]
	global_store_dword v[80:81], v84, off

.LBB0_1252:
	s_nop 0
	v_add_u32_e32 v96, 0xc000, v176
	v_mov_b32_e32 v97, v177
	s_waitcnt vmcnt(6)
	v_pk_fma_f32 v[80:81], v[78:79], v[106:107], v[126:127]
	v_pk_fma_f32 v[78:79], v[76:77], v[104:105], v[124:125]
	s_waitcnt vmcnt(5)
	v_pk_fma_f32 v[82:83], v[72:73], v[108:109], v[120:121]
	v_lshl_add_u64 v[72:73], v[96:97], 2, s[40:41]
	v_pk_fma_f32 v[84:85], v[74:75], v[110:111], v[122:123]
	global_store_dwordx4 v[72:73], v[78:81], off nt
	global_store_dwordx4 v[72:73], v[82:85], off offset:16 nt
	s_and_b64 vcc, exec, s[4:5]
	v_add_u32_e32 v86, 0xc080, v176
	s_waitcnt vmcnt(6)
	v_pk_fma_f32 v[76:77], v[68:69], v[88:89], v[116:117]
	s_waitcnt vmcnt(5)
	v_pk_fma_f32 v[72:73], v[64:65], v[92:93], v[112:113]
	s_cbranch_vccnz .LBB0_1283
	v_pk_mul_f32 v[64:65], v[204:205], v[80:81]
	v_pk_mul_f32 v[68:69], v[202:203], v[78:79]
	v_pk_mul_f32 v[100:101], v[194:195], v[82:83]
	v_cvt_pk_bf16_f32 v98, v68, v69
	v_cvt_pk_bf16_f32 v99, v64, v65
	v_lshl_add_u64 v[64:65], v[96:97], 1, s[50:51]
	v_pk_mul_f32 v[74:75], v[208:209], v[84:85]
	v_cvt_pk_bf16_f32 v100, v100, v101
	v_mul_f32_e32 v68, v85, v85
	v_cvt_pk_bf16_f32 v101, v74, v75
	global_store_dwordx4 v[64:65], v[98:101], off
	v_mul_f32_e32 v64, v79, v79
	v_mul_f32_e32 v65, v81, v81
	v_fmac_f32_e32 v64, v78, v78
	v_fmac_f32_e32 v65, v80, v80
	v_add_f32_e32 v64, v64, v65
	v_mul_f32_e32 v65, v83, v83
	v_fmac_f32_e32 v65, v82, v82
	v_fmac_f32_e32 v68, v84, v84
	v_add_f32_e32 v65, v65, v68
	v_mov_b32_e32 v87, v177
	v_add_f32_e32 v97, v64, v65
	v_pk_fma_f32 v[78:79], v[70:71], v[90:91], v[118:119]
	v_lshl_add_u64 v[64:65], v[86:87], 2, s[40:41]
	v_pk_fma_f32 v[74:75], v[66:67], v[94:95], v[114:115]
	global_store_dwordx4 v[64:65], v[76:79], off nt
	global_store_dwordx4 v[64:65], v[72:75], off offset:16 nt
	v_pk_mul_f32 v[64:65], v[200:201], v[78:79]
	v_pk_mul_f32 v[68:69], v[198:199], v[76:77]
	v_pk_mul_f32 v[82:83], v[196:197], v[72:73]
	v_cvt_pk_bf16_f32 v80, v68, v69
	v_cvt_pk_bf16_f32 v81, v64, v65
	v_lshl_add_u64 v[64:65], v[86:87], 1, s[50:51]
	v_pk_mul_f32 v[84:85], v[206:207], v[74:75]
	v_cvt_pk_bf16_f32 v82, v82, v83
	v_mul_f32_e32 v68, v75, v75
	v_cvt_pk_bf16_f32 v83, v84, v85
	global_store_dwordx4 v[64:65], v[80:83], off
	v_mul_f32_e32 v64, v77, v77
	v_mul_f32_e32 v65, v79, v79
	v_fmac_f32_e32 v64, v76, v76
	v_fmac_f32_e32 v65, v78, v78
	v_add_f32_e32 v64, v64, v65
	v_mul_f32_e32 v65, v73, v73
	v_fmac_f32_e32 v65, v72, v72
	v_fmac_f32_e32 v68, v74, v74
	v_add_f32_e32 v65, v65, v68
	v_add_f32_e32 v64, v64, v65
	v_add_f32_e32 v64, v97, v64
	v_mov_b32_e32 v65, v64
	s_nop 1
	v_permlane16_swap_b32_e32 v64, v65
	v_add_f32_e32 v64, v64, v65
	v_mov_b32_e32 v65, v64
	s_nop 1
	v_permlane32_swap_b32_e32 v64, v65
	s_and_saveexec_b64 s[52:53], s[2:3]
	s_cbranch_execz .LBB0_1255
	v_add_f32_e32 v68, v64, v65
	v_lshrrev_b32_e32 v64, 4, v96
	s_lshl_b32 s64, s6, 2
	v_and_b32_e32 v64, 0xfffffc0, v64
	v_mov_b32_e32 v65, v177
	s_ashr_i32 s65, s64, 31
	v_lshl_add_u64 v[64:65], s[42:43], 0, v[64:65]
	v_lshl_add_u64 v[64:65], s[64:65], 2, v[64:65]
	s_lshl_b32 s44, s80, 2
	v_lshl_add_u64 v[64:65], v[64:65], 0, s[44:45]
	global_store_dword v[64:65], v68, off

.LBB0_1257:
	s_mov_b64 s[52:53], 0x80000
	v_add_co_u32_e32 v66, vcc, 0x80000, v210
	v_lshl_add_u64 v[64:65], v[210:211], 0, s[52:53]
	s_nop 0
	v_addc_co_u32_e32 v67, vcc, 0, v211, vcc
	s_mov_b64 s[52:53], 0x80200
	global_load_dwordx4 v[96:99], v[66:67], off nt
	global_load_dwordx4 v[114:117], v[64:65], off offset:16 nt
	v_lshl_add_u64 v[64:65], v[210:211], 0, s[52:53]
	global_load_dwordx4 v[84:87], v[66:67], off offset:512 nt
	global_load_dwordx4 v[80:83], v[64:65], off offset:16 nt
	s_mov_b64 s[52:53], 0x90000
	v_add_co_u32_e32 v66, vcc, 0x90000, v210
	v_lshl_add_u64 v[64:65], v[210:211], 0, s[52:53]
	s_nop 0
	v_addc_co_u32_e32 v67, vcc, 0, v211, vcc
	s_mov_b64 s[52:53], 0x90200
	global_load_dwordx4 v[76:79], v[66:67], off nt
	global_load_dwordx4 v[72:75], v[64:65], off offset:16 nt
	v_lshl_add_u64 v[64:65], v[210:211], 0, s[52:53]
	global_load_dwordx4 v[68:71], v[66:67], off offset:512 nt
	s_nop 0
	global_load_dwordx4 v[64:67], v[64:65], off offset:16 nt
	s_mov_b64 s[98:99], 0x20000
	v_lshl_add_u64 v[226:227], v[226:227], 0, s[98:99]
	global_load_dword v233, v[226:227], off
	v_add_u32_e32 v112, 0x20000, v176
	v_mov_b32_e32 v113, v177
	s_and_b64 vcc, exec, s[4:5]
	s_waitcnt vmcnt(8)
	v_pk_fma_f32 v[102:103], v[62:63], v[106:107], v[98:99]
	v_pk_fma_f32 v[100:101], v[60:61], v[104:105], v[96:97]
	s_waitcnt vmcnt(7)
	v_pk_fma_f32 v[96:97], v[56:57], v[108:109], v[114:115]
	v_lshl_add_u64 v[56:57], v[112:113], 2, s[40:41]
	v_pk_fma_f32 v[98:99], v[58:59], v[110:111], v[116:117]
	global_store_dwordx4 v[56:57], v[100:103], off nt
	global_store_dwordx4 v[56:57], v[96:99], off offset:16 nt
	v_add_u32_e32 v114, 0x20080, v176
	s_waitcnt vmcnt(8)
	v_pk_fma_f32 v[56:57], v[52:53], v[88:89], v[84:85]
	s_waitcnt vmcnt(7)
	v_pk_fma_f32 v[60:61], v[48:49], v[92:93], v[80:81]
	s_cbranch_vccnz .LBB0_1284
	v_pk_mul_f32 v[48:49], v[204:205], v[102:103]
	v_pk_mul_f32 v[52:53], v[202:203], v[100:101]
	v_pk_mul_f32 v[58:59], v[208:209], v[98:99]
	v_cvt_pk_bf16_f32 v116, v52, v53
	v_cvt_pk_bf16_f32 v117, v48, v49
	v_lshl_add_u64 v[48:49], v[112:113], 1, s[50:51]
	v_pk_mul_f32 v[62:63], v[194:195], v[96:97]
	v_mul_f32_e32 v52, v99, v99
	v_cvt_pk_bf16_f32 v118, v62, v63
	v_cvt_pk_bf16_f32 v119, v58, v59
	global_store_dwordx4 v[48:49], v[116:119], off
	v_mul_f32_e32 v48, v101, v101
	v_mul_f32_e32 v49, v103, v103
	v_fmac_f32_e32 v48, v100, v100
	v_fmac_f32_e32 v49, v102, v102
	v_add_f32_e32 v48, v48, v49
	v_mul_f32_e32 v49, v97, v97
	v_fmac_f32_e32 v49, v96, v96
	v_fmac_f32_e32 v52, v98, v98
	v_add_f32_e32 v49, v49, v52
	v_mov_b32_e32 v115, v177
	v_add_f32_e32 v100, v48, v49
	v_pk_fma_f32 v[58:59], v[54:55], v[90:91], v[86:87]
	v_lshl_add_u64 v[48:49], v[114:115], 2, s[40:41]
	v_pk_fma_f32 v[62:63], v[50:51], v[94:95], v[82:83]
	global_store_dwordx4 v[48:49], v[56:59], off nt
	global_store_dwordx4 v[48:49], v[60:63], off offset:16 nt
	v_pk_mul_f32 v[48:49], v[200:201], v[58:59]
	v_pk_mul_f32 v[52:53], v[198:199], v[56:57]
	v_pk_mul_f32 v[80:81], v[206:207], v[62:63]
	v_cvt_pk_bf16_f32 v96, v52, v53
	v_cvt_pk_bf16_f32 v97, v48, v49
	v_lshl_add_u64 v[48:49], v[114:115], 1, s[50:51]
	v_pk_mul_f32 v[84:85], v[196:197], v[60:61]
	v_mul_f32_e32 v52, v63, v63
	v_cvt_pk_bf16_f32 v98, v84, v85
	v_cvt_pk_bf16_f32 v99, v80, v81
	global_store_dwordx4 v[48:49], v[96:99], off
	v_mul_f32_e32 v48, v57, v57
	v_mul_f32_e32 v49, v59, v59
	v_fmac_f32_e32 v48, v56, v56
	v_fmac_f32_e32 v49, v58, v58
	v_add_f32_e32 v48, v48, v49
	v_mul_f32_e32 v49, v61, v61
	v_fmac_f32_e32 v49, v60, v60
	v_fmac_f32_e32 v52, v62, v62
	v_add_f32_e32 v49, v49, v52
	v_add_f32_e32 v48, v48, v49
	v_add_f32_e32 v48, v100, v48
	v_mov_b32_e32 v49, v48
	s_nop 1
	v_permlane16_swap_b32_e32 v48, v49
	v_add_f32_e32 v48, v48, v49
	v_mov_b32_e32 v49, v48
	s_nop 1
	v_permlane32_swap_b32_e32 v48, v49
	s_and_saveexec_b64 s[52:53], s[2:3]
	s_cbranch_execz .LBB0_1260
	v_add_f32_e32 v52, v48, v49
	v_lshrrev_b32_e32 v48, 4, v112
	s_lshl_b32 s64, s6, 2
	v_and_b32_e32 v48, 0xfffffc0, v48
	v_mov_b32_e32 v49, v177
	s_ashr_i32 s65, s64, 31
	v_lshl_add_u64 v[48:49], s[42:43], 0, v[48:49]
	v_lshl_add_u64 v[48:49], s[64:65], 2, v[48:49]
	s_lshl_b32 s44, s80, 2
	v_lshl_add_u64 v[48:49], v[48:49], 0, s[44:45]
	global_store_dword v[48:49], v52, off

.LBB0_1262:
	s_nop 0
	v_add_u32_e32 v56, 0x24000, v176
	v_mov_b32_e32 v57, v177
	s_waitcnt vmcnt(6)
	v_pk_fma_f32 v[48:49], v[46:47], v[106:107], v[78:79]
	v_pk_fma_f32 v[46:47], v[44:45], v[104:105], v[76:77]
	s_waitcnt vmcnt(5)
	v_pk_fma_f32 v[50:51], v[40:41], v[108:109], v[72:73]
	v_lshl_add_u64 v[40:41], v[56:57], 2, s[40:41]
	v_pk_fma_f32 v[52:53], v[42:43], v[110:111], v[74:75]
	global_store_dwordx4 v[40:41], v[46:49], off nt
	global_store_dwordx4 v[40:41], v[50:53], off offset:16 nt
	s_and_b64 vcc, exec, s[4:5]
	v_add_u32_e32 v54, 0x24080, v176
	s_waitcnt vmcnt(6)
	v_pk_fma_f32 v[44:45], v[36:37], v[88:89], v[68:69]
	s_waitcnt vmcnt(5)
	v_pk_fma_f32 v[40:41], v[32:33], v[92:93], v[64:65]
	s_cbranch_vccnz .LBB0_1285
	v_pk_mul_f32 v[32:33], v[204:205], v[48:49]
	v_pk_mul_f32 v[36:37], v[202:203], v[46:47]
	v_pk_mul_f32 v[60:61], v[194:195], v[50:51]
	v_cvt_pk_bf16_f32 v58, v36, v37
	v_cvt_pk_bf16_f32 v59, v32, v33
	v_lshl_add_u64 v[32:33], v[56:57], 1, s[50:51]
	v_pk_mul_f32 v[42:43], v[208:209], v[52:53]
	v_cvt_pk_bf16_f32 v60, v60, v61
	v_mul_f32_e32 v36, v53, v53
	v_cvt_pk_bf16_f32 v61, v42, v43
	global_store_dwordx4 v[32:33], v[58:61], off
	v_mul_f32_e32 v32, v47, v47
	v_mul_f32_e32 v33, v49, v49
	v_fmac_f32_e32 v32, v46, v46
	v_fmac_f32_e32 v33, v48, v48
	v_add_f32_e32 v32, v32, v33
	v_mul_f32_e32 v33, v51, v51
	v_fmac_f32_e32 v33, v50, v50
	v_fmac_f32_e32 v36, v52, v52
	v_add_f32_e32 v33, v33, v36
	v_mov_b32_e32 v55, v177
	v_add_f32_e32 v57, v32, v33
	v_pk_fma_f32 v[46:47], v[38:39], v[90:91], v[70:71]
	v_lshl_add_u64 v[32:33], v[54:55], 2, s[40:41]
	v_pk_fma_f32 v[42:43], v[34:35], v[94:95], v[66:67]
	global_store_dwordx4 v[32:33], v[44:47], off nt
	global_store_dwordx4 v[32:33], v[40:43], off offset:16 nt
	v_pk_mul_f32 v[32:33], v[200:201], v[46:47]
	v_pk_mul_f32 v[36:37], v[198:199], v[44:45]
	v_pk_mul_f32 v[50:51], v[196:197], v[40:41]
	v_cvt_pk_bf16_f32 v48, v36, v37
	v_cvt_pk_bf16_f32 v49, v32, v33
	v_lshl_add_u64 v[32:33], v[54:55], 1, s[50:51]
	v_pk_mul_f32 v[52:53], v[206:207], v[42:43]
	v_cvt_pk_bf16_f32 v50, v50, v51
	v_mul_f32_e32 v36, v43, v43
	v_cvt_pk_bf16_f32 v51, v52, v53
	global_store_dwordx4 v[32:33], v[48:51], off
	v_mul_f32_e32 v32, v45, v45
	v_mul_f32_e32 v33, v47, v47
	v_fmac_f32_e32 v32, v44, v44
	v_fmac_f32_e32 v33, v46, v46
	v_add_f32_e32 v32, v32, v33
	v_mul_f32_e32 v33, v41, v41
	v_fmac_f32_e32 v33, v40, v40
	v_fmac_f32_e32 v36, v42, v42
	v_add_f32_e32 v33, v33, v36
	v_add_f32_e32 v32, v32, v33
	v_add_f32_e32 v32, v57, v32
	v_mov_b32_e32 v33, v32
	s_nop 1
	v_permlane16_swap_b32_e32 v32, v33
	v_add_f32_e32 v32, v32, v33
	v_mov_b32_e32 v33, v32
	s_nop 1
	v_permlane32_swap_b32_e32 v32, v33
	s_and_saveexec_b64 s[52:53], s[2:3]
	s_cbranch_execz .LBB0_1265
	v_add_f32_e32 v36, v32, v33
	v_lshrrev_b32_e32 v32, 4, v56
	s_lshl_b32 s64, s6, 2
	v_and_b32_e32 v32, 0xfffffc0, v32
	v_mov_b32_e32 v33, v177
	s_ashr_i32 s65, s64, 31
	v_lshl_add_u64 v[32:33], s[42:43], 0, v[32:33]
	v_lshl_add_u64 v[32:33], s[64:65], 2, v[32:33]
	s_lshl_b32 s44, s80, 2
	v_lshl_add_u64 v[32:33], v[32:33], 0, s[44:45]
	global_store_dword v[32:33], v36, off
